# loader-side VALU removed from GEMM main loops (saddr LDS-DMA, immediate ds_read offsets); no per-segment setprio; lean phase-1 converter
# speedup vs baseline: 1.0051x; 1.0051x over previous
; #define PG8_STAGE(bufoff, gbase, voff) do { _Pragma("unroll") for (int _i = 0; _i < 2; ++_i) \
;         __builtin_amdgcn_global_load_lds((const unsigned*)((const char*)(gbase) + (voff)[_i]), (PG8_LAS unsigned*)(lds + (bufoff) + ldsw + _i * 8192), 16, 0, 0); } while (0)
; #define PG8_LDA(dst, b, h) do { _Pragma("unroll") for (int m = 0; m < 4; ++m) _Pragma("unroll") for (int k = 0; k < 2; ++k) dst[m][k] = *(const PG8_LAS bf16x8*)(lds + PG8_SA(b, h) + aoff + m * 2048 + k * 1024); } while (0)
; #define PG8_LDB(dst, b, h) do { _Pragma("unroll") for (int n = 0; n < 2; ++n) _Pragma("unroll") for (int k = 0; k < 2; ++k) dst[n][k] = *(const PG8_LAS bf16x8*)(lds + PG8_SB(b, h) + boff + n * 2048 + k * 1024); } while (0)
; #define PG8_MMA(ai, bj, At, Bt) do { __builtin_amdgcn_s_setprio(1); _Pragma("unroll") for (int m = 0; m < 4; ++m) _Pragma("unroll") for (int n = 0; n < 2; ++n) _Pragma("unroll") for (int k = 0; k < 2; ++k) \
;         acc[ai][bj][m][n] = __builtin_amdgcn_mfma_f32_16x16x32_bf16(Bt[n][k], At[m][k], acc[ai][bj][m][n], 0, 0, 0); __builtin_amdgcn_s_setprio(0); } while (0)
; #define PG8_WAIT_V(n) asm volatile("s_waitcnt vmcnt(" #n ")" ::: "memory")
; template <class Epi, class Sched, bool ALIGN_EPI = false, bool SP2 = false>
; __device__ __forceinline__ void gemm_phase(PG8_LAS unsigned char* lds, const Gemm g, const Sched& S, const Epi& E) {
;     ...
;         const char* nA = has_next ? (const char*)g.A + (size_t)nxt.pm * tstep : cA; const char* nB = has_next ? (const char*)g.Bt + (size_t)nxt.pn * tstep : cB;
;         for (int t = 0; t < nt; t += 2) {
;             const bool last = (t == nt - 2);
;             const char* a1 = cA + (size_t)(t + 1) * kstep;
;             const char* a2 = last ? nA : cA + (size_t)(t + 2) * kstep; const char* b2 = last ? nB : cB + (size_t)(t + 2) * kstep;
;             const char* a3 = a2 + kstep; const char* b3 = b2 + kstep;
;             if (last && has_next) S.a_ready(nxt);
;             if constexpr (SP2) {
;             PG8_LDB(B0, 0, 0); PG8_LDB(B1, 0, 1); PG8_SCHED; PG8_LDA(At, 0, 0); PG8_STAGE(PG8_SA(1, 1), a1 + hstep, voffA);
;             PG8_WAIT_V(8); PG8_WAIT_L(0); PG8_BAR; PG8_MMA(0, 0, At, B0); PG8_MMA(0, 1, At, B1); PG8_BAR; PG8_SCHED;
;             PG8_LDA(At, 0, 1); PG8_STAGE(PG8_SB(0, 0), b2, voffB); PG8_STAGE(PG8_SB(0, 1), b2 + hstep, voffB); PG8_STAGE(PG8_SA(0, 0), a2, voffA);
.LBB0_672:
	s_ashr_i32 s11, s10, 31
	s_lshl_b64 s[14:15], s[10:11], 21
	s_add_u32 s14, s96, s14
	s_addc_u32 s15, s97, s15
	s_and_b64 s[16:17], s[0:1], exec
	s_cselect_b32 s11, s15, s23
	s_cselect_b32 s52, s14, s22
	s_ashr_i32 s13, s12, 31
	s_lshl_b64 s[16:17], s[12:13], 21
	s_add_u32 s16, s33, s16
	s_addc_u32 s17, s42, s17
	s_and_b64 s[24:25], s[0:1], exec
	s_cselect_b32 s13, s17, s21
	s_cselect_b32 s53, s16, s20
	s_add_u32 s22, s22, 0x100080
	s_addc_u32 s23, s23, 0
	s_add_u32 s62, s20, 0x100
	s_addc_u32 s34, s21, 0
	s_mov_b32 s35, -2
	v_add_u32_e32 v241, 0x10000, v153
.LBB0_673:
	ds_read_b128 v[148:151], v241 offset:0
	ds_read_b128 v[156:159], v241 offset:1024
	ds_read_b128 v[166:169], v241 offset:2048
	ds_read_b128 v[170:173], v241 offset:3072
	ds_read_b128 v[174:177], v241 offset:16384
	ds_read_b128 v[178:181], v241 offset:17408
	ds_read_b128 v[182:185], v241 offset:18432
	ds_read_b128 v[186:189], v241 offset:19456
	s_add_u32 s20, s22, 0xfff00080
	s_addc_u32 s21, s23, -1
	s_cmp_eq_u32 s35, 60
	s_cselect_b32 s25, s11, s21
	s_cselect_b32 s24, s52, s20
	s_cselect_b32 s21, s13, s34
	s_cselect_b32 s20, s53, s62
	s_add_i32 m0, s19, 0xc000
	ds_read_b128 v[190:193], v161
	ds_read_b128 v[194:197], v161 offset:1024
	ds_read_b128 v[198:201], v161 offset:2048
	ds_read_b128 v[202:205], v161 offset:3072
	ds_read_b128 v[206:209], v161 offset:4096
	ds_read_b128 v[210:213], v161 offset:5120
	ds_read_b128 v[214:217], v161 offset:6144
	ds_read_b128 v[218:221], v161 offset:7168
	global_load_lds_dwordx4 v138, s[22:23]
	s_add_i32 m0, s19, 0xe000
	s_nop 0
	global_load_lds_dwordx4 v140, s[22:23]
	s_waitcnt vmcnt(8)
	s_waitcnt lgkmcnt(0)
	s_barrier
	s_waitcnt lgkmcnt(0)
	v_mfma_f32_16x16x32_bf16 v[118:121], v[148:151], v[190:193], v[118:121]
	v_mfma_f32_16x16x32_bf16 v[114:117], v[166:169], v[190:193], v[114:117]
	v_mfma_f32_16x16x32_bf16 v[102:105], v[148:151], v[198:201], v[102:105]
	v_mfma_f32_16x16x32_bf16 v[98:101], v[166:169], v[198:201], v[98:101]
	v_mfma_f32_16x16x32_bf16 v[86:89], v[148:151], v[206:209], v[86:89]
	v_mfma_f32_16x16x32_bf16 v[82:85], v[166:169], v[206:209], v[82:85]
	v_mfma_f32_16x16x32_bf16 v[70:73], v[148:151], v[214:217], v[70:73]
	v_mfma_f32_16x16x32_bf16 v[66:69], v[166:169], v[214:217], v[66:69]
	v_mfma_f32_16x16x32_bf16 v[118:121], v[156:159], v[194:197], v[118:121]
	v_mfma_f32_16x16x32_bf16 v[114:117], v[170:173], v[194:197], v[114:117]
	v_mfma_f32_16x16x32_bf16 v[102:105], v[156:159], v[202:205], v[102:105]
	v_mfma_f32_16x16x32_bf16 v[98:101], v[170:173], v[202:205], v[98:101]
	v_mfma_f32_16x16x32_bf16 v[86:89], v[156:159], v[210:213], v[86:89]
	v_mfma_f32_16x16x32_bf16 v[82:85], v[170:173], v[210:213], v[82:85]
	v_mfma_f32_16x16x32_bf16 v[70:73], v[156:159], v[218:221], v[70:73]
	v_mfma_f32_16x16x32_bf16 v[66:69], v[170:173], v[218:221], v[66:69]
	v_mfma_f32_16x16x32_bf16 v[126:129], v[174:177], v[190:193], v[126:129]
	v_mfma_f32_16x16x32_bf16 v[122:125], v[182:185], v[190:193], v[122:125]
	v_mfma_f32_16x16x32_bf16 v[110:113], v[174:177], v[198:201], v[110:113]
	v_mfma_f32_16x16x32_bf16 v[106:109], v[182:185], v[198:201], v[106:109]
	v_mfma_f32_16x16x32_bf16 v[94:97], v[174:177], v[206:209], v[94:97]
	v_mfma_f32_16x16x32_bf16 v[90:93], v[182:185], v[206:209], v[90:93]
	v_mfma_f32_16x16x32_bf16 v[78:81], v[174:177], v[214:217], v[78:81]
	v_mfma_f32_16x16x32_bf16 v[74:77], v[182:185], v[214:217], v[74:77]
	v_mfma_f32_16x16x32_bf16 v[126:129], v[178:181], v[194:197], v[126:129]
	v_mfma_f32_16x16x32_bf16 v[122:125], v[186:189], v[194:197], v[122:125]
	v_mfma_f32_16x16x32_bf16 v[110:113], v[178:181], v[202:205], v[110:113]
	v_mfma_f32_16x16x32_bf16 v[106:109], v[186:189], v[202:205], v[106:109]
	v_mfma_f32_16x16x32_bf16 v[94:97], v[178:181], v[210:213], v[94:97]
	v_mfma_f32_16x16x32_bf16 v[90:93], v[186:189], v[210:213], v[90:93]
	v_mfma_f32_16x16x32_bf16 v[78:81], v[178:181], v[218:221], v[78:81]
	v_mfma_f32_16x16x32_bf16 v[74:77], v[186:189], v[218:221], v[74:77]
	s_barrier
	s_add_i32 s63, s43, s26
	v_lshl_add_u64 v[222:223], s[20:21], 0, v[132:133]
	s_mov_b32 m0, s63
	ds_read_b128 v[190:193], v161 offset:16384
	ds_read_b128 v[194:197], v161 offset:17408
	ds_read_b128 v[198:201], v161 offset:18432
	ds_read_b128 v[202:205], v161 offset:19456
	ds_read_b128 v[206:209], v161 offset:20480
	ds_read_b128 v[210:213], v161 offset:21504
	ds_read_b128 v[214:217], v161 offset:22528
	ds_read_b128 v[218:221], v161 offset:23552
	global_load_lds_dwordx4 v[222:223], off
	s_add_i32 m0, s63, 0x2000
	s_add_u32 s64, s20, 0x100000
	v_lshl_add_u64 v[224:225], s[20:21], 0, v[136:137]
	s_addc_u32 s65, s21, 0
	s_add_i32 s63, s46, s26
	global_load_lds_dwordx4 v[224:225], off
	s_mov_b32 m0, s63
	v_lshl_add_u64 v[228:229], s[24:25], 0, v[134:135]
	global_load_lds_dwordx4 v132, s[64:65]
	s_add_i32 m0, s63, 0x2000
	s_nop 0
	global_load_lds_dwordx4 v136, s[64:65]
	v_lshl_add_u64 v[226:227], s[24:25], 0, v[130:131]
	s_mov_b32 m0, s19
	s_nop 0
	global_load_lds_dwordx4 v[226:227], off
	s_mov_b32 m0, s29
	s_nop 0
	global_load_lds_dwordx4 v[228:229], off
	s_waitcnt vmcnt(8)
	s_waitcnt lgkmcnt(0)
	s_barrier
; #define PG8_STAGE(bufoff, gbase, voff) do { _Pragma("unroll") for (int _i = 0; _i < 2; ++_i) \
;         __builtin_amdgcn_global_load_lds((const unsigned*)((const char*)(gbase) + (voff)[_i]), (PG8_LAS unsigned*)(lds + (bufoff) + ldsw + _i * 8192), 16, 0, 0); } while (0)
; #define PG8_LDA(dst, b, h) do { _Pragma("unroll") for (int m = 0; m < 4; ++m) _Pragma("unroll") for (int k = 0; k < 2; ++k) dst[m][k] = *(const PG8_LAS bf16x8*)(lds + PG8_SA(b, h) + aoff + m * 2048 + k * 1024); } while (0)
; #define PG8_LDB(dst, b, h) do { _Pragma("unroll") for (int n = 0; n < 2; ++n) _Pragma("unroll") for (int k = 0; k < 2; ++k) dst[n][k] = *(const PG8_LAS bf16x8*)(lds + PG8_SB(b, h) + boff + n * 2048 + k * 1024); } while (0)
; #define PG8_MMA(ai, bj, At, Bt) do { __builtin_amdgcn_s_setprio(1); _Pragma("unroll") for (int m = 0; m < 4; ++m) _Pragma("unroll") for (int n = 0; n < 2; ++n) _Pragma("unroll") for (int k = 0; k < 2; ++k) \
;         acc[ai][bj][m][n] = __builtin_amdgcn_mfma_f32_16x16x32_bf16(Bt[n][k], At[m][k], acc[ai][bj][m][n], 0, 0, 0); __builtin_amdgcn_s_setprio(0); } while (0)
; #define PG8_WAIT_V(n) asm volatile("s_waitcnt vmcnt(" #n ")" ::: "memory")
; #define PG8_WAIT_L(n) asm volatile("s_waitcnt lgkmcnt(" #n ")" ::: "memory")
; #define PG8_BAR __builtin_amdgcn_s_barrier()
; #define PG8_SCHED __builtin_amdgcn_sched_barrier(0)
; template <class Epi, class Sched, bool ALIGN_EPI = false, bool SP2 = false>
; __device__ __forceinline__ void gemm_phase(PG8_LAS unsigned char* lds, const Gemm g, const Sched& S, const Epi& E) {
;     ...
;             PG8_WAIT_V(8); PG8_WAIT_L(0); PG8_BAR; PG8_MMA(1, 0, At, B0); PG8_MMA(1, 1, At, B1); PG8_BAR; PG8_SCHED;
;             PG8_LDB(B0, 1, 0); PG8_LDB(B1, 1, 1); PG8_SCHED; PG8_LDA(At, 1, 0); PG8_STAGE(PG8_SA(0, 1), a2 + hstep, voffA);
;             PG8_WAIT_V(8); PG8_WAIT_L(0); PG8_BAR; PG8_MMA(0, 0, At, B0); PG8_MMA(0, 1, At, B1); PG8_BAR; PG8_SCHED;
	s_waitcnt lgkmcnt(0)
	v_mfma_f32_16x16x32_bf16 v[54:57], v[148:151], v[190:193], v[54:57]
	v_mfma_f32_16x16x32_bf16 v[50:53], v[166:169], v[190:193], v[50:53]
	v_mfma_f32_16x16x32_bf16 v[38:41], v[148:151], v[198:201], v[38:41]
	v_mfma_f32_16x16x32_bf16 v[34:37], v[166:169], v[198:201], v[34:37]
	v_mfma_f32_16x16x32_bf16 v[22:25], v[148:151], v[206:209], v[22:25]
	v_mfma_f32_16x16x32_bf16 v[18:21], v[166:169], v[206:209], v[18:21]
	v_mfma_f32_16x16x32_bf16 v[6:9], v[148:151], v[214:217], v[6:9]
	v_mfma_f32_16x16x32_bf16 v[2:5], v[166:169], v[214:217], v[2:5]
	v_mfma_f32_16x16x32_bf16 v[54:57], v[156:159], v[194:197], v[54:57]
	v_mfma_f32_16x16x32_bf16 v[50:53], v[170:173], v[194:197], v[50:53]
	v_mfma_f32_16x16x32_bf16 v[38:41], v[156:159], v[202:205], v[38:41]
	v_mfma_f32_16x16x32_bf16 v[34:37], v[170:173], v[202:205], v[34:37]
	v_mfma_f32_16x16x32_bf16 v[22:25], v[156:159], v[210:213], v[22:25]
	v_mfma_f32_16x16x32_bf16 v[18:21], v[170:173], v[210:213], v[18:21]
	v_mfma_f32_16x16x32_bf16 v[6:9], v[156:159], v[218:221], v[6:9]
	v_mfma_f32_16x16x32_bf16 v[2:5], v[170:173], v[218:221], v[2:5]
	v_mfma_f32_16x16x32_bf16 v[62:65], v[174:177], v[190:193], v[62:65]
	v_mfma_f32_16x16x32_bf16 v[58:61], v[182:185], v[190:193], v[58:61]
	v_mfma_f32_16x16x32_bf16 v[46:49], v[174:177], v[198:201], v[46:49]
	v_mfma_f32_16x16x32_bf16 v[42:45], v[182:185], v[198:201], v[42:45]
	v_mfma_f32_16x16x32_bf16 v[30:33], v[174:177], v[206:209], v[30:33]
	v_mfma_f32_16x16x32_bf16 v[26:29], v[182:185], v[206:209], v[26:29]
	v_mfma_f32_16x16x32_bf16 v[10:13], v[174:177], v[214:217], v[10:13]
	v_mfma_f32_16x16x32_bf16 v[14:17], v[182:185], v[214:217], v[14:17]
	v_mfma_f32_16x16x32_bf16 v[62:65], v[178:181], v[194:197], v[62:65]
	v_mfma_f32_16x16x32_bf16 v[58:61], v[186:189], v[194:197], v[58:61]
	v_mfma_f32_16x16x32_bf16 v[46:49], v[178:181], v[202:205], v[46:49]
	v_mfma_f32_16x16x32_bf16 v[42:45], v[186:189], v[202:205], v[42:45]
	v_mfma_f32_16x16x32_bf16 v[30:33], v[178:181], v[210:213], v[30:33]
	v_mfma_f32_16x16x32_bf16 v[26:29], v[186:189], v[210:213], v[26:29]
	v_mfma_f32_16x16x32_bf16 v[10:13], v[178:181], v[218:221], v[10:13]
	v_mfma_f32_16x16x32_bf16 v[14:17], v[186:189], v[218:221], v[14:17]
	s_barrier
	s_add_i32 s63, 0, 0x18000
	s_add_i32 s64, 0, 0x1c000
	ds_read_b128 v[148:151], v241 offset:32768
	ds_read_b128 v[156:159], v241 offset:33792
	ds_read_b128 v[166:169], v241 offset:34816
	ds_read_b128 v[170:173], v241 offset:35840
	ds_read_b128 v[174:177], v241 offset:49152
	ds_read_b128 v[178:181], v241 offset:50176
	ds_read_b128 v[182:185], v241 offset:51200
	ds_read_b128 v[186:189], v241 offset:52224
	s_add_u32 s24, s24, 0x100000
	s_addc_u32 s25, s25, 0
	s_mov_b32 m0, s30
	ds_read_b128 v[190:193], v161 offset:32768
	ds_read_b128 v[194:197], v161 offset:33792
	ds_read_b128 v[198:201], v161 offset:34816
	ds_read_b128 v[202:205], v161 offset:35840
	ds_read_b128 v[206:209], v161 offset:36864
	ds_read_b128 v[210:213], v161 offset:37888
	ds_read_b128 v[214:217], v161 offset:38912
	ds_read_b128 v[218:221], v161 offset:39936
	global_load_lds_dwordx4 v130, s[24:25]
	s_mov_b32 m0, s31
	s_nop 0
	global_load_lds_dwordx4 v134, s[24:25]
	s_waitcnt vmcnt(8)
	s_waitcnt lgkmcnt(0)
	s_barrier
	s_waitcnt lgkmcnt(0)
	v_mfma_f32_16x16x32_bf16 v[118:121], v[148:151], v[190:193], v[118:121]
	v_mfma_f32_16x16x32_bf16 v[114:117], v[166:169], v[190:193], v[114:117]
	v_mfma_f32_16x16x32_bf16 v[102:105], v[148:151], v[198:201], v[102:105]
	v_mfma_f32_16x16x32_bf16 v[98:101], v[166:169], v[198:201], v[98:101]
	v_mfma_f32_16x16x32_bf16 v[86:89], v[148:151], v[206:209], v[86:89]
	v_mfma_f32_16x16x32_bf16 v[82:85], v[166:169], v[206:209], v[82:85]
	v_mfma_f32_16x16x32_bf16 v[70:73], v[148:151], v[214:217], v[70:73]
	v_mfma_f32_16x16x32_bf16 v[66:69], v[166:169], v[214:217], v[66:69]
	v_mfma_f32_16x16x32_bf16 v[118:121], v[156:159], v[194:197], v[118:121]
	v_mfma_f32_16x16x32_bf16 v[114:117], v[170:173], v[194:197], v[114:117]
	v_mfma_f32_16x16x32_bf16 v[102:105], v[156:159], v[202:205], v[102:105]
	v_mfma_f32_16x16x32_bf16 v[98:101], v[170:173], v[202:205], v[98:101]
	v_mfma_f32_16x16x32_bf16 v[86:89], v[156:159], v[210:213], v[86:89]
	v_mfma_f32_16x16x32_bf16 v[82:85], v[170:173], v[210:213], v[82:85]
	v_mfma_f32_16x16x32_bf16 v[70:73], v[156:159], v[218:221], v[70:73]
	v_mfma_f32_16x16x32_bf16 v[66:69], v[170:173], v[218:221], v[66:69]
	v_mfma_f32_16x16x32_bf16 v[126:129], v[174:177], v[190:193], v[126:129]
	v_mfma_f32_16x16x32_bf16 v[122:125], v[182:185], v[190:193], v[122:125]
	v_mfma_f32_16x16x32_bf16 v[110:113], v[174:177], v[198:201], v[110:113]
	v_mfma_f32_16x16x32_bf16 v[106:109], v[182:185], v[198:201], v[106:109]
	v_mfma_f32_16x16x32_bf16 v[94:97], v[174:177], v[206:209], v[94:97]
	v_mfma_f32_16x16x32_bf16 v[90:93], v[182:185], v[206:209], v[90:93]
	v_mfma_f32_16x16x32_bf16 v[78:81], v[174:177], v[214:217], v[78:81]
	v_mfma_f32_16x16x32_bf16 v[74:77], v[182:185], v[214:217], v[74:77]
	v_mfma_f32_16x16x32_bf16 v[126:129], v[178:181], v[194:197], v[126:129]
	v_mfma_f32_16x16x32_bf16 v[122:125], v[186:189], v[194:197], v[122:125]
	v_mfma_f32_16x16x32_bf16 v[110:113], v[178:181], v[202:205], v[110:113]
	v_mfma_f32_16x16x32_bf16 v[106:109], v[186:189], v[202:205], v[106:109]
	v_mfma_f32_16x16x32_bf16 v[94:97], v[178:181], v[210:213], v[94:97]
	v_mfma_f32_16x16x32_bf16 v[90:93], v[186:189], v[210:213], v[90:93]
	v_mfma_f32_16x16x32_bf16 v[78:81], v[178:181], v[218:221], v[78:81]
	v_mfma_f32_16x16x32_bf16 v[74:77], v[186:189], v[218:221], v[74:77]
	s_barrier
; #define PG8_STAGE(bufoff, gbase, voff) do { _Pragma("unroll") for (int _i = 0; _i < 2; ++_i) \
;         __builtin_amdgcn_global_load_lds((const unsigned*)((const char*)(gbase) + (voff)[_i]), (PG8_LAS unsigned*)(lds + (bufoff) + ldsw + _i * 8192), 16, 0, 0); } while (0)
; #define PG8_LDA(dst, b, h) do { _Pragma("unroll") for (int m = 0; m < 4; ++m) _Pragma("unroll") for (int k = 0; k < 2; ++k) dst[m][k] = *(const PG8_LAS bf16x8*)(lds + PG8_SA(b, h) + aoff + m * 2048 + k * 1024); } while (0)
; #define PG8_MMA(ai, bj, At, Bt) do { __builtin_amdgcn_s_setprio(1); _Pragma("unroll") for (int m = 0; m < 4; ++m) _Pragma("unroll") for (int n = 0; n < 2; ++n) _Pragma("unroll") for (int k = 0; k < 2; ++k) \
;         acc[ai][bj][m][n] = __builtin_amdgcn_mfma_f32_16x16x32_bf16(Bt[n][k], At[m][k], acc[ai][bj][m][n], 0, 0, 0); __builtin_amdgcn_s_setprio(0); } while (0)
; #define PG8_WAIT_V(n) asm volatile("s_waitcnt vmcnt(" #n ")" ::: "memory")
; #define PG8_WAIT_L(n) asm volatile("s_waitcnt lgkmcnt(" #n ")" ::: "memory")
; #define PG8_BAR __builtin_amdgcn_s_barrier()
; #define PG8_SCHED __builtin_amdgcn_sched_barrier(0)
; template <class Epi, class Sched, bool ALIGN_EPI = false, bool SP2 = false>
; __device__ __forceinline__ void gemm_phase(PG8_LAS unsigned char* lds, const Gemm g, const Sched& S, const Epi& E) {
;     ...
;         for (int t = 0; t < nt; t += 2) {
;     ...
;             PG8_LDA(At, 1, 1); PG8_STAGE(PG8_SB(1, 0), b3, voffB); PG8_STAGE(PG8_SB(1, 1), b3 + hstep, voffB); PG8_STAGE(PG8_SA(1, 0), a3, voffA);
;             PG8_WAIT_V(8); PG8_WAIT_L(0); PG8_BAR; PG8_MMA(1, 0, At, B0); PG8_MMA(1, 1, At, B1); PG8_BAR; PG8_SCHED;
	s_add_i32 s24, s63, s26
	s_add_i32 m0, s24, 0xffffff80
	ds_read_b128 v[190:193], v161 offset:49152
	ds_read_b128 v[194:197], v161 offset:50176
	ds_read_b128 v[198:201], v161 offset:51200
	ds_read_b128 v[202:205], v161 offset:52224
	ds_read_b128 v[206:209], v161 offset:53248
	ds_read_b128 v[210:213], v161 offset:54272
	ds_read_b128 v[214:217], v161 offset:55296
	ds_read_b128 v[218:221], v161 offset:56320
	global_load_lds_dwordx4 v[222:223], off offset:128
	s_add_i32 m0, s24, 0x1f80
	s_add_u32 s20, s20, 0x100080
	s_addc_u32 s21, s21, 0
	s_add_i32 s24, s64, s26
	global_load_lds_dwordx4 v[224:225], off offset:128
	s_mov_b32 m0, s24
	s_nop 0
	global_load_lds_dwordx4 v132, s[20:21]
	s_add_i32 m0, s24, 0x2000
	s_nop 0
	global_load_lds_dwordx4 v136, s[20:21]
	s_add_i32 m0, s40, 0xffffff80
	s_nop 0
	global_load_lds_dwordx4 v[226:227], off offset:128
	s_add_i32 m0, s41, 0xffffff80
	s_nop 0
	global_load_lds_dwordx4 v[228:229], off offset:128
	s_waitcnt vmcnt(8)
	s_waitcnt lgkmcnt(0)
	s_barrier
	s_waitcnt lgkmcnt(0)
	v_mfma_f32_16x16x32_bf16 v[54:57], v[148:151], v[190:193], v[54:57]
	v_mfma_f32_16x16x32_bf16 v[50:53], v[166:169], v[190:193], v[50:53]
	v_mfma_f32_16x16x32_bf16 v[38:41], v[148:151], v[198:201], v[38:41]
	v_mfma_f32_16x16x32_bf16 v[34:37], v[166:169], v[198:201], v[34:37]
	v_mfma_f32_16x16x32_bf16 v[22:25], v[148:151], v[206:209], v[22:25]
	v_mfma_f32_16x16x32_bf16 v[18:21], v[166:169], v[206:209], v[18:21]
	v_mfma_f32_16x16x32_bf16 v[6:9], v[148:151], v[214:217], v[6:9]
	v_mfma_f32_16x16x32_bf16 v[2:5], v[166:169], v[214:217], v[2:5]
	v_mfma_f32_16x16x32_bf16 v[54:57], v[156:159], v[194:197], v[54:57]
	v_mfma_f32_16x16x32_bf16 v[50:53], v[170:173], v[194:197], v[50:53]
	v_mfma_f32_16x16x32_bf16 v[38:41], v[156:159], v[202:205], v[38:41]
	v_mfma_f32_16x16x32_bf16 v[34:37], v[170:173], v[202:205], v[34:37]
	v_mfma_f32_16x16x32_bf16 v[22:25], v[156:159], v[210:213], v[22:25]
	v_mfma_f32_16x16x32_bf16 v[18:21], v[170:173], v[210:213], v[18:21]
	v_mfma_f32_16x16x32_bf16 v[6:9], v[156:159], v[218:221], v[6:9]
	v_mfma_f32_16x16x32_bf16 v[2:5], v[170:173], v[218:221], v[2:5]
	v_mfma_f32_16x16x32_bf16 v[62:65], v[174:177], v[190:193], v[62:65]
	v_mfma_f32_16x16x32_bf16 v[58:61], v[182:185], v[190:193], v[58:61]
	v_mfma_f32_16x16x32_bf16 v[46:49], v[174:177], v[198:201], v[46:49]
	v_mfma_f32_16x16x32_bf16 v[42:45], v[182:185], v[198:201], v[42:45]
	v_mfma_f32_16x16x32_bf16 v[30:33], v[174:177], v[206:209], v[30:33]
	v_mfma_f32_16x16x32_bf16 v[26:29], v[182:185], v[206:209], v[26:29]
	v_mfma_f32_16x16x32_bf16 v[10:13], v[174:177], v[214:217], v[10:13]
	v_mfma_f32_16x16x32_bf16 v[14:17], v[182:185], v[214:217], v[14:17]
	v_mfma_f32_16x16x32_bf16 v[62:65], v[178:181], v[194:197], v[62:65]
	v_mfma_f32_16x16x32_bf16 v[58:61], v[186:189], v[194:197], v[58:61]
	v_mfma_f32_16x16x32_bf16 v[46:49], v[178:181], v[202:205], v[46:49]
	v_mfma_f32_16x16x32_bf16 v[42:45], v[186:189], v[202:205], v[42:45]
	v_mfma_f32_16x16x32_bf16 v[30:33], v[178:181], v[210:213], v[30:33]
	v_mfma_f32_16x16x32_bf16 v[26:29], v[186:189], v[210:213], v[26:29]
	v_mfma_f32_16x16x32_bf16 v[10:13], v[178:181], v[218:221], v[10:13]
	v_mfma_f32_16x16x32_bf16 v[14:17], v[186:189], v[218:221], v[14:17]
	s_barrier
	s_add_i32 s35, s35, 2
	s_add_u32 s22, s22, 0x100
	s_addc_u32 s23, s23, 0
	s_add_u32 s62, s62, 0x100
	s_addc_u32 s34, s34, 0
	s_cmp_gt_u32 s35, 61
	s_cbranch_scc0 .LBB0_673


; #define PG8_BAR __builtin_amdgcn_s_barrier()
; template <class Epi, class Sched, bool ALIGN_EPI = false, bool SP2 = false>
; __device__ __forceinline__ void gemm_phase(PG8_LAS unsigned char* lds, const Gemm g, const Sched& S, const Epi& E) {
;     ...
;         if constexpr (ALIGN_EPI) { if (wr == 0) PG8_BAR; }
	s_and_b64 vcc, exec, s[8:9]
	s_cbranch_vccz .LBB0_676
	s_barrier

; #define PG8_STAGE(bufoff, gbase, voff) do { _Pragma("unroll") for (int _i = 0; _i < 2; ++_i) \
;         __builtin_amdgcn_global_load_lds((const unsigned*)((const char*)(gbase) + (voff)[_i]), (PG8_LAS unsigned*)(lds + (bufoff) + ldsw + _i * 8192), 16, 0, 0); } while (0)
; #define PG8_LDA(dst, b, h) do { _Pragma("unroll") for (int m = 0; m < 4; ++m) _Pragma("unroll") for (int k = 0; k < 2; ++k) dst[m][k] = *(const PG8_LAS bf16x8*)(lds + PG8_SA(b, h) + aoff + m * 2048 + k * 1024); } while (0)
; #define PG8_LDB(dst, b, h) do { _Pragma("unroll") for (int n = 0; n < 2; ++n) _Pragma("unroll") for (int k = 0; k < 2; ++k) dst[n][k] = *(const PG8_LAS bf16x8*)(lds + PG8_SB(b, h) + boff + n * 2048 + k * 1024); } while (0)
; #define PG8_MMA(ai, bj, At, Bt) do { __builtin_amdgcn_s_setprio(1); _Pragma("unroll") for (int m = 0; m < 4; ++m) _Pragma("unroll") for (int n = 0; n < 2; ++n) _Pragma("unroll") for (int k = 0; k < 2; ++k) \
;         acc[ai][bj][m][n] = __builtin_amdgcn_mfma_f32_16x16x32_bf16(Bt[n][k], At[m][k], acc[ai][bj][m][n], 0, 0, 0); __builtin_amdgcn_s_setprio(0); } while (0)
; #define PG8_WAIT_V(n) asm volatile("s_waitcnt vmcnt(" #n ")" ::: "memory")
; template <class Epi, class Sched, bool ALIGN_EPI = false, bool SP2 = false>
; __device__ __forceinline__ void gemm_phase(PG8_LAS unsigned char* lds, const Gemm g, const Sched& S, const Epi& E) {
;     ...
;         const char* nA = has_next ? (const char*)g.A + (size_t)nxt.pm * tstep : cA; const char* nB = has_next ? (const char*)g.Bt + (size_t)nxt.pn * tstep : cB;
;         for (int t = 0; t < nt; t += 2) {
;             const bool last = (t == nt - 2);
;             const char* a1 = cA + (size_t)(t + 1) * kstep;
;             const char* a2 = last ? nA : cA + (size_t)(t + 2) * kstep; const char* b2 = last ? nB : cB + (size_t)(t + 2) * kstep;
;             const char* a3 = a2 + kstep; const char* b3 = b2 + kstep;
;             if (last && has_next) S.a_ready(nxt);
;             if constexpr (SP2) {
;             PG8_LDB(B0, 0, 0); PG8_LDB(B1, 0, 1); PG8_SCHED; PG8_LDA(At, 0, 0); PG8_STAGE(PG8_SA(1, 1), a1 + hstep, voffA);
;             PG8_WAIT_V(8); PG8_WAIT_L(0); PG8_BAR; PG8_MMA(0, 0, At, B0); PG8_MMA(0, 1, At, B1); PG8_BAR; PG8_SCHED;
;             PG8_LDA(At, 0, 1); PG8_STAGE(PG8_SB(0, 0), b2, voffB); PG8_STAGE(PG8_SB(0, 1), b2 + hstep, voffB); PG8_STAGE(PG8_SA(0, 0), a2, voffA);
.LBB0_1038:
	s_ashr_i32 s15, s14, 31
	s_lshl_b64 s[16:17], s[14:15], 21
	s_add_u32 s16, s30, s16
	s_addc_u32 s17, s31, s17
	s_and_b64 s[18:19], s[2:3], exec
	s_cselect_b32 s15, s17, s27
	s_cselect_b32 s21, s16, s26
	s_ashr_i32 s13, s12, 31
	s_lshl_b64 s[18:19], s[12:13], 21
	s_add_u32 s18, s34, s18
	s_addc_u32 s19, s35, s19
	s_and_b64 s[28:29], s[2:3], exec
	s_cselect_b32 s13, s19, s25
	s_cselect_b32 s65, s18, s24
	s_add_u32 s26, s26, 0x100080
	s_addc_u32 s27, s27, 0
	s_add_u32 s66, s24, 0x100
	s_addc_u32 s67, s25, 0
	s_mov_b32 s68, -2
	v_add_u32_e32 v241, 0x10000, v165
.LBB0_1039:
	ds_read_b128 v[130:133], v241 offset:0
	ds_read_b128 v[134:137], v241 offset:1024
	ds_read_b128 v[138:141], v241 offset:2048
	ds_read_b128 v[142:145], v241 offset:3072
	ds_read_b128 v[146:149], v241 offset:16384
	ds_read_b128 v[150:153], v241 offset:17408
	ds_read_b128 v[172:175], v241 offset:18432
	ds_read_b128 v[176:179], v241 offset:19456
	s_add_u32 s24, s26, 0xfff00080
	s_addc_u32 s25, s27, -1
	s_cmp_eq_u32 s68, 60
	s_cselect_b32 s29, s15, s25
	s_cselect_b32 s28, s21, s24
	s_cselect_b32 s25, s13, s67
	s_cselect_b32 s24, s65, s66
	s_add_i32 m0, s23, 0xc000
	ds_read_b128 v[180:183], v185
	ds_read_b128 v[188:191], v185 offset:1024
	ds_read_b128 v[192:195], v185 offset:2048
	ds_read_b128 v[196:199], v185 offset:3072
	ds_read_b128 v[200:203], v185 offset:4096
	ds_read_b128 v[204:207], v185 offset:5120
	ds_read_b128 v[208:211], v185 offset:6144
	ds_read_b128 v[212:215], v185 offset:7168
	global_load_lds_dwordx4 v162, s[26:27]
	s_add_i32 m0, s23, 0xe000
	s_nop 0
	global_load_lds_dwordx4 v166, s[26:27]
	s_waitcnt vmcnt(8)
	s_waitcnt lgkmcnt(0)
	s_barrier
	s_waitcnt lgkmcnt(0)
	v_mfma_f32_16x16x32_bf16 v[114:117], v[130:133], v[180:183], v[114:117]
	v_mfma_f32_16x16x32_bf16 v[118:121], v[138:141], v[180:183], v[118:121]
	v_mfma_f32_16x16x32_bf16 v[106:109], v[130:133], v[192:195], v[106:109]
	v_mfma_f32_16x16x32_bf16 v[98:101], v[138:141], v[192:195], v[98:101]
	v_mfma_f32_16x16x32_bf16 v[90:93], v[130:133], v[200:203], v[90:93]
	v_mfma_f32_16x16x32_bf16 v[82:85], v[138:141], v[200:203], v[82:85]
	v_mfma_f32_16x16x32_bf16 v[74:77], v[130:133], v[208:211], v[74:77]
	v_mfma_f32_16x16x32_bf16 v[66:69], v[138:141], v[208:211], v[66:69]
	v_mfma_f32_16x16x32_bf16 v[114:117], v[134:137], v[188:191], v[114:117]
	v_mfma_f32_16x16x32_bf16 v[118:121], v[142:145], v[188:191], v[118:121]
	v_mfma_f32_16x16x32_bf16 v[106:109], v[134:137], v[196:199], v[106:109]
	v_mfma_f32_16x16x32_bf16 v[98:101], v[142:145], v[196:199], v[98:101]
	v_mfma_f32_16x16x32_bf16 v[90:93], v[134:137], v[204:207], v[90:93]
	v_mfma_f32_16x16x32_bf16 v[82:85], v[142:145], v[204:207], v[82:85]
	v_mfma_f32_16x16x32_bf16 v[74:77], v[134:137], v[212:215], v[74:77]
	v_mfma_f32_16x16x32_bf16 v[66:69], v[142:145], v[212:215], v[66:69]
	v_mfma_f32_16x16x32_bf16 v[122:125], v[146:149], v[180:183], v[122:125]
	v_mfma_f32_16x16x32_bf16 v[126:129], v[172:175], v[180:183], v[126:129]
	v_mfma_f32_16x16x32_bf16 v[110:113], v[146:149], v[192:195], v[110:113]
	v_mfma_f32_16x16x32_bf16 v[102:105], v[172:175], v[192:195], v[102:105]
	v_mfma_f32_16x16x32_bf16 v[94:97], v[146:149], v[200:203], v[94:97]
	v_mfma_f32_16x16x32_bf16 v[86:89], v[172:175], v[200:203], v[86:89]
	v_mfma_f32_16x16x32_bf16 v[78:81], v[146:149], v[208:211], v[78:81]
	v_mfma_f32_16x16x32_bf16 v[70:73], v[172:175], v[208:211], v[70:73]
	v_mfma_f32_16x16x32_bf16 v[122:125], v[150:153], v[188:191], v[122:125]
	v_mfma_f32_16x16x32_bf16 v[126:129], v[176:179], v[188:191], v[126:129]
	v_mfma_f32_16x16x32_bf16 v[110:113], v[150:153], v[196:199], v[110:113]
	v_mfma_f32_16x16x32_bf16 v[102:105], v[176:179], v[196:199], v[102:105]
	v_mfma_f32_16x16x32_bf16 v[94:97], v[150:153], v[204:207], v[94:97]
	v_mfma_f32_16x16x32_bf16 v[86:89], v[176:179], v[204:207], v[86:89]
	v_mfma_f32_16x16x32_bf16 v[78:81], v[150:153], v[212:215], v[78:81]
	v_mfma_f32_16x16x32_bf16 v[70:73], v[176:179], v[212:215], v[70:73]
	s_barrier
	s_add_i32 s33, s62, s36
	v_lshl_add_u64 v[216:217], s[24:25], 0, v[156:157]
	s_mov_b32 m0, s33
	ds_read_b128 v[180:183], v185 offset:16384
	ds_read_b128 v[188:191], v185 offset:17408
	ds_read_b128 v[192:195], v185 offset:18432
	ds_read_b128 v[196:199], v185 offset:19456
	ds_read_b128 v[200:203], v185 offset:20480
	ds_read_b128 v[204:207], v185 offset:21504
	ds_read_b128 v[208:211], v185 offset:22528
	ds_read_b128 v[212:215], v185 offset:23552
	global_load_lds_dwordx4 v[216:217], off
	s_add_i32 m0, s33, 0x2000
	s_add_u32 s72, s24, 0x100000
	v_lshl_add_u64 v[218:219], s[24:25], 0, v[160:161]
	s_addc_u32 s73, s25, 0
	s_add_i32 s33, s63, s36
	global_load_lds_dwordx4 v[218:219], off
	s_mov_b32 m0, s33
	v_lshl_add_u64 v[222:223], s[28:29], 0, v[158:159]
	global_load_lds_dwordx4 v156, s[72:73]
	s_add_i32 m0, s33, 0x2000
	s_nop 0
	global_load_lds_dwordx4 v160, s[72:73]
	v_lshl_add_u64 v[220:221], s[28:29], 0, v[154:155]
	s_mov_b32 m0, s23
	s_nop 0
	global_load_lds_dwordx4 v[220:221], off
	s_mov_b32 m0, s37
	s_nop 0
	global_load_lds_dwordx4 v[222:223], off
	s_waitcnt vmcnt(8)
	s_waitcnt lgkmcnt(0)
	s_barrier
; #define PG8_STAGE(bufoff, gbase, voff) do { _Pragma("unroll") for (int _i = 0; _i < 2; ++_i) \
;         __builtin_amdgcn_global_load_lds((const unsigned*)((const char*)(gbase) + (voff)[_i]), (PG8_LAS unsigned*)(lds + (bufoff) + ldsw + _i * 8192), 16, 0, 0); } while (0)
; #define PG8_LDA(dst, b, h) do { _Pragma("unroll") for (int m = 0; m < 4; ++m) _Pragma("unroll") for (int k = 0; k < 2; ++k) dst[m][k] = *(const PG8_LAS bf16x8*)(lds + PG8_SA(b, h) + aoff + m * 2048 + k * 1024); } while (0)
; #define PG8_LDB(dst, b, h) do { _Pragma("unroll") for (int n = 0; n < 2; ++n) _Pragma("unroll") for (int k = 0; k < 2; ++k) dst[n][k] = *(const PG8_LAS bf16x8*)(lds + PG8_SB(b, h) + boff + n * 2048 + k * 1024); } while (0)
; #define PG8_MMA(ai, bj, At, Bt) do { __builtin_amdgcn_s_setprio(1); _Pragma("unroll") for (int m = 0; m < 4; ++m) _Pragma("unroll") for (int n = 0; n < 2; ++n) _Pragma("unroll") for (int k = 0; k < 2; ++k) \
;         acc[ai][bj][m][n] = __builtin_amdgcn_mfma_f32_16x16x32_bf16(Bt[n][k], At[m][k], acc[ai][bj][m][n], 0, 0, 0); __builtin_amdgcn_s_setprio(0); } while (0)
; #define PG8_WAIT_V(n) asm volatile("s_waitcnt vmcnt(" #n ")" ::: "memory")
; #define PG8_WAIT_L(n) asm volatile("s_waitcnt lgkmcnt(" #n ")" ::: "memory")
; #define PG8_BAR __builtin_amdgcn_s_barrier()
; #define PG8_SCHED __builtin_amdgcn_sched_barrier(0)
; template <class Epi, class Sched, bool ALIGN_EPI = false, bool SP2 = false>
; __device__ __forceinline__ void gemm_phase(PG8_LAS unsigned char* lds, const Gemm g, const Sched& S, const Epi& E) {
;     ...
;             PG8_WAIT_V(8); PG8_WAIT_L(0); PG8_BAR; PG8_MMA(1, 0, At, B0); PG8_MMA(1, 1, At, B1); PG8_BAR; PG8_SCHED;
;             PG8_LDB(B0, 1, 0); PG8_LDB(B1, 1, 1); PG8_SCHED; PG8_LDA(At, 1, 0); PG8_STAGE(PG8_SA(0, 1), a2 + hstep, voffA);
;             PG8_WAIT_V(8); PG8_WAIT_L(0); PG8_BAR; PG8_MMA(0, 0, At, B0); PG8_MMA(0, 1, At, B1); PG8_BAR; PG8_SCHED;
	s_waitcnt lgkmcnt(0)
	v_mfma_f32_16x16x32_bf16 v[58:61], v[130:133], v[180:183], v[58:61]
	v_mfma_f32_16x16x32_bf16 v[54:57], v[138:141], v[180:183], v[54:57]
	v_mfma_f32_16x16x32_bf16 v[42:45], v[130:133], v[192:195], v[42:45]
	v_mfma_f32_16x16x32_bf16 v[34:37], v[138:141], v[192:195], v[34:37]
	v_mfma_f32_16x16x32_bf16 v[26:29], v[130:133], v[200:203], v[26:29]
	v_mfma_f32_16x16x32_bf16 v[18:21], v[138:141], v[200:203], v[18:21]
	v_mfma_f32_16x16x32_bf16 v[6:9], v[130:133], v[208:211], v[6:9]
	v_mfma_f32_16x16x32_bf16 v[2:5], v[138:141], v[208:211], v[2:5]
	v_mfma_f32_16x16x32_bf16 v[58:61], v[134:137], v[188:191], v[58:61]
	v_mfma_f32_16x16x32_bf16 v[54:57], v[142:145], v[188:191], v[54:57]
	v_mfma_f32_16x16x32_bf16 v[42:45], v[134:137], v[196:199], v[42:45]
	v_mfma_f32_16x16x32_bf16 v[34:37], v[142:145], v[196:199], v[34:37]
	v_mfma_f32_16x16x32_bf16 v[26:29], v[134:137], v[204:207], v[26:29]
	v_mfma_f32_16x16x32_bf16 v[18:21], v[142:145], v[204:207], v[18:21]
	v_mfma_f32_16x16x32_bf16 v[6:9], v[134:137], v[212:215], v[6:9]
	v_mfma_f32_16x16x32_bf16 v[2:5], v[142:145], v[212:215], v[2:5]
	v_mfma_f32_16x16x32_bf16 v[62:65], v[146:149], v[180:183], v[62:65]
	v_mfma_f32_16x16x32_bf16 v[50:53], v[172:175], v[180:183], v[50:53]
	v_mfma_f32_16x16x32_bf16 v[46:49], v[146:149], v[192:195], v[46:49]
	v_mfma_f32_16x16x32_bf16 v[38:41], v[172:175], v[192:195], v[38:41]
	v_mfma_f32_16x16x32_bf16 v[30:33], v[146:149], v[200:203], v[30:33]
	v_mfma_f32_16x16x32_bf16 v[22:25], v[172:175], v[200:203], v[22:25]
	v_mfma_f32_16x16x32_bf16 v[10:13], v[146:149], v[208:211], v[10:13]
	v_mfma_f32_16x16x32_bf16 v[14:17], v[172:175], v[208:211], v[14:17]
	v_mfma_f32_16x16x32_bf16 v[62:65], v[150:153], v[188:191], v[62:65]
	v_mfma_f32_16x16x32_bf16 v[50:53], v[176:179], v[188:191], v[50:53]
	v_mfma_f32_16x16x32_bf16 v[46:49], v[150:153], v[196:199], v[46:49]
	v_mfma_f32_16x16x32_bf16 v[38:41], v[176:179], v[196:199], v[38:41]
	v_mfma_f32_16x16x32_bf16 v[30:33], v[150:153], v[204:207], v[30:33]
	v_mfma_f32_16x16x32_bf16 v[22:25], v[176:179], v[204:207], v[22:25]
	v_mfma_f32_16x16x32_bf16 v[10:13], v[150:153], v[212:215], v[10:13]
	v_mfma_f32_16x16x32_bf16 v[14:17], v[176:179], v[212:215], v[14:17]
	s_barrier
	s_add_i32 s33, 0, 0x18000
	s_add_i32 s42, 0, 0x1c000
	ds_read_b128 v[130:133], v241 offset:32768
	ds_read_b128 v[134:137], v241 offset:33792
	ds_read_b128 v[138:141], v241 offset:34816
	ds_read_b128 v[142:145], v241 offset:35840
	ds_read_b128 v[146:149], v241 offset:49152
	ds_read_b128 v[150:153], v241 offset:50176
	ds_read_b128 v[172:175], v241 offset:51200
	ds_read_b128 v[176:179], v241 offset:52224
	s_add_u32 s28, s28, 0x100000
	s_addc_u32 s29, s29, 0
	s_mov_b32 m0, s40
	ds_read_b128 v[180:183], v185 offset:32768
	ds_read_b128 v[188:191], v185 offset:33792
	ds_read_b128 v[192:195], v185 offset:34816
	ds_read_b128 v[196:199], v185 offset:35840
	ds_read_b128 v[200:203], v185 offset:36864
	ds_read_b128 v[204:207], v185 offset:37888
	ds_read_b128 v[208:211], v185 offset:38912
	ds_read_b128 v[212:215], v185 offset:39936
	global_load_lds_dwordx4 v154, s[28:29]
	s_mov_b32 m0, s41
	s_nop 0
	global_load_lds_dwordx4 v158, s[28:29]
	s_waitcnt vmcnt(8)
	s_waitcnt lgkmcnt(0)
	s_barrier
	s_waitcnt lgkmcnt(0)
	v_mfma_f32_16x16x32_bf16 v[114:117], v[130:133], v[180:183], v[114:117]
	v_mfma_f32_16x16x32_bf16 v[118:121], v[138:141], v[180:183], v[118:121]
	v_mfma_f32_16x16x32_bf16 v[106:109], v[130:133], v[192:195], v[106:109]
	v_mfma_f32_16x16x32_bf16 v[98:101], v[138:141], v[192:195], v[98:101]
	v_mfma_f32_16x16x32_bf16 v[90:93], v[130:133], v[200:203], v[90:93]
	v_mfma_f32_16x16x32_bf16 v[82:85], v[138:141], v[200:203], v[82:85]
	v_mfma_f32_16x16x32_bf16 v[74:77], v[130:133], v[208:211], v[74:77]
	v_mfma_f32_16x16x32_bf16 v[66:69], v[138:141], v[208:211], v[66:69]
	v_mfma_f32_16x16x32_bf16 v[114:117], v[134:137], v[188:191], v[114:117]
	v_mfma_f32_16x16x32_bf16 v[118:121], v[142:145], v[188:191], v[118:121]
	v_mfma_f32_16x16x32_bf16 v[106:109], v[134:137], v[196:199], v[106:109]
	v_mfma_f32_16x16x32_bf16 v[98:101], v[142:145], v[196:199], v[98:101]
	v_mfma_f32_16x16x32_bf16 v[90:93], v[134:137], v[204:207], v[90:93]
	v_mfma_f32_16x16x32_bf16 v[82:85], v[142:145], v[204:207], v[82:85]
	v_mfma_f32_16x16x32_bf16 v[74:77], v[134:137], v[212:215], v[74:77]
	v_mfma_f32_16x16x32_bf16 v[66:69], v[142:145], v[212:215], v[66:69]
	v_mfma_f32_16x16x32_bf16 v[122:125], v[146:149], v[180:183], v[122:125]
	v_mfma_f32_16x16x32_bf16 v[126:129], v[172:175], v[180:183], v[126:129]
	v_mfma_f32_16x16x32_bf16 v[110:113], v[146:149], v[192:195], v[110:113]
	v_mfma_f32_16x16x32_bf16 v[102:105], v[172:175], v[192:195], v[102:105]
	v_mfma_f32_16x16x32_bf16 v[94:97], v[146:149], v[200:203], v[94:97]
	v_mfma_f32_16x16x32_bf16 v[86:89], v[172:175], v[200:203], v[86:89]
	v_mfma_f32_16x16x32_bf16 v[78:81], v[146:149], v[208:211], v[78:81]
	v_mfma_f32_16x16x32_bf16 v[70:73], v[172:175], v[208:211], v[70:73]
	v_mfma_f32_16x16x32_bf16 v[122:125], v[150:153], v[188:191], v[122:125]
	v_mfma_f32_16x16x32_bf16 v[126:129], v[176:179], v[188:191], v[126:129]
	v_mfma_f32_16x16x32_bf16 v[110:113], v[150:153], v[196:199], v[110:113]
	v_mfma_f32_16x16x32_bf16 v[102:105], v[176:179], v[196:199], v[102:105]
	v_mfma_f32_16x16x32_bf16 v[94:97], v[150:153], v[204:207], v[94:97]
	v_mfma_f32_16x16x32_bf16 v[86:89], v[176:179], v[204:207], v[86:89]
	v_mfma_f32_16x16x32_bf16 v[78:81], v[150:153], v[212:215], v[78:81]
	v_mfma_f32_16x16x32_bf16 v[70:73], v[176:179], v[212:215], v[70:73]
	s_barrier
; #define PG8_STAGE(bufoff, gbase, voff) do { _Pragma("unroll") for (int _i = 0; _i < 2; ++_i) \
;         __builtin_amdgcn_global_load_lds((const unsigned*)((const char*)(gbase) + (voff)[_i]), (PG8_LAS unsigned*)(lds + (bufoff) + ldsw + _i * 8192), 16, 0, 0); } while (0)
; #define PG8_LDA(dst, b, h) do { _Pragma("unroll") for (int m = 0; m < 4; ++m) _Pragma("unroll") for (int k = 0; k < 2; ++k) dst[m][k] = *(const PG8_LAS bf16x8*)(lds + PG8_SA(b, h) + aoff + m * 2048 + k * 1024); } while (0)
; #define PG8_MMA(ai, bj, At, Bt) do { __builtin_amdgcn_s_setprio(1); _Pragma("unroll") for (int m = 0; m < 4; ++m) _Pragma("unroll") for (int n = 0; n < 2; ++n) _Pragma("unroll") for (int k = 0; k < 2; ++k) \
;         acc[ai][bj][m][n] = __builtin_amdgcn_mfma_f32_16x16x32_bf16(Bt[n][k], At[m][k], acc[ai][bj][m][n], 0, 0, 0); __builtin_amdgcn_s_setprio(0); } while (0)
; #define PG8_WAIT_V(n) asm volatile("s_waitcnt vmcnt(" #n ")" ::: "memory")
; #define PG8_WAIT_L(n) asm volatile("s_waitcnt lgkmcnt(" #n ")" ::: "memory")
; #define PG8_BAR __builtin_amdgcn_s_barrier()
; #define PG8_SCHED __builtin_amdgcn_sched_barrier(0)
; template <class Epi, class Sched, bool ALIGN_EPI = false, bool SP2 = false>
; __device__ __forceinline__ void gemm_phase(PG8_LAS unsigned char* lds, const Gemm g, const Sched& S, const Epi& E) {
;     ...
;         for (int t = 0; t < nt; t += 2) {
;     ...
;             PG8_LDA(At, 1, 1); PG8_STAGE(PG8_SB(1, 0), b3, voffB); PG8_STAGE(PG8_SB(1, 1), b3 + hstep, voffB); PG8_STAGE(PG8_SA(1, 0), a3, voffA);
;             PG8_WAIT_V(8); PG8_WAIT_L(0); PG8_BAR; PG8_MMA(1, 0, At, B0); PG8_MMA(1, 1, At, B1); PG8_BAR; PG8_SCHED;
	s_add_i32 s28, s33, s36
	s_add_i32 m0, s28, 0xffffff80
	ds_read_b128 v[180:183], v185 offset:49152
	ds_read_b128 v[188:191], v185 offset:50176
	ds_read_b128 v[192:195], v185 offset:51200
	ds_read_b128 v[196:199], v185 offset:52224
	ds_read_b128 v[200:203], v185 offset:53248
	ds_read_b128 v[204:207], v185 offset:54272
	ds_read_b128 v[208:211], v185 offset:55296
	ds_read_b128 v[212:215], v185 offset:56320
	global_load_lds_dwordx4 v[216:217], off offset:128
	s_add_i32 m0, s28, 0x1f80
	s_add_u32 s24, s24, 0x100080
	s_addc_u32 s25, s25, 0
	s_add_i32 s28, s42, s36
	global_load_lds_dwordx4 v[218:219], off offset:128
	s_mov_b32 m0, s28
	s_nop 0
	global_load_lds_dwordx4 v156, s[24:25]
	s_add_i32 m0, s28, 0x2000
	s_nop 0
	global_load_lds_dwordx4 v160, s[24:25]
	s_add_i32 m0, s46, 0xffffff80
	s_nop 0
	global_load_lds_dwordx4 v[220:221], off offset:128
	s_add_i32 m0, s47, 0xffffff80
	s_nop 0
	global_load_lds_dwordx4 v[222:223], off offset:128
	s_waitcnt vmcnt(8)
	s_waitcnt lgkmcnt(0)
	s_barrier
	s_waitcnt lgkmcnt(0)
	v_mfma_f32_16x16x32_bf16 v[58:61], v[130:133], v[180:183], v[58:61]
	v_mfma_f32_16x16x32_bf16 v[54:57], v[138:141], v[180:183], v[54:57]
	v_mfma_f32_16x16x32_bf16 v[42:45], v[130:133], v[192:195], v[42:45]
	v_mfma_f32_16x16x32_bf16 v[34:37], v[138:141], v[192:195], v[34:37]
	v_mfma_f32_16x16x32_bf16 v[26:29], v[130:133], v[200:203], v[26:29]
	v_mfma_f32_16x16x32_bf16 v[18:21], v[138:141], v[200:203], v[18:21]
	v_mfma_f32_16x16x32_bf16 v[6:9], v[130:133], v[208:211], v[6:9]
	v_mfma_f32_16x16x32_bf16 v[2:5], v[138:141], v[208:211], v[2:5]
	v_mfma_f32_16x16x32_bf16 v[58:61], v[134:137], v[188:191], v[58:61]
	v_mfma_f32_16x16x32_bf16 v[54:57], v[142:145], v[188:191], v[54:57]
	v_mfma_f32_16x16x32_bf16 v[42:45], v[134:137], v[196:199], v[42:45]
	v_mfma_f32_16x16x32_bf16 v[34:37], v[142:145], v[196:199], v[34:37]
	v_mfma_f32_16x16x32_bf16 v[26:29], v[134:137], v[204:207], v[26:29]
	v_mfma_f32_16x16x32_bf16 v[18:21], v[142:145], v[204:207], v[18:21]
	v_mfma_f32_16x16x32_bf16 v[6:9], v[134:137], v[212:215], v[6:9]
	v_mfma_f32_16x16x32_bf16 v[2:5], v[142:145], v[212:215], v[2:5]
	v_mfma_f32_16x16x32_bf16 v[62:65], v[146:149], v[180:183], v[62:65]
	v_mfma_f32_16x16x32_bf16 v[50:53], v[172:175], v[180:183], v[50:53]
	v_mfma_f32_16x16x32_bf16 v[46:49], v[146:149], v[192:195], v[46:49]
	v_mfma_f32_16x16x32_bf16 v[38:41], v[172:175], v[192:195], v[38:41]
	v_mfma_f32_16x16x32_bf16 v[30:33], v[146:149], v[200:203], v[30:33]
	v_mfma_f32_16x16x32_bf16 v[22:25], v[172:175], v[200:203], v[22:25]
	v_mfma_f32_16x16x32_bf16 v[10:13], v[146:149], v[208:211], v[10:13]
	v_mfma_f32_16x16x32_bf16 v[14:17], v[172:175], v[208:211], v[14:17]
	v_mfma_f32_16x16x32_bf16 v[62:65], v[150:153], v[188:191], v[62:65]
	v_mfma_f32_16x16x32_bf16 v[50:53], v[176:179], v[188:191], v[50:53]
	v_mfma_f32_16x16x32_bf16 v[46:49], v[150:153], v[196:199], v[46:49]
	v_mfma_f32_16x16x32_bf16 v[38:41], v[176:179], v[196:199], v[38:41]
	v_mfma_f32_16x16x32_bf16 v[30:33], v[150:153], v[204:207], v[30:33]
	v_mfma_f32_16x16x32_bf16 v[22:25], v[176:179], v[204:207], v[22:25]
	v_mfma_f32_16x16x32_bf16 v[10:13], v[150:153], v[212:215], v[10:13]
	v_mfma_f32_16x16x32_bf16 v[14:17], v[176:179], v[212:215], v[14:17]
	s_barrier
	s_add_i32 s68, s68, 2
	s_add_u32 s26, s26, 0x100
	s_addc_u32 s27, s27, 0
	s_add_u32 s66, s66, 0x100
	s_addc_u32 s67, s67, 0
	s_cmp_gt_u32 s68, 61
	s_cbranch_scc0 .LBB0_1039


; #define PG8_BAR __builtin_amdgcn_s_barrier()
; template <class Epi, class Sched, bool ALIGN_EPI = false, bool SP2 = false>
; __device__ __forceinline__ void gemm_phase(PG8_LAS unsigned char* lds, const Gemm g, const Sched& S, const Epi& E) {
;     ...
;         if constexpr (ALIGN_EPI) { if (wr == 0) PG8_BAR; }
	s_and_b64 vcc, exec, s[10:11]
	s_cbranch_vccz .LBB0_1042
	s_barrier

; #define PG8_STAGE(bufoff, gbase, voff) do { _Pragma("unroll") for (int _i = 0; _i < 2; ++_i) \
;         __builtin_amdgcn_global_load_lds((const unsigned*)((const char*)(gbase) + (voff)[_i]), (PG8_LAS unsigned*)(lds + (bufoff) + ldsw + _i * 8192), 16, 0, 0); } while (0)
; #define PG8_LDA(dst, b, h) do { _Pragma("unroll") for (int m = 0; m < 4; ++m) _Pragma("unroll") for (int k = 0; k < 2; ++k) dst[m][k] = *(const PG8_LAS bf16x8*)(lds + PG8_SA(b, h) + aoff + m * 2048 + k * 1024); } while (0)
; #define PG8_LDB(dst, b, h) do { _Pragma("unroll") for (int n = 0; n < 2; ++n) _Pragma("unroll") for (int k = 0; k < 2; ++k) dst[n][k] = *(const PG8_LAS bf16x8*)(lds + PG8_SB(b, h) + boff + n * 2048 + k * 1024); } while (0)
; #define PG8_MMA(ai, bj, At, Bt) do { __builtin_amdgcn_s_setprio(1); _Pragma("unroll") for (int m = 0; m < 4; ++m) _Pragma("unroll") for (int n = 0; n < 2; ++n) _Pragma("unroll") for (int k = 0; k < 2; ++k) \
;         acc[ai][bj][m][n] = __builtin_amdgcn_mfma_f32_16x16x32_bf16(Bt[n][k], At[m][k], acc[ai][bj][m][n], 0, 0, 0); __builtin_amdgcn_s_setprio(0); } while (0)
; #define PG8_WAIT_V(n) asm volatile("s_waitcnt vmcnt(" #n ")" ::: "memory")
; template <class Epi, class Sched, bool ALIGN_EPI = false, bool SP2 = false>
; __device__ __forceinline__ void gemm_phase(PG8_LAS unsigned char* lds, const Gemm g, const Sched& S, const Epi& E) {
;     ...
;         const char* nA = has_next ? (const char*)g.A + (size_t)nxt.pm * tstep : cA; const char* nB = has_next ? (const char*)g.Bt + (size_t)nxt.pn * tstep : cB;
;         for (int t = 0; t < nt; t += 2) {
;             const bool last = (t == nt - 2);
;             const char* a1 = cA + (size_t)(t + 1) * kstep;
;             const char* a2 = last ? nA : cA + (size_t)(t + 2) * kstep; const char* b2 = last ? nB : cB + (size_t)(t + 2) * kstep;
;             const char* a3 = a2 + kstep; const char* b3 = b2 + kstep;
;             if (last && has_next) S.a_ready(nxt);
;             if constexpr (SP2) {
;             PG8_LDB(B0, 0, 0); PG8_LDB(B1, 0, 1); PG8_SCHED; PG8_LDA(At, 0, 0); PG8_STAGE(PG8_SA(1, 1), a1 + hstep, voffA);
;             PG8_WAIT_V(8); PG8_WAIT_L(0); PG8_BAR; PG8_MMA(0, 0, At, B0); PG8_MMA(0, 1, At, B1); PG8_BAR; PG8_SCHED;
;             PG8_LDA(At, 0, 1); PG8_STAGE(PG8_SB(0, 0), b2, voffB); PG8_STAGE(PG8_SB(0, 1), b2 + hstep, voffB); PG8_STAGE(PG8_SA(0, 0), a2, voffA);
.LBB0_1125:
	s_ashr_i32 s15, s14, 31
	s_lshl_b64 s[16:17], s[14:15], 21
	s_add_u32 s16, s96, s16
	s_addc_u32 s17, s97, s17
	s_and_b64 s[18:19], s[0:1], exec
	s_cselect_b32 s15, s17, s25
	s_cselect_b32 s64, s16, s24
	s_ashr_i32 s13, s12, 31
	s_lshl_b64 s[18:19], s[12:13], 21
	s_add_u32 s18, s11, s18
	s_addc_u32 s19, s28, s19
	s_and_b64 s[26:27], s[0:1], exec
	s_cselect_b32 s13, s19, s23
	s_cselect_b32 s65, s18, s22
	s_add_u32 s24, s24, 0x100080
	s_addc_u32 s25, s25, 0
	s_add_u32 s66, s22, 0x100
	s_addc_u32 s67, s23, 0
	s_mov_b32 s68, -2
	v_add_u32_e32 v241, 0x10000, v151
.LBB0_1126:
	ds_read_b128 v[160:163], v241 offset:0
	ds_read_b128 v[166:169], v241 offset:1024
	ds_read_b128 v[170:173], v241 offset:2048
	ds_read_b128 v[174:177], v241 offset:3072
	ds_read_b128 v[178:181], v241 offset:16384
	ds_read_b128 v[182:185], v241 offset:17408
	ds_read_b128 v[186:189], v241 offset:18432
	ds_read_b128 v[190:193], v241 offset:19456
	s_add_u32 s22, s24, 0xfff00080
	s_addc_u32 s23, s25, -1
	s_cmp_eq_u32 s68, 60
	s_cselect_b32 s27, s15, s23
	s_cselect_b32 s26, s64, s22
	s_cselect_b32 s23, s13, s67
	s_cselect_b32 s22, s65, s66
	s_add_i32 m0, s21, 0xc000
	ds_read_b128 v[194:197], v155
	ds_read_b128 v[198:201], v155 offset:1024
	ds_read_b128 v[202:205], v155 offset:2048
	ds_read_b128 v[206:209], v155 offset:3072
	ds_read_b128 v[210:213], v155 offset:4096
	ds_read_b128 v[214:217], v155 offset:5120
	ds_read_b128 v[218:221], v155 offset:6144
	ds_read_b128 v[222:225], v155 offset:7168
	global_load_lds_dwordx4 v138, s[24:25]
	s_add_i32 m0, s21, 0xe000
	s_nop 0
	global_load_lds_dwordx4 v140, s[24:25]
	s_waitcnt vmcnt(8)
	s_waitcnt lgkmcnt(0)
	s_barrier
	s_waitcnt lgkmcnt(0)
	v_mfma_f32_16x16x32_bf16 v[122:125], v[160:163], v[194:197], v[122:125]
	v_mfma_f32_16x16x32_bf16 v[114:117], v[170:173], v[194:197], v[114:117]
	v_mfma_f32_16x16x32_bf16 v[106:109], v[160:163], v[202:205], v[106:109]
	v_mfma_f32_16x16x32_bf16 v[98:101], v[170:173], v[202:205], v[98:101]
	v_mfma_f32_16x16x32_bf16 v[90:93], v[160:163], v[210:213], v[90:93]
	v_mfma_f32_16x16x32_bf16 v[82:85], v[170:173], v[210:213], v[82:85]
	v_mfma_f32_16x16x32_bf16 v[74:77], v[160:163], v[218:221], v[74:77]
	v_mfma_f32_16x16x32_bf16 v[62:65], v[170:173], v[218:221], v[62:65]
	v_mfma_f32_16x16x32_bf16 v[122:125], v[166:169], v[198:201], v[122:125]
	v_mfma_f32_16x16x32_bf16 v[114:117], v[174:177], v[198:201], v[114:117]
	v_mfma_f32_16x16x32_bf16 v[106:109], v[166:169], v[206:209], v[106:109]
	v_mfma_f32_16x16x32_bf16 v[98:101], v[174:177], v[206:209], v[98:101]
	v_mfma_f32_16x16x32_bf16 v[90:93], v[166:169], v[214:217], v[90:93]
	v_mfma_f32_16x16x32_bf16 v[82:85], v[174:177], v[214:217], v[82:85]
	v_mfma_f32_16x16x32_bf16 v[74:77], v[166:169], v[222:225], v[74:77]
	v_mfma_f32_16x16x32_bf16 v[62:65], v[174:177], v[222:225], v[62:65]
	v_mfma_f32_16x16x32_bf16 v[126:129], v[178:181], v[194:197], v[126:129]
	v_mfma_f32_16x16x32_bf16 v[118:121], v[186:189], v[194:197], v[118:121]
	v_mfma_f32_16x16x32_bf16 v[110:113], v[178:181], v[202:205], v[110:113]
	v_mfma_f32_16x16x32_bf16 v[102:105], v[186:189], v[202:205], v[102:105]
	v_mfma_f32_16x16x32_bf16 v[94:97], v[178:181], v[210:213], v[94:97]
	v_mfma_f32_16x16x32_bf16 v[86:89], v[186:189], v[210:213], v[86:89]
	v_mfma_f32_16x16x32_bf16 v[78:81], v[178:181], v[218:221], v[78:81]
	v_mfma_f32_16x16x32_bf16 v[70:73], v[186:189], v[218:221], v[70:73]
	v_mfma_f32_16x16x32_bf16 v[126:129], v[182:185], v[198:201], v[126:129]
	v_mfma_f32_16x16x32_bf16 v[118:121], v[190:193], v[198:201], v[118:121]
	v_mfma_f32_16x16x32_bf16 v[110:113], v[182:185], v[206:209], v[110:113]
	v_mfma_f32_16x16x32_bf16 v[102:105], v[190:193], v[206:209], v[102:105]
	v_mfma_f32_16x16x32_bf16 v[94:97], v[182:185], v[214:217], v[94:97]
	v_mfma_f32_16x16x32_bf16 v[86:89], v[190:193], v[214:217], v[86:89]
	v_mfma_f32_16x16x32_bf16 v[78:81], v[182:185], v[222:225], v[78:81]
	v_mfma_f32_16x16x32_bf16 v[70:73], v[190:193], v[222:225], v[70:73]
	s_barrier
	s_add_i32 s33, s52, s29
	v_lshl_add_u64 v[148:149], s[22:23], 0, v[132:133]
	s_mov_b32 m0, s33
	ds_read_b128 v[194:197], v155 offset:16384
	ds_read_b128 v[198:201], v155 offset:17408
	ds_read_b128 v[202:205], v155 offset:18432
	ds_read_b128 v[206:209], v155 offset:19456
	ds_read_b128 v[210:213], v155 offset:20480
	ds_read_b128 v[214:217], v155 offset:21504
	ds_read_b128 v[218:221], v155 offset:22528
	ds_read_b128 v[222:225], v155 offset:23552
	global_load_lds_dwordx4 v[148:149], off
	s_add_i32 m0, s33, 0x2000
	s_add_u32 s72, s22, 0x100000
	v_lshl_add_u64 v[156:157], s[22:23], 0, v[136:137]
	s_addc_u32 s73, s23, 0
	s_add_i32 s33, s53, s29
	global_load_lds_dwordx4 v[156:157], off
	s_mov_b32 m0, s33
	v_lshl_add_u64 v[228:229], s[26:27], 0, v[134:135]
	global_load_lds_dwordx4 v132, s[72:73]
	s_add_i32 m0, s33, 0x2000
	s_nop 0
	global_load_lds_dwordx4 v136, s[72:73]
	v_lshl_add_u64 v[226:227], s[26:27], 0, v[130:131]
	s_mov_b32 m0, s21
	s_nop 0
	global_load_lds_dwordx4 v[226:227], off
	s_mov_b32 m0, s36
	s_nop 0
	global_load_lds_dwordx4 v[228:229], off
	s_waitcnt vmcnt(8)
	s_waitcnt lgkmcnt(0)
	s_barrier
; #define PG8_STAGE(bufoff, gbase, voff) do { _Pragma("unroll") for (int _i = 0; _i < 2; ++_i) \
;         __builtin_amdgcn_global_load_lds((const unsigned*)((const char*)(gbase) + (voff)[_i]), (PG8_LAS unsigned*)(lds + (bufoff) + ldsw + _i * 8192), 16, 0, 0); } while (0)
; #define PG8_LDA(dst, b, h) do { _Pragma("unroll") for (int m = 0; m < 4; ++m) _Pragma("unroll") for (int k = 0; k < 2; ++k) dst[m][k] = *(const PG8_LAS bf16x8*)(lds + PG8_SA(b, h) + aoff + m * 2048 + k * 1024); } while (0)
; #define PG8_LDB(dst, b, h) do { _Pragma("unroll") for (int n = 0; n < 2; ++n) _Pragma("unroll") for (int k = 0; k < 2; ++k) dst[n][k] = *(const PG8_LAS bf16x8*)(lds + PG8_SB(b, h) + boff + n * 2048 + k * 1024); } while (0)
; #define PG8_MMA(ai, bj, At, Bt) do { __builtin_amdgcn_s_setprio(1); _Pragma("unroll") for (int m = 0; m < 4; ++m) _Pragma("unroll") for (int n = 0; n < 2; ++n) _Pragma("unroll") for (int k = 0; k < 2; ++k) \
;         acc[ai][bj][m][n] = __builtin_amdgcn_mfma_f32_16x16x32_bf16(Bt[n][k], At[m][k], acc[ai][bj][m][n], 0, 0, 0); __builtin_amdgcn_s_setprio(0); } while (0)
; #define PG8_WAIT_V(n) asm volatile("s_waitcnt vmcnt(" #n ")" ::: "memory")
; #define PG8_WAIT_L(n) asm volatile("s_waitcnt lgkmcnt(" #n ")" ::: "memory")
; #define PG8_BAR __builtin_amdgcn_s_barrier()
; #define PG8_SCHED __builtin_amdgcn_sched_barrier(0)
; template <class Epi, class Sched, bool ALIGN_EPI = false, bool SP2 = false>
; __device__ __forceinline__ void gemm_phase(PG8_LAS unsigned char* lds, const Gemm g, const Sched& S, const Epi& E) {
;     ...
;             PG8_WAIT_V(8); PG8_WAIT_L(0); PG8_BAR; PG8_MMA(1, 0, At, B0); PG8_MMA(1, 1, At, B1); PG8_BAR; PG8_SCHED;
;             PG8_LDB(B0, 1, 0); PG8_LDB(B1, 1, 1); PG8_SCHED; PG8_LDA(At, 1, 0); PG8_STAGE(PG8_SA(0, 1), a2 + hstep, voffA);
;             PG8_WAIT_V(8); PG8_WAIT_L(0); PG8_BAR; PG8_MMA(0, 0, At, B0); PG8_MMA(0, 1, At, B1); PG8_BAR; PG8_SCHED;
	s_waitcnt lgkmcnt(0)
	v_mfma_f32_16x16x32_bf16 v[58:61], v[160:163], v[194:197], v[58:61]
	v_mfma_f32_16x16x32_bf16 v[50:53], v[170:173], v[194:197], v[50:53]
	v_mfma_f32_16x16x32_bf16 v[42:45], v[160:163], v[202:205], v[42:45]
	v_mfma_f32_16x16x32_bf16 v[34:37], v[170:173], v[202:205], v[34:37]
	v_mfma_f32_16x16x32_bf16 v[26:29], v[160:163], v[210:213], v[26:29]
	v_mfma_f32_16x16x32_bf16 v[18:21], v[170:173], v[210:213], v[18:21]
	v_mfma_f32_16x16x32_bf16 v[10:13], v[160:163], v[218:221], v[10:13]
	v_mfma_f32_16x16x32_bf16 v[2:5], v[170:173], v[218:221], v[2:5]
	v_mfma_f32_16x16x32_bf16 v[58:61], v[166:169], v[198:201], v[58:61]
	v_mfma_f32_16x16x32_bf16 v[50:53], v[174:177], v[198:201], v[50:53]
	v_mfma_f32_16x16x32_bf16 v[42:45], v[166:169], v[206:209], v[42:45]
	v_mfma_f32_16x16x32_bf16 v[34:37], v[174:177], v[206:209], v[34:37]
	v_mfma_f32_16x16x32_bf16 v[26:29], v[166:169], v[214:217], v[26:29]
	v_mfma_f32_16x16x32_bf16 v[18:21], v[174:177], v[214:217], v[18:21]
	v_mfma_f32_16x16x32_bf16 v[10:13], v[166:169], v[222:225], v[10:13]
	v_mfma_f32_16x16x32_bf16 v[2:5], v[174:177], v[222:225], v[2:5]
	v_mfma_f32_16x16x32_bf16 v[66:69], v[178:181], v[194:197], v[66:69]
	v_mfma_f32_16x16x32_bf16 v[54:57], v[186:189], v[194:197], v[54:57]
	v_mfma_f32_16x16x32_bf16 v[46:49], v[178:181], v[202:205], v[46:49]
	v_mfma_f32_16x16x32_bf16 v[38:41], v[186:189], v[202:205], v[38:41]
	v_mfma_f32_16x16x32_bf16 v[30:33], v[178:181], v[210:213], v[30:33]
	v_mfma_f32_16x16x32_bf16 v[22:25], v[186:189], v[210:213], v[22:25]
	v_mfma_f32_16x16x32_bf16 v[14:17], v[178:181], v[218:221], v[14:17]
	v_mfma_f32_16x16x32_bf16 v[6:9], v[186:189], v[218:221], v[6:9]
	v_mfma_f32_16x16x32_bf16 v[66:69], v[182:185], v[198:201], v[66:69]
	v_mfma_f32_16x16x32_bf16 v[54:57], v[190:193], v[198:201], v[54:57]
	v_mfma_f32_16x16x32_bf16 v[46:49], v[182:185], v[206:209], v[46:49]
	v_mfma_f32_16x16x32_bf16 v[38:41], v[190:193], v[206:209], v[38:41]
	v_mfma_f32_16x16x32_bf16 v[30:33], v[182:185], v[214:217], v[30:33]
	v_mfma_f32_16x16x32_bf16 v[22:25], v[190:193], v[214:217], v[22:25]
	v_mfma_f32_16x16x32_bf16 v[14:17], v[182:185], v[222:225], v[14:17]
	v_mfma_f32_16x16x32_bf16 v[6:9], v[190:193], v[222:225], v[6:9]
	s_barrier
	s_add_i32 s33, 0, 0x18000
	s_add_i32 s42, 0, 0x1c000
	ds_read_b128 v[160:163], v241 offset:32768
	ds_read_b128 v[166:169], v241 offset:33792
	ds_read_b128 v[170:173], v241 offset:34816
	ds_read_b128 v[174:177], v241 offset:35840
	ds_read_b128 v[178:181], v241 offset:49152
	ds_read_b128 v[182:185], v241 offset:50176
	ds_read_b128 v[186:189], v241 offset:51200
	ds_read_b128 v[190:193], v241 offset:52224
	s_add_u32 s26, s26, 0x100000
	s_addc_u32 s27, s27, 0
	s_mov_b32 m0, s37
	ds_read_b128 v[194:197], v155 offset:32768
	ds_read_b128 v[198:201], v155 offset:33792
	ds_read_b128 v[202:205], v155 offset:34816
	ds_read_b128 v[206:209], v155 offset:35840
	ds_read_b128 v[210:213], v155 offset:36864
	ds_read_b128 v[214:217], v155 offset:37888
	ds_read_b128 v[218:221], v155 offset:38912
	ds_read_b128 v[222:225], v155 offset:39936
	global_load_lds_dwordx4 v130, s[26:27]
	s_mov_b32 m0, s40
	s_nop 0
	global_load_lds_dwordx4 v134, s[26:27]
	s_waitcnt vmcnt(8)
	s_waitcnt lgkmcnt(0)
	s_barrier
	s_waitcnt lgkmcnt(0)
	v_mfma_f32_16x16x32_bf16 v[122:125], v[160:163], v[194:197], v[122:125]
	v_mfma_f32_16x16x32_bf16 v[114:117], v[170:173], v[194:197], v[114:117]
	v_mfma_f32_16x16x32_bf16 v[106:109], v[160:163], v[202:205], v[106:109]
	v_mfma_f32_16x16x32_bf16 v[98:101], v[170:173], v[202:205], v[98:101]
	v_mfma_f32_16x16x32_bf16 v[90:93], v[160:163], v[210:213], v[90:93]
	v_mfma_f32_16x16x32_bf16 v[82:85], v[170:173], v[210:213], v[82:85]
	v_mfma_f32_16x16x32_bf16 v[74:77], v[160:163], v[218:221], v[74:77]
	v_mfma_f32_16x16x32_bf16 v[62:65], v[170:173], v[218:221], v[62:65]
	v_mfma_f32_16x16x32_bf16 v[122:125], v[166:169], v[198:201], v[122:125]
	v_mfma_f32_16x16x32_bf16 v[114:117], v[174:177], v[198:201], v[114:117]
	v_mfma_f32_16x16x32_bf16 v[106:109], v[166:169], v[206:209], v[106:109]
	v_mfma_f32_16x16x32_bf16 v[98:101], v[174:177], v[206:209], v[98:101]
	v_mfma_f32_16x16x32_bf16 v[90:93], v[166:169], v[214:217], v[90:93]
	v_mfma_f32_16x16x32_bf16 v[82:85], v[174:177], v[214:217], v[82:85]
	v_mfma_f32_16x16x32_bf16 v[74:77], v[166:169], v[222:225], v[74:77]
	v_mfma_f32_16x16x32_bf16 v[62:65], v[174:177], v[222:225], v[62:65]
	v_mfma_f32_16x16x32_bf16 v[126:129], v[178:181], v[194:197], v[126:129]
	v_mfma_f32_16x16x32_bf16 v[118:121], v[186:189], v[194:197], v[118:121]
	v_mfma_f32_16x16x32_bf16 v[110:113], v[178:181], v[202:205], v[110:113]
	v_mfma_f32_16x16x32_bf16 v[102:105], v[186:189], v[202:205], v[102:105]
	v_mfma_f32_16x16x32_bf16 v[94:97], v[178:181], v[210:213], v[94:97]
	v_mfma_f32_16x16x32_bf16 v[86:89], v[186:189], v[210:213], v[86:89]
	v_mfma_f32_16x16x32_bf16 v[78:81], v[178:181], v[218:221], v[78:81]
	v_mfma_f32_16x16x32_bf16 v[70:73], v[186:189], v[218:221], v[70:73]
	v_mfma_f32_16x16x32_bf16 v[126:129], v[182:185], v[198:201], v[126:129]
	v_mfma_f32_16x16x32_bf16 v[118:121], v[190:193], v[198:201], v[118:121]
	v_mfma_f32_16x16x32_bf16 v[110:113], v[182:185], v[206:209], v[110:113]
	v_mfma_f32_16x16x32_bf16 v[102:105], v[190:193], v[206:209], v[102:105]
	v_mfma_f32_16x16x32_bf16 v[94:97], v[182:185], v[214:217], v[94:97]
	v_mfma_f32_16x16x32_bf16 v[86:89], v[190:193], v[214:217], v[86:89]
	v_mfma_f32_16x16x32_bf16 v[78:81], v[182:185], v[222:225], v[78:81]
	v_mfma_f32_16x16x32_bf16 v[70:73], v[190:193], v[222:225], v[70:73]
	s_barrier
; #define PG8_STAGE(bufoff, gbase, voff) do { _Pragma("unroll") for (int _i = 0; _i < 2; ++_i) \
;         __builtin_amdgcn_global_load_lds((const unsigned*)((const char*)(gbase) + (voff)[_i]), (PG8_LAS unsigned*)(lds + (bufoff) + ldsw + _i * 8192), 16, 0, 0); } while (0)
; #define PG8_LDA(dst, b, h) do { _Pragma("unroll") for (int m = 0; m < 4; ++m) _Pragma("unroll") for (int k = 0; k < 2; ++k) dst[m][k] = *(const PG8_LAS bf16x8*)(lds + PG8_SA(b, h) + aoff + m * 2048 + k * 1024); } while (0)
; #define PG8_MMA(ai, bj, At, Bt) do { __builtin_amdgcn_s_setprio(1); _Pragma("unroll") for (int m = 0; m < 4; ++m) _Pragma("unroll") for (int n = 0; n < 2; ++n) _Pragma("unroll") for (int k = 0; k < 2; ++k) \
;         acc[ai][bj][m][n] = __builtin_amdgcn_mfma_f32_16x16x32_bf16(Bt[n][k], At[m][k], acc[ai][bj][m][n], 0, 0, 0); __builtin_amdgcn_s_setprio(0); } while (0)
; #define PG8_WAIT_V(n) asm volatile("s_waitcnt vmcnt(" #n ")" ::: "memory")
; #define PG8_WAIT_L(n) asm volatile("s_waitcnt lgkmcnt(" #n ")" ::: "memory")
; #define PG8_BAR __builtin_amdgcn_s_barrier()
; #define PG8_SCHED __builtin_amdgcn_sched_barrier(0)
; template <class Epi, class Sched, bool ALIGN_EPI = false, bool SP2 = false>
; __device__ __forceinline__ void gemm_phase(PG8_LAS unsigned char* lds, const Gemm g, const Sched& S, const Epi& E) {
;     ...
;         for (int t = 0; t < nt; t += 2) {
;     ...
;             PG8_LDA(At, 1, 1); PG8_STAGE(PG8_SB(1, 0), b3, voffB); PG8_STAGE(PG8_SB(1, 1), b3 + hstep, voffB); PG8_STAGE(PG8_SA(1, 0), a3, voffA);
;             PG8_WAIT_V(8); PG8_WAIT_L(0); PG8_BAR; PG8_MMA(1, 0, At, B0); PG8_MMA(1, 1, At, B1); PG8_BAR; PG8_SCHED;
	s_add_i32 s26, s33, s29
	s_add_i32 m0, s26, 0xffffff80
	ds_read_b128 v[194:197], v155 offset:49152
	ds_read_b128 v[198:201], v155 offset:50176
	ds_read_b128 v[202:205], v155 offset:51200
	ds_read_b128 v[206:209], v155 offset:52224
	ds_read_b128 v[210:213], v155 offset:53248
	ds_read_b128 v[214:217], v155 offset:54272
	ds_read_b128 v[218:221], v155 offset:55296
	ds_read_b128 v[222:225], v155 offset:56320
	global_load_lds_dwordx4 v[148:149], off offset:128
	s_add_i32 m0, s26, 0x1f80
	s_add_u32 s22, s22, 0x100080
	s_addc_u32 s23, s23, 0
	s_add_i32 s26, s42, s29
	global_load_lds_dwordx4 v[156:157], off offset:128
	s_mov_b32 m0, s26
	s_nop 0
	global_load_lds_dwordx4 v132, s[22:23]
	s_add_i32 m0, s26, 0x2000
	s_nop 0
	global_load_lds_dwordx4 v136, s[22:23]
	s_add_i32 m0, s46, 0xffffff80
	s_nop 0
	global_load_lds_dwordx4 v[226:227], off offset:128
	s_add_i32 m0, s47, 0xffffff80
	s_nop 0
	global_load_lds_dwordx4 v[228:229], off offset:128
	s_waitcnt vmcnt(8)
	s_waitcnt lgkmcnt(0)
	s_barrier
	s_waitcnt lgkmcnt(0)
	v_mfma_f32_16x16x32_bf16 v[58:61], v[160:163], v[194:197], v[58:61]
	v_mfma_f32_16x16x32_bf16 v[50:53], v[170:173], v[194:197], v[50:53]
	v_mfma_f32_16x16x32_bf16 v[42:45], v[160:163], v[202:205], v[42:45]
	v_mfma_f32_16x16x32_bf16 v[34:37], v[170:173], v[202:205], v[34:37]
	v_mfma_f32_16x16x32_bf16 v[26:29], v[160:163], v[210:213], v[26:29]
	v_mfma_f32_16x16x32_bf16 v[18:21], v[170:173], v[210:213], v[18:21]
	v_mfma_f32_16x16x32_bf16 v[10:13], v[160:163], v[218:221], v[10:13]
	v_mfma_f32_16x16x32_bf16 v[2:5], v[170:173], v[218:221], v[2:5]
	v_mfma_f32_16x16x32_bf16 v[58:61], v[166:169], v[198:201], v[58:61]
	v_mfma_f32_16x16x32_bf16 v[50:53], v[174:177], v[198:201], v[50:53]
	v_mfma_f32_16x16x32_bf16 v[42:45], v[166:169], v[206:209], v[42:45]
	v_mfma_f32_16x16x32_bf16 v[34:37], v[174:177], v[206:209], v[34:37]
	v_mfma_f32_16x16x32_bf16 v[26:29], v[166:169], v[214:217], v[26:29]
	v_mfma_f32_16x16x32_bf16 v[18:21], v[174:177], v[214:217], v[18:21]
	v_mfma_f32_16x16x32_bf16 v[10:13], v[166:169], v[222:225], v[10:13]
	v_mfma_f32_16x16x32_bf16 v[2:5], v[174:177], v[222:225], v[2:5]
	v_mfma_f32_16x16x32_bf16 v[66:69], v[178:181], v[194:197], v[66:69]
	v_mfma_f32_16x16x32_bf16 v[54:57], v[186:189], v[194:197], v[54:57]
	v_mfma_f32_16x16x32_bf16 v[46:49], v[178:181], v[202:205], v[46:49]
	v_mfma_f32_16x16x32_bf16 v[38:41], v[186:189], v[202:205], v[38:41]
	v_mfma_f32_16x16x32_bf16 v[30:33], v[178:181], v[210:213], v[30:33]
	v_mfma_f32_16x16x32_bf16 v[22:25], v[186:189], v[210:213], v[22:25]
	v_mfma_f32_16x16x32_bf16 v[14:17], v[178:181], v[218:221], v[14:17]
	v_mfma_f32_16x16x32_bf16 v[6:9], v[186:189], v[218:221], v[6:9]
	v_mfma_f32_16x16x32_bf16 v[66:69], v[182:185], v[198:201], v[66:69]
	v_mfma_f32_16x16x32_bf16 v[54:57], v[190:193], v[198:201], v[54:57]
	v_mfma_f32_16x16x32_bf16 v[46:49], v[182:185], v[206:209], v[46:49]
	v_mfma_f32_16x16x32_bf16 v[38:41], v[190:193], v[206:209], v[38:41]
	v_mfma_f32_16x16x32_bf16 v[30:33], v[182:185], v[214:217], v[30:33]
	v_mfma_f32_16x16x32_bf16 v[22:25], v[190:193], v[214:217], v[22:25]
	v_mfma_f32_16x16x32_bf16 v[14:17], v[182:185], v[222:225], v[14:17]
	v_mfma_f32_16x16x32_bf16 v[6:9], v[190:193], v[222:225], v[6:9]
	s_barrier
	s_add_i32 s68, s68, 2
	s_add_u32 s24, s24, 0x100
	s_addc_u32 s25, s25, 0
	s_add_u32 s66, s66, 0x100
	s_addc_u32 s67, s67, 0
	s_cmp_gt_u32 s68, 61
	s_cbranch_scc0 .LBB0_1126


; #define PG8_BAR __builtin_amdgcn_s_barrier()
; template <class Epi, class Sched, bool ALIGN_EPI = false, bool SP2 = false>
; __device__ __forceinline__ void gemm_phase(PG8_LAS unsigned char* lds, const Gemm g, const Sched& S, const Epi& E) {
;     ...
;         if constexpr (ALIGN_EPI) { if (wr == 0) PG8_BAR; }
	s_and_b64 vcc, exec, s[8:9]
	s_cbranch_vccz .LBB0_1129
	s_barrier

; #define PG8_STAGE(bufoff, gbase, voff) do { _Pragma("unroll") for (int _i = 0; _i < 2; ++_i) \
;         __builtin_amdgcn_global_load_lds((const unsigned*)((const char*)(gbase) + (voff)[_i]), (PG8_LAS unsigned*)(lds + (bufoff) + ldsw + _i * 8192), 16, 0, 0); } while (0)
; #define PG8_LDA(dst, b, h) do { _Pragma("unroll") for (int m = 0; m < 4; ++m) _Pragma("unroll") for (int k = 0; k < 2; ++k) dst[m][k] = *(const PG8_LAS bf16x8*)(lds + PG8_SA(b, h) + aoff + m * 2048 + k * 1024); } while (0)
; #define PG8_LDB(dst, b, h) do { _Pragma("unroll") for (int n = 0; n < 2; ++n) _Pragma("unroll") for (int k = 0; k < 2; ++k) dst[n][k] = *(const PG8_LAS bf16x8*)(lds + PG8_SB(b, h) + boff + n * 2048 + k * 1024); } while (0)
; #define PG8_MMA(ai, bj, At, Bt) do { __builtin_amdgcn_s_setprio(1); _Pragma("unroll") for (int m = 0; m < 4; ++m) _Pragma("unroll") for (int n = 0; n < 2; ++n) _Pragma("unroll") for (int k = 0; k < 2; ++k) \
;         acc[ai][bj][m][n] = __builtin_amdgcn_mfma_f32_16x16x32_bf16(Bt[n][k], At[m][k], acc[ai][bj][m][n], 0, 0, 0); __builtin_amdgcn_s_setprio(0); } while (0)
; #define PG8_WAIT_V(n) asm volatile("s_waitcnt vmcnt(" #n ")" ::: "memory")
; template <class Epi, class Sched, bool ALIGN_EPI = false, bool SP2 = false>
; __device__ __forceinline__ void gemm_phase(PG8_LAS unsigned char* lds, const Gemm g, const Sched& S, const Epi& E) {
;     ...
;         const char* nA = has_next ? (const char*)g.A + (size_t)nxt.pm * tstep : cA; const char* nB = has_next ? (const char*)g.Bt + (size_t)nxt.pn * tstep : cB;
;         for (int t = 0; t < nt; t += 2) {
;             const bool last = (t == nt - 2);
;             const char* a1 = cA + (size_t)(t + 1) * kstep;
;             const char* a2 = last ? nA : cA + (size_t)(t + 2) * kstep; const char* b2 = last ? nB : cB + (size_t)(t + 2) * kstep;
;             const char* a3 = a2 + kstep; const char* b3 = b2 + kstep;
;             if (last && has_next) S.a_ready(nxt);
;             if constexpr (SP2) {
;             PG8_LDB(B0, 0, 0); PG8_LDB(B1, 0, 1); PG8_SCHED; PG8_LDA(At, 0, 0); PG8_STAGE(PG8_SA(1, 1), a1 + hstep, voffA);
;             PG8_WAIT_V(8); PG8_WAIT_L(0); PG8_BAR; PG8_MMA(0, 0, At, B0); PG8_MMA(0, 1, At, B1); PG8_BAR; PG8_SCHED;
;             PG8_LDA(At, 0, 1); PG8_STAGE(PG8_SB(0, 0), b2, voffB); PG8_STAGE(PG8_SB(0, 1), b2 + hstep, voffB); PG8_STAGE(PG8_SA(0, 0), a2, voffA);
.LBB0_1244:
	s_add_u32 s18, s18, 0x2b0080
	s_addc_u32 s19, s19, 0
	s_add_u32 s62, s16, 0x100
	s_addc_u32 s63, s17, 0
	s_mov_b32 s64, -2
	v_add_u32_e32 v241, 0x10000, v165
.LBB0_1245:
	ds_read_b128 v[130:133], v241 offset:0
	ds_read_b128 v[134:137], v241 offset:1024
	ds_read_b128 v[138:141], v241 offset:2048
	ds_read_b128 v[142:145], v241 offset:3072
	ds_read_b128 v[146:149], v241 offset:16384
	ds_read_b128 v[150:153], v241 offset:17408
	ds_read_b128 v[172:175], v241 offset:18432
	ds_read_b128 v[176:179], v241 offset:19456
	s_add_u32 s16, s18, 0xffd50080
	s_addc_u32 s17, s19, -1
	s_cmpk_eq_i32 s64, 0xa8
	s_cselect_b32 s21, s5, s17
	s_cselect_b32 s20, s4, s16
	s_cselect_b32 s17, s15, s63
	s_cselect_b32 s16, s14, s62
	s_add_i32 m0, s25, 0xc000
	ds_read_b128 v[180:183], v185
	ds_read_b128 v[188:191], v185 offset:1024
	ds_read_b128 v[192:195], v185 offset:2048
	ds_read_b128 v[196:199], v185 offset:3072
	ds_read_b128 v[200:203], v185 offset:4096
	ds_read_b128 v[204:207], v185 offset:5120
	ds_read_b128 v[208:211], v185 offset:6144
	ds_read_b128 v[212:215], v185 offset:7168
	global_load_lds_dwordx4 v162, s[18:19]
	s_add_i32 m0, s25, 0xe000
	s_nop 0
	global_load_lds_dwordx4 v166, s[18:19]
	s_waitcnt vmcnt(8)
	s_waitcnt lgkmcnt(0)
	s_barrier
	s_waitcnt lgkmcnt(0)
	v_mfma_f32_16x16x32_bf16 v[114:117], v[130:133], v[180:183], v[114:117]
	v_mfma_f32_16x16x32_bf16 v[118:121], v[138:141], v[180:183], v[118:121]
	v_mfma_f32_16x16x32_bf16 v[106:109], v[130:133], v[192:195], v[106:109]
	v_mfma_f32_16x16x32_bf16 v[98:101], v[138:141], v[192:195], v[98:101]
	v_mfma_f32_16x16x32_bf16 v[90:93], v[130:133], v[200:203], v[90:93]
	v_mfma_f32_16x16x32_bf16 v[82:85], v[138:141], v[200:203], v[82:85]
	v_mfma_f32_16x16x32_bf16 v[74:77], v[130:133], v[208:211], v[74:77]
	v_mfma_f32_16x16x32_bf16 v[66:69], v[138:141], v[208:211], v[66:69]
	v_mfma_f32_16x16x32_bf16 v[114:117], v[134:137], v[188:191], v[114:117]
	v_mfma_f32_16x16x32_bf16 v[118:121], v[142:145], v[188:191], v[118:121]
	v_mfma_f32_16x16x32_bf16 v[106:109], v[134:137], v[196:199], v[106:109]
	v_mfma_f32_16x16x32_bf16 v[98:101], v[142:145], v[196:199], v[98:101]
	v_mfma_f32_16x16x32_bf16 v[90:93], v[134:137], v[204:207], v[90:93]
	v_mfma_f32_16x16x32_bf16 v[82:85], v[142:145], v[204:207], v[82:85]
	v_mfma_f32_16x16x32_bf16 v[74:77], v[134:137], v[212:215], v[74:77]
	v_mfma_f32_16x16x32_bf16 v[66:69], v[142:145], v[212:215], v[66:69]
	v_mfma_f32_16x16x32_bf16 v[122:125], v[146:149], v[180:183], v[122:125]
	v_mfma_f32_16x16x32_bf16 v[126:129], v[172:175], v[180:183], v[126:129]
	v_mfma_f32_16x16x32_bf16 v[110:113], v[146:149], v[192:195], v[110:113]
	v_mfma_f32_16x16x32_bf16 v[102:105], v[172:175], v[192:195], v[102:105]
	v_mfma_f32_16x16x32_bf16 v[94:97], v[146:149], v[200:203], v[94:97]
	v_mfma_f32_16x16x32_bf16 v[86:89], v[172:175], v[200:203], v[86:89]
	v_mfma_f32_16x16x32_bf16 v[78:81], v[146:149], v[208:211], v[78:81]
	v_mfma_f32_16x16x32_bf16 v[70:73], v[172:175], v[208:211], v[70:73]
	v_mfma_f32_16x16x32_bf16 v[122:125], v[150:153], v[188:191], v[122:125]
	v_mfma_f32_16x16x32_bf16 v[126:129], v[176:179], v[188:191], v[126:129]
	v_mfma_f32_16x16x32_bf16 v[110:113], v[150:153], v[196:199], v[110:113]
	v_mfma_f32_16x16x32_bf16 v[102:105], v[176:179], v[196:199], v[102:105]
	v_mfma_f32_16x16x32_bf16 v[94:97], v[150:153], v[204:207], v[94:97]
	v_mfma_f32_16x16x32_bf16 v[86:89], v[176:179], v[204:207], v[86:89]
	v_mfma_f32_16x16x32_bf16 v[78:81], v[150:153], v[212:215], v[78:81]
	v_mfma_f32_16x16x32_bf16 v[70:73], v[176:179], v[212:215], v[70:73]
	s_barrier
	s_add_i32 s33, s40, s24
	v_lshl_add_u64 v[216:217], s[16:17], 0, v[156:157]
	s_mov_b32 m0, s33
	ds_read_b128 v[180:183], v185 offset:16384
	ds_read_b128 v[188:191], v185 offset:17408
	ds_read_b128 v[192:195], v185 offset:18432
	ds_read_b128 v[196:199], v185 offset:19456
	ds_read_b128 v[200:203], v185 offset:20480
	ds_read_b128 v[204:207], v185 offset:21504
	ds_read_b128 v[208:211], v185 offset:22528
	ds_read_b128 v[212:215], v185 offset:23552
	global_load_lds_dwordx4 v[216:217], off
	s_add_i32 m0, s33, 0x2000
	s_add_u32 s66, s16, 0x2b0000
	v_lshl_add_u64 v[218:219], s[16:17], 0, v[160:161]
	s_addc_u32 s67, s17, 0
	s_add_i32 s33, s41, s24
	global_load_lds_dwordx4 v[218:219], off
	s_mov_b32 m0, s33
	v_lshl_add_u64 v[222:223], s[20:21], 0, v[158:159]
	global_load_lds_dwordx4 v156, s[66:67]
	s_add_i32 m0, s33, 0x2000
	s_nop 0
	global_load_lds_dwordx4 v160, s[66:67]
	v_lshl_add_u64 v[220:221], s[20:21], 0, v[154:155]
	s_mov_b32 m0, s25
	s_nop 0
	global_load_lds_dwordx4 v[220:221], off
	s_mov_b32 m0, s26
	s_nop 0
	global_load_lds_dwordx4 v[222:223], off
	s_waitcnt vmcnt(8)
	s_waitcnt lgkmcnt(0)
	s_barrier
; #define PG8_STAGE(bufoff, gbase, voff) do { _Pragma("unroll") for (int _i = 0; _i < 2; ++_i) \
;         __builtin_amdgcn_global_load_lds((const unsigned*)((const char*)(gbase) + (voff)[_i]), (PG8_LAS unsigned*)(lds + (bufoff) + ldsw + _i * 8192), 16, 0, 0); } while (0)
; #define PG8_LDA(dst, b, h) do { _Pragma("unroll") for (int m = 0; m < 4; ++m) _Pragma("unroll") for (int k = 0; k < 2; ++k) dst[m][k] = *(const PG8_LAS bf16x8*)(lds + PG8_SA(b, h) + aoff + m * 2048 + k * 1024); } while (0)
; #define PG8_LDB(dst, b, h) do { _Pragma("unroll") for (int n = 0; n < 2; ++n) _Pragma("unroll") for (int k = 0; k < 2; ++k) dst[n][k] = *(const PG8_LAS bf16x8*)(lds + PG8_SB(b, h) + boff + n * 2048 + k * 1024); } while (0)
; #define PG8_MMA(ai, bj, At, Bt) do { __builtin_amdgcn_s_setprio(1); _Pragma("unroll") for (int m = 0; m < 4; ++m) _Pragma("unroll") for (int n = 0; n < 2; ++n) _Pragma("unroll") for (int k = 0; k < 2; ++k) \
;         acc[ai][bj][m][n] = __builtin_amdgcn_mfma_f32_16x16x32_bf16(Bt[n][k], At[m][k], acc[ai][bj][m][n], 0, 0, 0); __builtin_amdgcn_s_setprio(0); } while (0)
; #define PG8_WAIT_V(n) asm volatile("s_waitcnt vmcnt(" #n ")" ::: "memory")
; #define PG8_WAIT_L(n) asm volatile("s_waitcnt lgkmcnt(" #n ")" ::: "memory")
; #define PG8_BAR __builtin_amdgcn_s_barrier()
; #define PG8_SCHED __builtin_amdgcn_sched_barrier(0)
; template <class Epi, class Sched, bool ALIGN_EPI = false, bool SP2 = false>
; __device__ __forceinline__ void gemm_phase(PG8_LAS unsigned char* lds, const Gemm g, const Sched& S, const Epi& E) {
;     ...
;             PG8_WAIT_V(8); PG8_WAIT_L(0); PG8_BAR; PG8_MMA(1, 0, At, B0); PG8_MMA(1, 1, At, B1); PG8_BAR; PG8_SCHED;
;             PG8_LDB(B0, 1, 0); PG8_LDB(B1, 1, 1); PG8_SCHED; PG8_LDA(At, 1, 0); PG8_STAGE(PG8_SA(0, 1), a2 + hstep, voffA);
;             PG8_WAIT_V(8); PG8_WAIT_L(0); PG8_BAR; PG8_MMA(0, 0, At, B0); PG8_MMA(0, 1, At, B1); PG8_BAR; PG8_SCHED;
	s_waitcnt lgkmcnt(0)
	v_mfma_f32_16x16x32_bf16 v[58:61], v[130:133], v[180:183], v[58:61]
	v_mfma_f32_16x16x32_bf16 v[54:57], v[138:141], v[180:183], v[54:57]
	v_mfma_f32_16x16x32_bf16 v[42:45], v[130:133], v[192:195], v[42:45]
	v_mfma_f32_16x16x32_bf16 v[34:37], v[138:141], v[192:195], v[34:37]
	v_mfma_f32_16x16x32_bf16 v[26:29], v[130:133], v[200:203], v[26:29]
	v_mfma_f32_16x16x32_bf16 v[18:21], v[138:141], v[200:203], v[18:21]
	v_mfma_f32_16x16x32_bf16 v[6:9], v[130:133], v[208:211], v[6:9]
	v_mfma_f32_16x16x32_bf16 v[2:5], v[138:141], v[208:211], v[2:5]
	v_mfma_f32_16x16x32_bf16 v[58:61], v[134:137], v[188:191], v[58:61]
	v_mfma_f32_16x16x32_bf16 v[54:57], v[142:145], v[188:191], v[54:57]
	v_mfma_f32_16x16x32_bf16 v[42:45], v[134:137], v[196:199], v[42:45]
	v_mfma_f32_16x16x32_bf16 v[34:37], v[142:145], v[196:199], v[34:37]
	v_mfma_f32_16x16x32_bf16 v[26:29], v[134:137], v[204:207], v[26:29]
	v_mfma_f32_16x16x32_bf16 v[18:21], v[142:145], v[204:207], v[18:21]
	v_mfma_f32_16x16x32_bf16 v[6:9], v[134:137], v[212:215], v[6:9]
	v_mfma_f32_16x16x32_bf16 v[2:5], v[142:145], v[212:215], v[2:5]
	v_mfma_f32_16x16x32_bf16 v[62:65], v[146:149], v[180:183], v[62:65]
	v_mfma_f32_16x16x32_bf16 v[50:53], v[172:175], v[180:183], v[50:53]
	v_mfma_f32_16x16x32_bf16 v[46:49], v[146:149], v[192:195], v[46:49]
	v_mfma_f32_16x16x32_bf16 v[38:41], v[172:175], v[192:195], v[38:41]
	v_mfma_f32_16x16x32_bf16 v[30:33], v[146:149], v[200:203], v[30:33]
	v_mfma_f32_16x16x32_bf16 v[22:25], v[172:175], v[200:203], v[22:25]
	v_mfma_f32_16x16x32_bf16 v[10:13], v[146:149], v[208:211], v[10:13]
	v_mfma_f32_16x16x32_bf16 v[14:17], v[172:175], v[208:211], v[14:17]
	v_mfma_f32_16x16x32_bf16 v[62:65], v[150:153], v[188:191], v[62:65]
	v_mfma_f32_16x16x32_bf16 v[50:53], v[176:179], v[188:191], v[50:53]
	v_mfma_f32_16x16x32_bf16 v[46:49], v[150:153], v[196:199], v[46:49]
	v_mfma_f32_16x16x32_bf16 v[38:41], v[176:179], v[196:199], v[38:41]
	v_mfma_f32_16x16x32_bf16 v[30:33], v[150:153], v[204:207], v[30:33]
	v_mfma_f32_16x16x32_bf16 v[22:25], v[176:179], v[204:207], v[22:25]
	v_mfma_f32_16x16x32_bf16 v[10:13], v[150:153], v[212:215], v[10:13]
	v_mfma_f32_16x16x32_bf16 v[14:17], v[176:179], v[212:215], v[14:17]
	s_barrier
	s_add_i32 s33, 0, 0x18000
	s_add_i32 s42, 0, 0x1c000
	ds_read_b128 v[130:133], v241 offset:32768
	ds_read_b128 v[134:137], v241 offset:33792
	ds_read_b128 v[138:141], v241 offset:34816
	ds_read_b128 v[142:145], v241 offset:35840
	ds_read_b128 v[146:149], v241 offset:49152
	ds_read_b128 v[150:153], v241 offset:50176
	ds_read_b128 v[172:175], v241 offset:51200
	ds_read_b128 v[176:179], v241 offset:52224
	s_add_u32 s20, s20, 0x2b0000
	s_addc_u32 s21, s21, 0
	s_mov_b32 m0, s27
	ds_read_b128 v[180:183], v185 offset:32768
	ds_read_b128 v[188:191], v185 offset:33792
	ds_read_b128 v[192:195], v185 offset:34816
	ds_read_b128 v[196:199], v185 offset:35840
	ds_read_b128 v[200:203], v185 offset:36864
	ds_read_b128 v[204:207], v185 offset:37888
	ds_read_b128 v[208:211], v185 offset:38912
	ds_read_b128 v[212:215], v185 offset:39936
	global_load_lds_dwordx4 v154, s[20:21]
	s_mov_b32 m0, s28
	s_nop 0
	global_load_lds_dwordx4 v158, s[20:21]
	s_waitcnt vmcnt(8)
	s_waitcnt lgkmcnt(0)
	s_barrier
	s_waitcnt lgkmcnt(0)
	v_mfma_f32_16x16x32_bf16 v[114:117], v[130:133], v[180:183], v[114:117]
	v_mfma_f32_16x16x32_bf16 v[118:121], v[138:141], v[180:183], v[118:121]
	v_mfma_f32_16x16x32_bf16 v[106:109], v[130:133], v[192:195], v[106:109]
	v_mfma_f32_16x16x32_bf16 v[98:101], v[138:141], v[192:195], v[98:101]
	v_mfma_f32_16x16x32_bf16 v[90:93], v[130:133], v[200:203], v[90:93]
	v_mfma_f32_16x16x32_bf16 v[82:85], v[138:141], v[200:203], v[82:85]
	v_mfma_f32_16x16x32_bf16 v[74:77], v[130:133], v[208:211], v[74:77]
	v_mfma_f32_16x16x32_bf16 v[66:69], v[138:141], v[208:211], v[66:69]
	v_mfma_f32_16x16x32_bf16 v[114:117], v[134:137], v[188:191], v[114:117]
	v_mfma_f32_16x16x32_bf16 v[118:121], v[142:145], v[188:191], v[118:121]
	v_mfma_f32_16x16x32_bf16 v[106:109], v[134:137], v[196:199], v[106:109]
	v_mfma_f32_16x16x32_bf16 v[98:101], v[142:145], v[196:199], v[98:101]
	v_mfma_f32_16x16x32_bf16 v[90:93], v[134:137], v[204:207], v[90:93]
	v_mfma_f32_16x16x32_bf16 v[82:85], v[142:145], v[204:207], v[82:85]
	v_mfma_f32_16x16x32_bf16 v[74:77], v[134:137], v[212:215], v[74:77]
	v_mfma_f32_16x16x32_bf16 v[66:69], v[142:145], v[212:215], v[66:69]
	v_mfma_f32_16x16x32_bf16 v[122:125], v[146:149], v[180:183], v[122:125]
	v_mfma_f32_16x16x32_bf16 v[126:129], v[172:175], v[180:183], v[126:129]
	v_mfma_f32_16x16x32_bf16 v[110:113], v[146:149], v[192:195], v[110:113]
	v_mfma_f32_16x16x32_bf16 v[102:105], v[172:175], v[192:195], v[102:105]
	v_mfma_f32_16x16x32_bf16 v[94:97], v[146:149], v[200:203], v[94:97]
	v_mfma_f32_16x16x32_bf16 v[86:89], v[172:175], v[200:203], v[86:89]
	v_mfma_f32_16x16x32_bf16 v[78:81], v[146:149], v[208:211], v[78:81]
	v_mfma_f32_16x16x32_bf16 v[70:73], v[172:175], v[208:211], v[70:73]
	v_mfma_f32_16x16x32_bf16 v[122:125], v[150:153], v[188:191], v[122:125]
	v_mfma_f32_16x16x32_bf16 v[126:129], v[176:179], v[188:191], v[126:129]
	v_mfma_f32_16x16x32_bf16 v[110:113], v[150:153], v[196:199], v[110:113]
	v_mfma_f32_16x16x32_bf16 v[102:105], v[176:179], v[196:199], v[102:105]
	v_mfma_f32_16x16x32_bf16 v[94:97], v[150:153], v[204:207], v[94:97]
	v_mfma_f32_16x16x32_bf16 v[86:89], v[176:179], v[204:207], v[86:89]
	v_mfma_f32_16x16x32_bf16 v[78:81], v[150:153], v[212:215], v[78:81]
	v_mfma_f32_16x16x32_bf16 v[70:73], v[176:179], v[212:215], v[70:73]
	s_barrier
; #define PG8_STAGE(bufoff, gbase, voff) do { _Pragma("unroll") for (int _i = 0; _i < 2; ++_i) \
;         __builtin_amdgcn_global_load_lds((const unsigned*)((const char*)(gbase) + (voff)[_i]), (PG8_LAS unsigned*)(lds + (bufoff) + ldsw + _i * 8192), 16, 0, 0); } while (0)
; #define PG8_LDA(dst, b, h) do { _Pragma("unroll") for (int m = 0; m < 4; ++m) _Pragma("unroll") for (int k = 0; k < 2; ++k) dst[m][k] = *(const PG8_LAS bf16x8*)(lds + PG8_SA(b, h) + aoff + m * 2048 + k * 1024); } while (0)
; #define PG8_MMA(ai, bj, At, Bt) do { __builtin_amdgcn_s_setprio(1); _Pragma("unroll") for (int m = 0; m < 4; ++m) _Pragma("unroll") for (int n = 0; n < 2; ++n) _Pragma("unroll") for (int k = 0; k < 2; ++k) \
;         acc[ai][bj][m][n] = __builtin_amdgcn_mfma_f32_16x16x32_bf16(Bt[n][k], At[m][k], acc[ai][bj][m][n], 0, 0, 0); __builtin_amdgcn_s_setprio(0); } while (0)
; #define PG8_WAIT_V(n) asm volatile("s_waitcnt vmcnt(" #n ")" ::: "memory")
; #define PG8_WAIT_L(n) asm volatile("s_waitcnt lgkmcnt(" #n ")" ::: "memory")
; #define PG8_BAR __builtin_amdgcn_s_barrier()
; #define PG8_SCHED __builtin_amdgcn_sched_barrier(0)
; template <class Epi, class Sched, bool ALIGN_EPI = false, bool SP2 = false>
; __device__ __forceinline__ void gemm_phase(PG8_LAS unsigned char* lds, const Gemm g, const Sched& S, const Epi& E) {
;     ...
;         for (int t = 0; t < nt; t += 2) {
;     ...
;             PG8_LDA(At, 1, 1); PG8_STAGE(PG8_SB(1, 0), b3, voffB); PG8_STAGE(PG8_SB(1, 1), b3 + hstep, voffB); PG8_STAGE(PG8_SA(1, 0), a3, voffA);
;             PG8_WAIT_V(8); PG8_WAIT_L(0); PG8_BAR; PG8_MMA(1, 0, At, B0); PG8_MMA(1, 1, At, B1); PG8_BAR; PG8_SCHED;
	s_add_i32 s20, s33, s24
	s_add_i32 m0, s20, 0xffffff80
	ds_read_b128 v[180:183], v185 offset:49152
	ds_read_b128 v[188:191], v185 offset:50176
	ds_read_b128 v[192:195], v185 offset:51200
	ds_read_b128 v[196:199], v185 offset:52224
	ds_read_b128 v[200:203], v185 offset:53248
	ds_read_b128 v[204:207], v185 offset:54272
	ds_read_b128 v[208:211], v185 offset:55296
	ds_read_b128 v[212:215], v185 offset:56320
	global_load_lds_dwordx4 v[216:217], off offset:128
	s_add_i32 m0, s20, 0x1f80
	s_add_u32 s16, s16, 0x2b0080
	s_addc_u32 s17, s17, 0
	s_add_i32 s20, s42, s24
	global_load_lds_dwordx4 v[218:219], off offset:128
	s_mov_b32 m0, s20
	s_nop 0
	global_load_lds_dwordx4 v156, s[16:17]
	s_add_i32 m0, s20, 0x2000
	s_nop 0
	global_load_lds_dwordx4 v160, s[16:17]
	s_add_i32 m0, s34, 0xffffff80
	s_nop 0
	global_load_lds_dwordx4 v[220:221], off offset:128
	s_add_i32 m0, s35, 0xffffff80
	s_nop 0
	global_load_lds_dwordx4 v[222:223], off offset:128
	s_waitcnt vmcnt(8)
	s_waitcnt lgkmcnt(0)
	s_barrier
	s_waitcnt lgkmcnt(0)
	v_mfma_f32_16x16x32_bf16 v[58:61], v[130:133], v[180:183], v[58:61]
	v_mfma_f32_16x16x32_bf16 v[54:57], v[138:141], v[180:183], v[54:57]
	v_mfma_f32_16x16x32_bf16 v[42:45], v[130:133], v[192:195], v[42:45]
	v_mfma_f32_16x16x32_bf16 v[34:37], v[138:141], v[192:195], v[34:37]
	v_mfma_f32_16x16x32_bf16 v[26:29], v[130:133], v[200:203], v[26:29]
	v_mfma_f32_16x16x32_bf16 v[18:21], v[138:141], v[200:203], v[18:21]
	v_mfma_f32_16x16x32_bf16 v[6:9], v[130:133], v[208:211], v[6:9]
	v_mfma_f32_16x16x32_bf16 v[2:5], v[138:141], v[208:211], v[2:5]
	v_mfma_f32_16x16x32_bf16 v[58:61], v[134:137], v[188:191], v[58:61]
	v_mfma_f32_16x16x32_bf16 v[54:57], v[142:145], v[188:191], v[54:57]
	v_mfma_f32_16x16x32_bf16 v[42:45], v[134:137], v[196:199], v[42:45]
	v_mfma_f32_16x16x32_bf16 v[34:37], v[142:145], v[196:199], v[34:37]
	v_mfma_f32_16x16x32_bf16 v[26:29], v[134:137], v[204:207], v[26:29]
	v_mfma_f32_16x16x32_bf16 v[18:21], v[142:145], v[204:207], v[18:21]
	v_mfma_f32_16x16x32_bf16 v[6:9], v[134:137], v[212:215], v[6:9]
	v_mfma_f32_16x16x32_bf16 v[2:5], v[142:145], v[212:215], v[2:5]
	v_mfma_f32_16x16x32_bf16 v[62:65], v[146:149], v[180:183], v[62:65]
	v_mfma_f32_16x16x32_bf16 v[50:53], v[172:175], v[180:183], v[50:53]
	v_mfma_f32_16x16x32_bf16 v[46:49], v[146:149], v[192:195], v[46:49]
	v_mfma_f32_16x16x32_bf16 v[38:41], v[172:175], v[192:195], v[38:41]
	v_mfma_f32_16x16x32_bf16 v[30:33], v[146:149], v[200:203], v[30:33]
	v_mfma_f32_16x16x32_bf16 v[22:25], v[172:175], v[200:203], v[22:25]
	v_mfma_f32_16x16x32_bf16 v[10:13], v[146:149], v[208:211], v[10:13]
	v_mfma_f32_16x16x32_bf16 v[14:17], v[172:175], v[208:211], v[14:17]
	v_mfma_f32_16x16x32_bf16 v[62:65], v[150:153], v[188:191], v[62:65]
	v_mfma_f32_16x16x32_bf16 v[50:53], v[176:179], v[188:191], v[50:53]
	v_mfma_f32_16x16x32_bf16 v[46:49], v[150:153], v[196:199], v[46:49]
	v_mfma_f32_16x16x32_bf16 v[38:41], v[176:179], v[196:199], v[38:41]
	v_mfma_f32_16x16x32_bf16 v[30:33], v[150:153], v[204:207], v[30:33]
	v_mfma_f32_16x16x32_bf16 v[22:25], v[176:179], v[204:207], v[22:25]
	v_mfma_f32_16x16x32_bf16 v[10:13], v[150:153], v[212:215], v[10:13]
	v_mfma_f32_16x16x32_bf16 v[14:17], v[176:179], v[212:215], v[14:17]
	s_barrier
	s_add_i32 s64, s64, 2
	s_add_u32 s18, s18, 0x100
	s_addc_u32 s19, s19, 0
	s_add_u32 s62, s62, 0x100
	s_addc_u32 s63, s63, 0
	s_cmpk_gt_u32 s64, 0xa9
	s_cbranch_scc0 .LBB0_1245


; #define PG8_BAR __builtin_amdgcn_s_barrier()
; template <class Epi, class Sched, bool ALIGN_EPI = false, bool SP2 = false>
; __device__ __forceinline__ void gemm_phase(PG8_LAS unsigned char* lds, const Gemm g, const Sched& S, const Epi& E) {
;     ...
;         if constexpr (ALIGN_EPI) { if (wr == 0) PG8_BAR; }
	s_and_b64 vcc, exec, s[12:13]
	s_cbranch_vccz .LBB0_1248
	s_barrier

; #define PG8_STAGE(bufoff, gbase, voff) do { _Pragma("unroll") for (int _i = 0; _i < 2; ++_i) \
;         __builtin_amdgcn_global_load_lds((const unsigned*)((const char*)(gbase) + (voff)[_i]), (PG8_LAS unsigned*)(lds + (bufoff) + ldsw + _i * 8192), 16, 0, 0); } while (0)
; #define PG8_LDA(dst, b, h) do { _Pragma("unroll") for (int m = 0; m < 4; ++m) _Pragma("unroll") for (int k = 0; k < 2; ++k) dst[m][k] = *(const PG8_LAS bf16x8*)(lds + PG8_SA(b, h) + aoff + m * 2048 + k * 1024); } while (0)
; #define PG8_LDB(dst, b, h) do { _Pragma("unroll") for (int n = 0; n < 2; ++n) _Pragma("unroll") for (int k = 0; k < 2; ++k) dst[n][k] = *(const PG8_LAS bf16x8*)(lds + PG8_SB(b, h) + boff + n * 2048 + k * 1024); } while (0)
; #define PG8_MMA(ai, bj, At, Bt) do { __builtin_amdgcn_s_setprio(1); _Pragma("unroll") for (int m = 0; m < 4; ++m) _Pragma("unroll") for (int n = 0; n < 2; ++n) _Pragma("unroll") for (int k = 0; k < 2; ++k) \
;         acc[ai][bj][m][n] = __builtin_amdgcn_mfma_f32_16x16x32_bf16(Bt[n][k], At[m][k], acc[ai][bj][m][n], 0, 0, 0); __builtin_amdgcn_s_setprio(0); } while (0)
; #define PG8_WAIT_V(n) asm volatile("s_waitcnt vmcnt(" #n ")" ::: "memory")
; template <class Epi, class Sched, bool ALIGN_EPI = false, bool SP2 = false>
; __device__ __forceinline__ void gemm_phase(PG8_LAS unsigned char* lds, const Gemm g, const Sched& S, const Epi& E) {
;     ...
;         const char* nA = has_next ? (const char*)g.A + (size_t)nxt.pm * tstep : cA; const char* nB = has_next ? (const char*)g.Bt + (size_t)nxt.pn * tstep : cB;
;         for (int t = 0; t < nt; t += 2) {
;             const bool last = (t == nt - 2);
;             const char* a1 = cA + (size_t)(t + 1) * kstep;
;             const char* a2 = last ? nA : cA + (size_t)(t + 2) * kstep; const char* b2 = last ? nB : cB + (size_t)(t + 2) * kstep;
;             const char* a3 = a2 + kstep; const char* b3 = b2 + kstep;
;             if (last && has_next) S.a_ready(nxt);
;             if constexpr (SP2) {
;             PG8_LDB(B0, 0, 0); PG8_LDB(B1, 0, 1); PG8_SCHED; PG8_LDA(At, 0, 0); PG8_STAGE(PG8_SA(1, 1), a1 + hstep, voffA);
;             PG8_WAIT_V(8); PG8_WAIT_L(0); PG8_BAR; PG8_MMA(0, 0, At, B0); PG8_MMA(0, 1, At, B1); PG8_BAR; PG8_SCHED;
;             PG8_LDA(At, 0, 1); PG8_STAGE(PG8_SB(0, 0), b2, voffB); PG8_STAGE(PG8_SB(0, 1), b2 + hstep, voffB); PG8_STAGE(PG8_SA(0, 0), a2, voffA);
.LBB0_1331:
	s_ashr_i32 s13, s12, 31
	s_lshl_b64 s[14:15], s[12:13], 21
	s_add_u32 s14, s96, s14
	s_addc_u32 s15, s97, s15
	s_and_b64 s[16:17], s[0:1], exec
	s_cselect_b32 s13, s15, s23
	s_cselect_b32 s63, s14, s22
	s_ashr_i32 s11, s10, 31
	s_lshl_b64 s[16:17], s[10:11], 21
	s_add_u32 s16, s26, s16
	s_addc_u32 s17, s27, s17
	s_and_b64 s[24:25], s[0:1], exec
	s_cselect_b32 s11, s17, s21
	s_cselect_b32 s64, s16, s20
	s_add_u32 s22, s22, 0x100080
	s_addc_u32 s23, s23, 0
	s_add_u32 s65, s20, 0x100
	s_addc_u32 s66, s21, 0
	s_mov_b32 s67, -2
	v_add_u32_e32 v241, 0x10000, v147
.LBB0_1332:
	ds_read_b128 v[148:151], v241 offset:0
	ds_read_b128 v[156:159], v241 offset:1024
	ds_read_b128 v[166:169], v241 offset:2048
	ds_read_b128 v[170:173], v241 offset:3072
	ds_read_b128 v[174:177], v241 offset:16384
	ds_read_b128 v[178:181], v241 offset:17408
	ds_read_b128 v[182:185], v241 offset:18432
	ds_read_b128 v[186:189], v241 offset:19456
	s_add_u32 s20, s22, 0xfff00080
	s_addc_u32 s21, s23, -1
	s_cmp_eq_u32 s67, 60
	s_cselect_b32 s25, s13, s21
	s_cselect_b32 s24, s63, s20
	s_cselect_b32 s21, s11, s66
	s_cselect_b32 s20, s64, s65
	s_add_i32 m0, s19, 0xc000
	ds_read_b128 v[190:193], v155
	ds_read_b128 v[194:197], v155 offset:1024
	ds_read_b128 v[198:201], v155 offset:2048
	ds_read_b128 v[202:205], v155 offset:3072
	ds_read_b128 v[206:209], v155 offset:4096
	ds_read_b128 v[210:213], v155 offset:5120
	ds_read_b128 v[214:217], v155 offset:6144
	ds_read_b128 v[218:221], v155 offset:7168
	global_load_lds_dwordx4 v138, s[22:23]
	s_add_i32 m0, s19, 0xe000
	s_nop 0
	global_load_lds_dwordx4 v140, s[22:23]
	s_waitcnt vmcnt(8)
	s_waitcnt lgkmcnt(0)
	s_barrier
	s_waitcnt lgkmcnt(0)
	v_mfma_f32_16x16x32_bf16 v[118:121], v[148:151], v[190:193], v[118:121]
	v_mfma_f32_16x16x32_bf16 v[114:117], v[166:169], v[190:193], v[114:117]
	v_mfma_f32_16x16x32_bf16 v[102:105], v[148:151], v[198:201], v[102:105]
	v_mfma_f32_16x16x32_bf16 v[98:101], v[166:169], v[198:201], v[98:101]
	v_mfma_f32_16x16x32_bf16 v[86:89], v[148:151], v[206:209], v[86:89]
	v_mfma_f32_16x16x32_bf16 v[82:85], v[166:169], v[206:209], v[82:85]
	v_mfma_f32_16x16x32_bf16 v[70:73], v[148:151], v[214:217], v[70:73]
	v_mfma_f32_16x16x32_bf16 v[66:69], v[166:169], v[214:217], v[66:69]
	v_mfma_f32_16x16x32_bf16 v[118:121], v[156:159], v[194:197], v[118:121]
	v_mfma_f32_16x16x32_bf16 v[114:117], v[170:173], v[194:197], v[114:117]
	v_mfma_f32_16x16x32_bf16 v[102:105], v[156:159], v[202:205], v[102:105]
	v_mfma_f32_16x16x32_bf16 v[98:101], v[170:173], v[202:205], v[98:101]
	v_mfma_f32_16x16x32_bf16 v[86:89], v[156:159], v[210:213], v[86:89]
	v_mfma_f32_16x16x32_bf16 v[82:85], v[170:173], v[210:213], v[82:85]
	v_mfma_f32_16x16x32_bf16 v[70:73], v[156:159], v[218:221], v[70:73]
	v_mfma_f32_16x16x32_bf16 v[66:69], v[170:173], v[218:221], v[66:69]
	v_mfma_f32_16x16x32_bf16 v[126:129], v[174:177], v[190:193], v[126:129]
	v_mfma_f32_16x16x32_bf16 v[122:125], v[182:185], v[190:193], v[122:125]
	v_mfma_f32_16x16x32_bf16 v[110:113], v[174:177], v[198:201], v[110:113]
	v_mfma_f32_16x16x32_bf16 v[106:109], v[182:185], v[198:201], v[106:109]
	v_mfma_f32_16x16x32_bf16 v[94:97], v[174:177], v[206:209], v[94:97]
	v_mfma_f32_16x16x32_bf16 v[90:93], v[182:185], v[206:209], v[90:93]
	v_mfma_f32_16x16x32_bf16 v[78:81], v[174:177], v[214:217], v[78:81]
	v_mfma_f32_16x16x32_bf16 v[74:77], v[182:185], v[214:217], v[74:77]
	v_mfma_f32_16x16x32_bf16 v[126:129], v[178:181], v[194:197], v[126:129]
	v_mfma_f32_16x16x32_bf16 v[122:125], v[186:189], v[194:197], v[122:125]
	v_mfma_f32_16x16x32_bf16 v[110:113], v[178:181], v[202:205], v[110:113]
	v_mfma_f32_16x16x32_bf16 v[106:109], v[186:189], v[202:205], v[106:109]
	v_mfma_f32_16x16x32_bf16 v[94:97], v[178:181], v[210:213], v[94:97]
	v_mfma_f32_16x16x32_bf16 v[90:93], v[186:189], v[210:213], v[90:93]
	v_mfma_f32_16x16x32_bf16 v[78:81], v[178:181], v[218:221], v[78:81]
	v_mfma_f32_16x16x32_bf16 v[74:77], v[186:189], v[218:221], v[74:77]
	s_barrier
	s_add_i32 s33, s47, s28
	v_lshl_add_u64 v[162:163], s[20:21], 0, v[132:133]
	s_mov_b32 m0, s33
	ds_read_b128 v[190:193], v155 offset:16384
	ds_read_b128 v[194:197], v155 offset:17408
	ds_read_b128 v[198:201], v155 offset:18432
	ds_read_b128 v[202:205], v155 offset:19456
	ds_read_b128 v[206:209], v155 offset:20480
	ds_read_b128 v[210:213], v155 offset:21504
	ds_read_b128 v[214:217], v155 offset:22528
	ds_read_b128 v[218:221], v155 offset:23552
	global_load_lds_dwordx4 v[162:163], off
	s_add_i32 m0, s33, 0x2000
	s_add_u32 s68, s20, 0x100000
	v_lshl_add_u64 v[222:223], s[20:21], 0, v[136:137]
	s_addc_u32 s69, s21, 0
	s_add_i32 s33, s52, s28
	global_load_lds_dwordx4 v[222:223], off
	s_mov_b32 m0, s33
	v_lshl_add_u64 v[226:227], s[24:25], 0, v[134:135]
	global_load_lds_dwordx4 v132, s[68:69]
	s_add_i32 m0, s33, 0x2000
	s_nop 0
	global_load_lds_dwordx4 v136, s[68:69]
	v_lshl_add_u64 v[224:225], s[24:25], 0, v[130:131]
	s_mov_b32 m0, s19
	s_nop 0
	global_load_lds_dwordx4 v[224:225], off
	s_mov_b32 m0, s35
	s_nop 0
	global_load_lds_dwordx4 v[226:227], off
	s_waitcnt vmcnt(8)
	s_waitcnt lgkmcnt(0)
	s_barrier
; #define PG8_STAGE(bufoff, gbase, voff) do { _Pragma("unroll") for (int _i = 0; _i < 2; ++_i) \
;         __builtin_amdgcn_global_load_lds((const unsigned*)((const char*)(gbase) + (voff)[_i]), (PG8_LAS unsigned*)(lds + (bufoff) + ldsw + _i * 8192), 16, 0, 0); } while (0)
; #define PG8_LDA(dst, b, h) do { _Pragma("unroll") for (int m = 0; m < 4; ++m) _Pragma("unroll") for (int k = 0; k < 2; ++k) dst[m][k] = *(const PG8_LAS bf16x8*)(lds + PG8_SA(b, h) + aoff + m * 2048 + k * 1024); } while (0)
; #define PG8_LDB(dst, b, h) do { _Pragma("unroll") for (int n = 0; n < 2; ++n) _Pragma("unroll") for (int k = 0; k < 2; ++k) dst[n][k] = *(const PG8_LAS bf16x8*)(lds + PG8_SB(b, h) + boff + n * 2048 + k * 1024); } while (0)
; #define PG8_MMA(ai, bj, At, Bt) do { __builtin_amdgcn_s_setprio(1); _Pragma("unroll") for (int m = 0; m < 4; ++m) _Pragma("unroll") for (int n = 0; n < 2; ++n) _Pragma("unroll") for (int k = 0; k < 2; ++k) \
;         acc[ai][bj][m][n] = __builtin_amdgcn_mfma_f32_16x16x32_bf16(Bt[n][k], At[m][k], acc[ai][bj][m][n], 0, 0, 0); __builtin_amdgcn_s_setprio(0); } while (0)
; #define PG8_WAIT_V(n) asm volatile("s_waitcnt vmcnt(" #n ")" ::: "memory")
; #define PG8_WAIT_L(n) asm volatile("s_waitcnt lgkmcnt(" #n ")" ::: "memory")
; #define PG8_BAR __builtin_amdgcn_s_barrier()
; #define PG8_SCHED __builtin_amdgcn_sched_barrier(0)
; template <class Epi, class Sched, bool ALIGN_EPI = false, bool SP2 = false>
; __device__ __forceinline__ void gemm_phase(PG8_LAS unsigned char* lds, const Gemm g, const Sched& S, const Epi& E) {
;     ...
;             PG8_WAIT_V(8); PG8_WAIT_L(0); PG8_BAR; PG8_MMA(1, 0, At, B0); PG8_MMA(1, 1, At, B1); PG8_BAR; PG8_SCHED;
;             PG8_LDB(B0, 1, 0); PG8_LDB(B1, 1, 1); PG8_SCHED; PG8_LDA(At, 1, 0); PG8_STAGE(PG8_SA(0, 1), a2 + hstep, voffA);
;             PG8_WAIT_V(8); PG8_WAIT_L(0); PG8_BAR; PG8_MMA(0, 0, At, B0); PG8_MMA(0, 1, At, B1); PG8_BAR; PG8_SCHED;
	s_waitcnt lgkmcnt(0)
	v_mfma_f32_16x16x32_bf16 v[54:57], v[148:151], v[190:193], v[54:57]
	v_mfma_f32_16x16x32_bf16 v[50:53], v[166:169], v[190:193], v[50:53]
	v_mfma_f32_16x16x32_bf16 v[38:41], v[148:151], v[198:201], v[38:41]
	v_mfma_f32_16x16x32_bf16 v[34:37], v[166:169], v[198:201], v[34:37]
	v_mfma_f32_16x16x32_bf16 v[22:25], v[148:151], v[206:209], v[22:25]
	v_mfma_f32_16x16x32_bf16 v[18:21], v[166:169], v[206:209], v[18:21]
	v_mfma_f32_16x16x32_bf16 v[6:9], v[148:151], v[214:217], v[6:9]
	v_mfma_f32_16x16x32_bf16 v[2:5], v[166:169], v[214:217], v[2:5]
	v_mfma_f32_16x16x32_bf16 v[54:57], v[156:159], v[194:197], v[54:57]
	v_mfma_f32_16x16x32_bf16 v[50:53], v[170:173], v[194:197], v[50:53]
	v_mfma_f32_16x16x32_bf16 v[38:41], v[156:159], v[202:205], v[38:41]
	v_mfma_f32_16x16x32_bf16 v[34:37], v[170:173], v[202:205], v[34:37]
	v_mfma_f32_16x16x32_bf16 v[22:25], v[156:159], v[210:213], v[22:25]
	v_mfma_f32_16x16x32_bf16 v[18:21], v[170:173], v[210:213], v[18:21]
	v_mfma_f32_16x16x32_bf16 v[6:9], v[156:159], v[218:221], v[6:9]
	v_mfma_f32_16x16x32_bf16 v[2:5], v[170:173], v[218:221], v[2:5]
	v_mfma_f32_16x16x32_bf16 v[62:65], v[174:177], v[190:193], v[62:65]
	v_mfma_f32_16x16x32_bf16 v[58:61], v[182:185], v[190:193], v[58:61]
	v_mfma_f32_16x16x32_bf16 v[46:49], v[174:177], v[198:201], v[46:49]
	v_mfma_f32_16x16x32_bf16 v[42:45], v[182:185], v[198:201], v[42:45]
	v_mfma_f32_16x16x32_bf16 v[30:33], v[174:177], v[206:209], v[30:33]
	v_mfma_f32_16x16x32_bf16 v[26:29], v[182:185], v[206:209], v[26:29]
	v_mfma_f32_16x16x32_bf16 v[10:13], v[174:177], v[214:217], v[10:13]
	v_mfma_f32_16x16x32_bf16 v[14:17], v[182:185], v[214:217], v[14:17]
	v_mfma_f32_16x16x32_bf16 v[62:65], v[178:181], v[194:197], v[62:65]
	v_mfma_f32_16x16x32_bf16 v[58:61], v[186:189], v[194:197], v[58:61]
	v_mfma_f32_16x16x32_bf16 v[46:49], v[178:181], v[202:205], v[46:49]
	v_mfma_f32_16x16x32_bf16 v[42:45], v[186:189], v[202:205], v[42:45]
	v_mfma_f32_16x16x32_bf16 v[30:33], v[178:181], v[210:213], v[30:33]
	v_mfma_f32_16x16x32_bf16 v[26:29], v[186:189], v[210:213], v[26:29]
	v_mfma_f32_16x16x32_bf16 v[10:13], v[178:181], v[218:221], v[10:13]
	v_mfma_f32_16x16x32_bf16 v[14:17], v[186:189], v[218:221], v[14:17]
	s_barrier
	s_add_i32 s33, 0, 0x18000
	s_add_i32 s42, 0, 0x1c000
	ds_read_b128 v[148:151], v241 offset:32768
	ds_read_b128 v[156:159], v241 offset:33792
	ds_read_b128 v[166:169], v241 offset:34816
	ds_read_b128 v[170:173], v241 offset:35840
	ds_read_b128 v[174:177], v241 offset:49152
	ds_read_b128 v[178:181], v241 offset:50176
	ds_read_b128 v[182:185], v241 offset:51200
	ds_read_b128 v[186:189], v241 offset:52224
	s_add_u32 s24, s24, 0x100000
	s_addc_u32 s25, s25, 0
	s_mov_b32 m0, s36
	ds_read_b128 v[190:193], v155 offset:32768
	ds_read_b128 v[194:197], v155 offset:33792
	ds_read_b128 v[198:201], v155 offset:34816
	ds_read_b128 v[202:205], v155 offset:35840
	ds_read_b128 v[206:209], v155 offset:36864
	ds_read_b128 v[210:213], v155 offset:37888
	ds_read_b128 v[214:217], v155 offset:38912
	ds_read_b128 v[218:221], v155 offset:39936
	global_load_lds_dwordx4 v130, s[24:25]
	s_mov_b32 m0, s37
	s_nop 0
	global_load_lds_dwordx4 v134, s[24:25]
	s_waitcnt vmcnt(8)
	s_waitcnt lgkmcnt(0)
	s_barrier
	s_waitcnt lgkmcnt(0)
	v_mfma_f32_16x16x32_bf16 v[118:121], v[148:151], v[190:193], v[118:121]
	v_mfma_f32_16x16x32_bf16 v[114:117], v[166:169], v[190:193], v[114:117]
	v_mfma_f32_16x16x32_bf16 v[102:105], v[148:151], v[198:201], v[102:105]
	v_mfma_f32_16x16x32_bf16 v[98:101], v[166:169], v[198:201], v[98:101]
	v_mfma_f32_16x16x32_bf16 v[86:89], v[148:151], v[206:209], v[86:89]
	v_mfma_f32_16x16x32_bf16 v[82:85], v[166:169], v[206:209], v[82:85]
	v_mfma_f32_16x16x32_bf16 v[70:73], v[148:151], v[214:217], v[70:73]
	v_mfma_f32_16x16x32_bf16 v[66:69], v[166:169], v[214:217], v[66:69]
	v_mfma_f32_16x16x32_bf16 v[118:121], v[156:159], v[194:197], v[118:121]
	v_mfma_f32_16x16x32_bf16 v[114:117], v[170:173], v[194:197], v[114:117]
	v_mfma_f32_16x16x32_bf16 v[102:105], v[156:159], v[202:205], v[102:105]
	v_mfma_f32_16x16x32_bf16 v[98:101], v[170:173], v[202:205], v[98:101]
	v_mfma_f32_16x16x32_bf16 v[86:89], v[156:159], v[210:213], v[86:89]
	v_mfma_f32_16x16x32_bf16 v[82:85], v[170:173], v[210:213], v[82:85]
	v_mfma_f32_16x16x32_bf16 v[70:73], v[156:159], v[218:221], v[70:73]
	v_mfma_f32_16x16x32_bf16 v[66:69], v[170:173], v[218:221], v[66:69]
	v_mfma_f32_16x16x32_bf16 v[126:129], v[174:177], v[190:193], v[126:129]
	v_mfma_f32_16x16x32_bf16 v[122:125], v[182:185], v[190:193], v[122:125]
	v_mfma_f32_16x16x32_bf16 v[110:113], v[174:177], v[198:201], v[110:113]
	v_mfma_f32_16x16x32_bf16 v[106:109], v[182:185], v[198:201], v[106:109]
	v_mfma_f32_16x16x32_bf16 v[94:97], v[174:177], v[206:209], v[94:97]
	v_mfma_f32_16x16x32_bf16 v[90:93], v[182:185], v[206:209], v[90:93]
	v_mfma_f32_16x16x32_bf16 v[78:81], v[174:177], v[214:217], v[78:81]
	v_mfma_f32_16x16x32_bf16 v[74:77], v[182:185], v[214:217], v[74:77]
	v_mfma_f32_16x16x32_bf16 v[126:129], v[178:181], v[194:197], v[126:129]
	v_mfma_f32_16x16x32_bf16 v[122:125], v[186:189], v[194:197], v[122:125]
	v_mfma_f32_16x16x32_bf16 v[110:113], v[178:181], v[202:205], v[110:113]
	v_mfma_f32_16x16x32_bf16 v[106:109], v[186:189], v[202:205], v[106:109]
	v_mfma_f32_16x16x32_bf16 v[94:97], v[178:181], v[210:213], v[94:97]
	v_mfma_f32_16x16x32_bf16 v[90:93], v[186:189], v[210:213], v[90:93]
	v_mfma_f32_16x16x32_bf16 v[78:81], v[178:181], v[218:221], v[78:81]
	v_mfma_f32_16x16x32_bf16 v[74:77], v[186:189], v[218:221], v[74:77]
	s_barrier
; #define PG8_STAGE(bufoff, gbase, voff) do { _Pragma("unroll") for (int _i = 0; _i < 2; ++_i) \
;         __builtin_amdgcn_global_load_lds((const unsigned*)((const char*)(gbase) + (voff)[_i]), (PG8_LAS unsigned*)(lds + (bufoff) + ldsw + _i * 8192), 16, 0, 0); } while (0)
; #define PG8_LDA(dst, b, h) do { _Pragma("unroll") for (int m = 0; m < 4; ++m) _Pragma("unroll") for (int k = 0; k < 2; ++k) dst[m][k] = *(const PG8_LAS bf16x8*)(lds + PG8_SA(b, h) + aoff + m * 2048 + k * 1024); } while (0)
; #define PG8_MMA(ai, bj, At, Bt) do { __builtin_amdgcn_s_setprio(1); _Pragma("unroll") for (int m = 0; m < 4; ++m) _Pragma("unroll") for (int n = 0; n < 2; ++n) _Pragma("unroll") for (int k = 0; k < 2; ++k) \
;         acc[ai][bj][m][n] = __builtin_amdgcn_mfma_f32_16x16x32_bf16(Bt[n][k], At[m][k], acc[ai][bj][m][n], 0, 0, 0); __builtin_amdgcn_s_setprio(0); } while (0)
; #define PG8_WAIT_V(n) asm volatile("s_waitcnt vmcnt(" #n ")" ::: "memory")
; #define PG8_WAIT_L(n) asm volatile("s_waitcnt lgkmcnt(" #n ")" ::: "memory")
; #define PG8_BAR __builtin_amdgcn_s_barrier()
; #define PG8_SCHED __builtin_amdgcn_sched_barrier(0)
; template <class Epi, class Sched, bool ALIGN_EPI = false, bool SP2 = false>
; __device__ __forceinline__ void gemm_phase(PG8_LAS unsigned char* lds, const Gemm g, const Sched& S, const Epi& E) {
;     ...
;         for (int t = 0; t < nt; t += 2) {
;     ...
;             PG8_LDA(At, 1, 1); PG8_STAGE(PG8_SB(1, 0), b3, voffB); PG8_STAGE(PG8_SB(1, 1), b3 + hstep, voffB); PG8_STAGE(PG8_SA(1, 0), a3, voffA);
;             PG8_WAIT_V(8); PG8_WAIT_L(0); PG8_BAR; PG8_MMA(1, 0, At, B0); PG8_MMA(1, 1, At, B1); PG8_BAR; PG8_SCHED;
	s_add_i32 s24, s33, s28
	s_add_i32 m0, s24, 0xffffff80
	ds_read_b128 v[190:193], v155 offset:49152
	ds_read_b128 v[194:197], v155 offset:50176
	ds_read_b128 v[198:201], v155 offset:51200
	ds_read_b128 v[202:205], v155 offset:52224
	ds_read_b128 v[206:209], v155 offset:53248
	ds_read_b128 v[210:213], v155 offset:54272
	ds_read_b128 v[214:217], v155 offset:55296
	ds_read_b128 v[218:221], v155 offset:56320
	global_load_lds_dwordx4 v[162:163], off offset:128
	s_add_i32 m0, s24, 0x1f80
	s_add_u32 s20, s20, 0x100080
	s_addc_u32 s21, s21, 0
	s_add_i32 s24, s42, s28
	global_load_lds_dwordx4 v[222:223], off offset:128
	s_mov_b32 m0, s24
	s_nop 0
	global_load_lds_dwordx4 v132, s[20:21]
	s_add_i32 m0, s24, 0x2000
	s_nop 0
	global_load_lds_dwordx4 v136, s[20:21]
	s_add_i32 m0, s43, 0xffffff80
	s_nop 0
	global_load_lds_dwordx4 v[224:225], off offset:128
	s_add_i32 m0, s46, 0xffffff80
	s_nop 0
	global_load_lds_dwordx4 v[226:227], off offset:128
	s_waitcnt vmcnt(8)
	s_waitcnt lgkmcnt(0)
	s_barrier
	s_waitcnt lgkmcnt(0)
	v_mfma_f32_16x16x32_bf16 v[54:57], v[148:151], v[190:193], v[54:57]
	v_mfma_f32_16x16x32_bf16 v[50:53], v[166:169], v[190:193], v[50:53]
	v_mfma_f32_16x16x32_bf16 v[38:41], v[148:151], v[198:201], v[38:41]
	v_mfma_f32_16x16x32_bf16 v[34:37], v[166:169], v[198:201], v[34:37]
	v_mfma_f32_16x16x32_bf16 v[22:25], v[148:151], v[206:209], v[22:25]
	v_mfma_f32_16x16x32_bf16 v[18:21], v[166:169], v[206:209], v[18:21]
	v_mfma_f32_16x16x32_bf16 v[6:9], v[148:151], v[214:217], v[6:9]
	v_mfma_f32_16x16x32_bf16 v[2:5], v[166:169], v[214:217], v[2:5]
	v_mfma_f32_16x16x32_bf16 v[54:57], v[156:159], v[194:197], v[54:57]
	v_mfma_f32_16x16x32_bf16 v[50:53], v[170:173], v[194:197], v[50:53]
	v_mfma_f32_16x16x32_bf16 v[38:41], v[156:159], v[202:205], v[38:41]
	v_mfma_f32_16x16x32_bf16 v[34:37], v[170:173], v[202:205], v[34:37]
	v_mfma_f32_16x16x32_bf16 v[22:25], v[156:159], v[210:213], v[22:25]
	v_mfma_f32_16x16x32_bf16 v[18:21], v[170:173], v[210:213], v[18:21]
	v_mfma_f32_16x16x32_bf16 v[6:9], v[156:159], v[218:221], v[6:9]
	v_mfma_f32_16x16x32_bf16 v[2:5], v[170:173], v[218:221], v[2:5]
	v_mfma_f32_16x16x32_bf16 v[62:65], v[174:177], v[190:193], v[62:65]
	v_mfma_f32_16x16x32_bf16 v[58:61], v[182:185], v[190:193], v[58:61]
	v_mfma_f32_16x16x32_bf16 v[46:49], v[174:177], v[198:201], v[46:49]
	v_mfma_f32_16x16x32_bf16 v[42:45], v[182:185], v[198:201], v[42:45]
	v_mfma_f32_16x16x32_bf16 v[30:33], v[174:177], v[206:209], v[30:33]
	v_mfma_f32_16x16x32_bf16 v[26:29], v[182:185], v[206:209], v[26:29]
	v_mfma_f32_16x16x32_bf16 v[10:13], v[174:177], v[214:217], v[10:13]
	v_mfma_f32_16x16x32_bf16 v[14:17], v[182:185], v[214:217], v[14:17]
	v_mfma_f32_16x16x32_bf16 v[62:65], v[178:181], v[194:197], v[62:65]
	v_mfma_f32_16x16x32_bf16 v[58:61], v[186:189], v[194:197], v[58:61]
	v_mfma_f32_16x16x32_bf16 v[46:49], v[178:181], v[202:205], v[46:49]
	v_mfma_f32_16x16x32_bf16 v[42:45], v[186:189], v[202:205], v[42:45]
	v_mfma_f32_16x16x32_bf16 v[30:33], v[178:181], v[210:213], v[30:33]
	v_mfma_f32_16x16x32_bf16 v[26:29], v[186:189], v[210:213], v[26:29]
	v_mfma_f32_16x16x32_bf16 v[10:13], v[178:181], v[218:221], v[10:13]
	v_mfma_f32_16x16x32_bf16 v[14:17], v[186:189], v[218:221], v[14:17]
	s_barrier
	s_add_i32 s67, s67, 2
	s_add_u32 s22, s22, 0x100
	s_addc_u32 s23, s23, 0
	s_add_u32 s65, s65, 0x100
	s_addc_u32 s66, s66, 0
	s_cmp_gt_u32 s67, 61
	s_cbranch_scc0 .LBB0_1332


; #define PG8_BAR __builtin_amdgcn_s_barrier()
; template <class Epi, class Sched, bool ALIGN_EPI = false, bool SP2 = false>
; __device__ __forceinline__ void gemm_phase(PG8_LAS unsigned char* lds, const Gemm g, const Sched& S, const Epi& E) {
;     ...
;         if constexpr (ALIGN_EPI) { if (wr == 0) PG8_BAR; }
	s_and_b64 vcc, exec, s[8:9]
	s_cbranch_vccz .LBB0_1335
	s_barrier

; #define PG8_STAGE(bufoff, gbase, voff) do { _Pragma("unroll") for (int _i = 0; _i < 2; ++_i) \
;         __builtin_amdgcn_global_load_lds((const unsigned*)((const char*)(gbase) + (voff)[_i]), (PG8_LAS unsigned*)(lds + (bufoff) + ldsw + _i * 8192), 16, 0, 0); } while (0)
; #define PG8_LDA(dst, b, h) do { _Pragma("unroll") for (int m = 0; m < 4; ++m) _Pragma("unroll") for (int k = 0; k < 2; ++k) dst[m][k] = *(const PG8_LAS bf16x8*)(lds + PG8_SA(b, h) + aoff + m * 2048 + k * 1024); } while (0)
; #define PG8_LDB(dst, b, h) do { _Pragma("unroll") for (int n = 0; n < 2; ++n) _Pragma("unroll") for (int k = 0; k < 2; ++k) dst[n][k] = *(const PG8_LAS bf16x8*)(lds + PG8_SB(b, h) + boff + n * 2048 + k * 1024); } while (0)
; #define PG8_MMA(ai, bj, At, Bt) do { __builtin_amdgcn_s_setprio(1); _Pragma("unroll") for (int m = 0; m < 4; ++m) _Pragma("unroll") for (int n = 0; n < 2; ++n) _Pragma("unroll") for (int k = 0; k < 2; ++k) \
;         acc[ai][bj][m][n] = __builtin_amdgcn_mfma_f32_16x16x32_bf16(Bt[n][k], At[m][k], acc[ai][bj][m][n], 0, 0, 0); __builtin_amdgcn_s_setprio(0); } while (0)
; #define PG8_WAIT_V(n) asm volatile("s_waitcnt vmcnt(" #n ")" ::: "memory")
; template <class Epi, class Sched, bool ALIGN_EPI = false, bool SP2 = false>
; __device__ __forceinline__ void gemm_phase(PG8_LAS unsigned char* lds, const Gemm g, const Sched& S, const Epi& E) {
;     ...
;         const char* nA = has_next ? (const char*)g.A + (size_t)nxt.pm * tstep : cA; const char* nB = has_next ? (const char*)g.Bt + (size_t)nxt.pn * tstep : cB;
;         for (int t = 0; t < nt; t += 2) {
;             const bool last = (t == nt - 2);
;             const char* a1 = cA + (size_t)(t + 1) * kstep;
;             const char* a2 = last ? nA : cA + (size_t)(t + 2) * kstep; const char* b2 = last ? nB : cB + (size_t)(t + 2) * kstep;
;             const char* a3 = a2 + kstep; const char* b3 = b2 + kstep;
;             if (last && has_next) S.a_ready(nxt);
;             if constexpr (SP2) {
;             PG8_LDB(B0, 0, 0); PG8_LDB(B1, 0, 1); PG8_SCHED; PG8_LDA(At, 0, 0); PG8_STAGE(PG8_SA(1, 1), a1 + hstep, voffA);
;             PG8_WAIT_V(8); PG8_WAIT_L(0); PG8_BAR; PG8_MMA(0, 0, At, B0); PG8_MMA(0, 1, At, B1); PG8_BAR; PG8_SCHED;
;             PG8_LDA(At, 0, 1); PG8_STAGE(PG8_SB(0, 0), b2, voffB); PG8_STAGE(PG8_SB(0, 1), b2 + hstep, voffB); PG8_STAGE(PG8_SA(0, 0), a2, voffA);
.LBB0_1594:
	s_ashr_i32 s15, s14, 31
	s_lshl_b64 s[16:17], s[14:15], 21
	s_add_u32 s16, s30, s16
	s_addc_u32 s17, s31, s17
	s_and_b64 s[18:19], s[2:3], exec
	s_cselect_b32 s15, s17, s27
	s_cselect_b32 s21, s16, s26
	s_ashr_i32 s13, s12, 31
	s_lshl_b64 s[18:19], s[12:13], 21
	s_add_u32 s18, s34, s18
	s_addc_u32 s19, s35, s19
	s_and_b64 s[28:29], s[2:3], exec
	s_cselect_b32 s13, s19, s25
	s_cselect_b32 s51, s18, s24
	s_add_u32 s26, s26, 0x100080
	s_addc_u32 s27, s27, 0
	s_add_u32 s52, s24, 0x100
	s_addc_u32 s53, s25, 0
	s_mov_b32 s62, -2
	v_add_u32_e32 v241, 0x10000, v165
.LBB0_1595:
	ds_read_b128 v[130:133], v241 offset:0
	ds_read_b128 v[134:137], v241 offset:1024
	ds_read_b128 v[138:141], v241 offset:2048
	ds_read_b128 v[142:145], v241 offset:3072
	ds_read_b128 v[146:149], v241 offset:16384
	ds_read_b128 v[150:153], v241 offset:17408
	ds_read_b128 v[172:175], v241 offset:18432
	ds_read_b128 v[176:179], v241 offset:19456
	s_add_u32 s24, s26, 0xfff00080
	s_addc_u32 s25, s27, -1
	s_cmp_eq_u32 s62, 60
	s_cselect_b32 s29, s15, s25
	s_cselect_b32 s28, s21, s24
	s_cselect_b32 s25, s13, s53
	s_cselect_b32 s24, s51, s52
	s_add_i32 m0, s23, 0xc000
	ds_read_b128 v[180:183], v185
	ds_read_b128 v[188:191], v185 offset:1024
	ds_read_b128 v[192:195], v185 offset:2048
	ds_read_b128 v[196:199], v185 offset:3072
	ds_read_b128 v[200:203], v185 offset:4096
	ds_read_b128 v[204:207], v185 offset:5120
	ds_read_b128 v[208:211], v185 offset:6144
	ds_read_b128 v[212:215], v185 offset:7168
	global_load_lds_dwordx4 v162, s[26:27]
	s_add_i32 m0, s23, 0xe000
	s_nop 0
	global_load_lds_dwordx4 v166, s[26:27]
	s_waitcnt vmcnt(8)
	s_waitcnt lgkmcnt(0)
	s_barrier
	s_waitcnt lgkmcnt(0)
	v_mfma_f32_16x16x32_bf16 v[114:117], v[130:133], v[180:183], v[114:117]
	v_mfma_f32_16x16x32_bf16 v[118:121], v[138:141], v[180:183], v[118:121]
	v_mfma_f32_16x16x32_bf16 v[106:109], v[130:133], v[192:195], v[106:109]
	v_mfma_f32_16x16x32_bf16 v[98:101], v[138:141], v[192:195], v[98:101]
	v_mfma_f32_16x16x32_bf16 v[90:93], v[130:133], v[200:203], v[90:93]
	v_mfma_f32_16x16x32_bf16 v[82:85], v[138:141], v[200:203], v[82:85]
	v_mfma_f32_16x16x32_bf16 v[74:77], v[130:133], v[208:211], v[74:77]
	v_mfma_f32_16x16x32_bf16 v[66:69], v[138:141], v[208:211], v[66:69]
	v_mfma_f32_16x16x32_bf16 v[114:117], v[134:137], v[188:191], v[114:117]
	v_mfma_f32_16x16x32_bf16 v[118:121], v[142:145], v[188:191], v[118:121]
	v_mfma_f32_16x16x32_bf16 v[106:109], v[134:137], v[196:199], v[106:109]
	v_mfma_f32_16x16x32_bf16 v[98:101], v[142:145], v[196:199], v[98:101]
	v_mfma_f32_16x16x32_bf16 v[90:93], v[134:137], v[204:207], v[90:93]
	v_mfma_f32_16x16x32_bf16 v[82:85], v[142:145], v[204:207], v[82:85]
	v_mfma_f32_16x16x32_bf16 v[74:77], v[134:137], v[212:215], v[74:77]
	v_mfma_f32_16x16x32_bf16 v[66:69], v[142:145], v[212:215], v[66:69]
	v_mfma_f32_16x16x32_bf16 v[122:125], v[146:149], v[180:183], v[122:125]
	v_mfma_f32_16x16x32_bf16 v[126:129], v[172:175], v[180:183], v[126:129]
	v_mfma_f32_16x16x32_bf16 v[110:113], v[146:149], v[192:195], v[110:113]
	v_mfma_f32_16x16x32_bf16 v[102:105], v[172:175], v[192:195], v[102:105]
	v_mfma_f32_16x16x32_bf16 v[94:97], v[146:149], v[200:203], v[94:97]
	v_mfma_f32_16x16x32_bf16 v[86:89], v[172:175], v[200:203], v[86:89]
	v_mfma_f32_16x16x32_bf16 v[78:81], v[146:149], v[208:211], v[78:81]
	v_mfma_f32_16x16x32_bf16 v[70:73], v[172:175], v[208:211], v[70:73]
	v_mfma_f32_16x16x32_bf16 v[122:125], v[150:153], v[188:191], v[122:125]
	v_mfma_f32_16x16x32_bf16 v[126:129], v[176:179], v[188:191], v[126:129]
	v_mfma_f32_16x16x32_bf16 v[110:113], v[150:153], v[196:199], v[110:113]
	v_mfma_f32_16x16x32_bf16 v[102:105], v[176:179], v[196:199], v[102:105]
	v_mfma_f32_16x16x32_bf16 v[94:97], v[150:153], v[204:207], v[94:97]
	v_mfma_f32_16x16x32_bf16 v[86:89], v[176:179], v[204:207], v[86:89]
	v_mfma_f32_16x16x32_bf16 v[78:81], v[150:153], v[212:215], v[78:81]
	v_mfma_f32_16x16x32_bf16 v[70:73], v[176:179], v[212:215], v[70:73]
	s_barrier
	s_add_i32 s33, s48, s36
	v_lshl_add_u64 v[216:217], s[24:25], 0, v[156:157]
	s_mov_b32 m0, s33
	ds_read_b128 v[180:183], v185 offset:16384
	ds_read_b128 v[188:191], v185 offset:17408
	ds_read_b128 v[192:195], v185 offset:18432
	ds_read_b128 v[196:199], v185 offset:19456
	ds_read_b128 v[200:203], v185 offset:20480
	ds_read_b128 v[204:207], v185 offset:21504
	ds_read_b128 v[208:211], v185 offset:22528
	ds_read_b128 v[212:215], v185 offset:23552
	global_load_lds_dwordx4 v[216:217], off
	s_add_i32 m0, s33, 0x2000
	s_add_u32 s64, s24, 0x100000
	v_lshl_add_u64 v[218:219], s[24:25], 0, v[160:161]
	s_addc_u32 s65, s25, 0
	s_add_i32 s33, s49, s36
	global_load_lds_dwordx4 v[218:219], off
	s_mov_b32 m0, s33
	v_lshl_add_u64 v[222:223], s[28:29], 0, v[158:159]
	global_load_lds_dwordx4 v156, s[64:65]
	s_add_i32 m0, s33, 0x2000
	s_nop 0
	global_load_lds_dwordx4 v160, s[64:65]
	v_lshl_add_u64 v[220:221], s[28:29], 0, v[154:155]
	s_mov_b32 m0, s23
	s_nop 0
	global_load_lds_dwordx4 v[220:221], off
	s_mov_b32 m0, s37
	s_nop 0
	global_load_lds_dwordx4 v[222:223], off
	s_waitcnt vmcnt(8)
	s_waitcnt lgkmcnt(0)
	s_barrier
; #define PG8_STAGE(bufoff, gbase, voff) do { _Pragma("unroll") for (int _i = 0; _i < 2; ++_i) \
;         __builtin_amdgcn_global_load_lds((const unsigned*)((const char*)(gbase) + (voff)[_i]), (PG8_LAS unsigned*)(lds + (bufoff) + ldsw + _i * 8192), 16, 0, 0); } while (0)
; #define PG8_LDA(dst, b, h) do { _Pragma("unroll") for (int m = 0; m < 4; ++m) _Pragma("unroll") for (int k = 0; k < 2; ++k) dst[m][k] = *(const PG8_LAS bf16x8*)(lds + PG8_SA(b, h) + aoff + m * 2048 + k * 1024); } while (0)
; #define PG8_LDB(dst, b, h) do { _Pragma("unroll") for (int n = 0; n < 2; ++n) _Pragma("unroll") for (int k = 0; k < 2; ++k) dst[n][k] = *(const PG8_LAS bf16x8*)(lds + PG8_SB(b, h) + boff + n * 2048 + k * 1024); } while (0)
; #define PG8_MMA(ai, bj, At, Bt) do { __builtin_amdgcn_s_setprio(1); _Pragma("unroll") for (int m = 0; m < 4; ++m) _Pragma("unroll") for (int n = 0; n < 2; ++n) _Pragma("unroll") for (int k = 0; k < 2; ++k) \
;         acc[ai][bj][m][n] = __builtin_amdgcn_mfma_f32_16x16x32_bf16(Bt[n][k], At[m][k], acc[ai][bj][m][n], 0, 0, 0); __builtin_amdgcn_s_setprio(0); } while (0)
; #define PG8_WAIT_V(n) asm volatile("s_waitcnt vmcnt(" #n ")" ::: "memory")
; #define PG8_WAIT_L(n) asm volatile("s_waitcnt lgkmcnt(" #n ")" ::: "memory")
; #define PG8_BAR __builtin_amdgcn_s_barrier()
; #define PG8_SCHED __builtin_amdgcn_sched_barrier(0)
; template <class Epi, class Sched, bool ALIGN_EPI = false, bool SP2 = false>
; __device__ __forceinline__ void gemm_phase(PG8_LAS unsigned char* lds, const Gemm g, const Sched& S, const Epi& E) {
;     ...
;             PG8_WAIT_V(8); PG8_WAIT_L(0); PG8_BAR; PG8_MMA(1, 0, At, B0); PG8_MMA(1, 1, At, B1); PG8_BAR; PG8_SCHED;
;             PG8_LDB(B0, 1, 0); PG8_LDB(B1, 1, 1); PG8_SCHED; PG8_LDA(At, 1, 0); PG8_STAGE(PG8_SA(0, 1), a2 + hstep, voffA);
;             PG8_WAIT_V(8); PG8_WAIT_L(0); PG8_BAR; PG8_MMA(0, 0, At, B0); PG8_MMA(0, 1, At, B1); PG8_BAR; PG8_SCHED;
	s_waitcnt lgkmcnt(0)
	v_mfma_f32_16x16x32_bf16 v[58:61], v[130:133], v[180:183], v[58:61]
	v_mfma_f32_16x16x32_bf16 v[54:57], v[138:141], v[180:183], v[54:57]
	v_mfma_f32_16x16x32_bf16 v[42:45], v[130:133], v[192:195], v[42:45]
	v_mfma_f32_16x16x32_bf16 v[34:37], v[138:141], v[192:195], v[34:37]
	v_mfma_f32_16x16x32_bf16 v[26:29], v[130:133], v[200:203], v[26:29]
	v_mfma_f32_16x16x32_bf16 v[18:21], v[138:141], v[200:203], v[18:21]
	v_mfma_f32_16x16x32_bf16 v[6:9], v[130:133], v[208:211], v[6:9]
	v_mfma_f32_16x16x32_bf16 v[2:5], v[138:141], v[208:211], v[2:5]
	v_mfma_f32_16x16x32_bf16 v[58:61], v[134:137], v[188:191], v[58:61]
	v_mfma_f32_16x16x32_bf16 v[54:57], v[142:145], v[188:191], v[54:57]
	v_mfma_f32_16x16x32_bf16 v[42:45], v[134:137], v[196:199], v[42:45]
	v_mfma_f32_16x16x32_bf16 v[34:37], v[142:145], v[196:199], v[34:37]
	v_mfma_f32_16x16x32_bf16 v[26:29], v[134:137], v[204:207], v[26:29]
	v_mfma_f32_16x16x32_bf16 v[18:21], v[142:145], v[204:207], v[18:21]
	v_mfma_f32_16x16x32_bf16 v[6:9], v[134:137], v[212:215], v[6:9]
	v_mfma_f32_16x16x32_bf16 v[2:5], v[142:145], v[212:215], v[2:5]
	v_mfma_f32_16x16x32_bf16 v[62:65], v[146:149], v[180:183], v[62:65]
	v_mfma_f32_16x16x32_bf16 v[50:53], v[172:175], v[180:183], v[50:53]
	v_mfma_f32_16x16x32_bf16 v[46:49], v[146:149], v[192:195], v[46:49]
	v_mfma_f32_16x16x32_bf16 v[38:41], v[172:175], v[192:195], v[38:41]
	v_mfma_f32_16x16x32_bf16 v[30:33], v[146:149], v[200:203], v[30:33]
	v_mfma_f32_16x16x32_bf16 v[22:25], v[172:175], v[200:203], v[22:25]
	v_mfma_f32_16x16x32_bf16 v[10:13], v[146:149], v[208:211], v[10:13]
	v_mfma_f32_16x16x32_bf16 v[14:17], v[172:175], v[208:211], v[14:17]
	v_mfma_f32_16x16x32_bf16 v[62:65], v[150:153], v[188:191], v[62:65]
	v_mfma_f32_16x16x32_bf16 v[50:53], v[176:179], v[188:191], v[50:53]
	v_mfma_f32_16x16x32_bf16 v[46:49], v[150:153], v[196:199], v[46:49]
	v_mfma_f32_16x16x32_bf16 v[38:41], v[176:179], v[196:199], v[38:41]
	v_mfma_f32_16x16x32_bf16 v[30:33], v[150:153], v[204:207], v[30:33]
	v_mfma_f32_16x16x32_bf16 v[22:25], v[176:179], v[204:207], v[22:25]
	v_mfma_f32_16x16x32_bf16 v[10:13], v[150:153], v[212:215], v[10:13]
	v_mfma_f32_16x16x32_bf16 v[14:17], v[176:179], v[212:215], v[14:17]
	s_barrier
	s_add_i32 s33, 0, 0x18000
	s_add_i32 s42, 0, 0x1c000
	ds_read_b128 v[130:133], v241 offset:32768
	ds_read_b128 v[134:137], v241 offset:33792
	ds_read_b128 v[138:141], v241 offset:34816
	ds_read_b128 v[142:145], v241 offset:35840
	ds_read_b128 v[146:149], v241 offset:49152
	ds_read_b128 v[150:153], v241 offset:50176
	ds_read_b128 v[172:175], v241 offset:51200
	ds_read_b128 v[176:179], v241 offset:52224
	s_add_u32 s28, s28, 0x100000
	s_addc_u32 s29, s29, 0
	s_mov_b32 m0, s40
	ds_read_b128 v[180:183], v185 offset:32768
	ds_read_b128 v[188:191], v185 offset:33792
	ds_read_b128 v[192:195], v185 offset:34816
	ds_read_b128 v[196:199], v185 offset:35840
	ds_read_b128 v[200:203], v185 offset:36864
	ds_read_b128 v[204:207], v185 offset:37888
	ds_read_b128 v[208:211], v185 offset:38912
	ds_read_b128 v[212:215], v185 offset:39936
	global_load_lds_dwordx4 v154, s[28:29]
	s_mov_b32 m0, s41
	s_nop 0
	global_load_lds_dwordx4 v158, s[28:29]
	s_waitcnt vmcnt(8)
	s_waitcnt lgkmcnt(0)
	s_barrier
	s_waitcnt lgkmcnt(0)
	v_mfma_f32_16x16x32_bf16 v[114:117], v[130:133], v[180:183], v[114:117]
	v_mfma_f32_16x16x32_bf16 v[118:121], v[138:141], v[180:183], v[118:121]
	v_mfma_f32_16x16x32_bf16 v[106:109], v[130:133], v[192:195], v[106:109]
	v_mfma_f32_16x16x32_bf16 v[98:101], v[138:141], v[192:195], v[98:101]
	v_mfma_f32_16x16x32_bf16 v[90:93], v[130:133], v[200:203], v[90:93]
	v_mfma_f32_16x16x32_bf16 v[82:85], v[138:141], v[200:203], v[82:85]
	v_mfma_f32_16x16x32_bf16 v[74:77], v[130:133], v[208:211], v[74:77]
	v_mfma_f32_16x16x32_bf16 v[66:69], v[138:141], v[208:211], v[66:69]
	v_mfma_f32_16x16x32_bf16 v[114:117], v[134:137], v[188:191], v[114:117]
	v_mfma_f32_16x16x32_bf16 v[118:121], v[142:145], v[188:191], v[118:121]
	v_mfma_f32_16x16x32_bf16 v[106:109], v[134:137], v[196:199], v[106:109]
	v_mfma_f32_16x16x32_bf16 v[98:101], v[142:145], v[196:199], v[98:101]
	v_mfma_f32_16x16x32_bf16 v[90:93], v[134:137], v[204:207], v[90:93]
	v_mfma_f32_16x16x32_bf16 v[82:85], v[142:145], v[204:207], v[82:85]
	v_mfma_f32_16x16x32_bf16 v[74:77], v[134:137], v[212:215], v[74:77]
	v_mfma_f32_16x16x32_bf16 v[66:69], v[142:145], v[212:215], v[66:69]
	v_mfma_f32_16x16x32_bf16 v[122:125], v[146:149], v[180:183], v[122:125]
	v_mfma_f32_16x16x32_bf16 v[126:129], v[172:175], v[180:183], v[126:129]
	v_mfma_f32_16x16x32_bf16 v[110:113], v[146:149], v[192:195], v[110:113]
	v_mfma_f32_16x16x32_bf16 v[102:105], v[172:175], v[192:195], v[102:105]
	v_mfma_f32_16x16x32_bf16 v[94:97], v[146:149], v[200:203], v[94:97]
	v_mfma_f32_16x16x32_bf16 v[86:89], v[172:175], v[200:203], v[86:89]
	v_mfma_f32_16x16x32_bf16 v[78:81], v[146:149], v[208:211], v[78:81]
	v_mfma_f32_16x16x32_bf16 v[70:73], v[172:175], v[208:211], v[70:73]
	v_mfma_f32_16x16x32_bf16 v[122:125], v[150:153], v[188:191], v[122:125]
	v_mfma_f32_16x16x32_bf16 v[126:129], v[176:179], v[188:191], v[126:129]
	v_mfma_f32_16x16x32_bf16 v[110:113], v[150:153], v[196:199], v[110:113]
	v_mfma_f32_16x16x32_bf16 v[102:105], v[176:179], v[196:199], v[102:105]
	v_mfma_f32_16x16x32_bf16 v[94:97], v[150:153], v[204:207], v[94:97]
	v_mfma_f32_16x16x32_bf16 v[86:89], v[176:179], v[204:207], v[86:89]
	v_mfma_f32_16x16x32_bf16 v[78:81], v[150:153], v[212:215], v[78:81]
	v_mfma_f32_16x16x32_bf16 v[70:73], v[176:179], v[212:215], v[70:73]
	s_barrier
; #define PG8_STAGE(bufoff, gbase, voff) do { _Pragma("unroll") for (int _i = 0; _i < 2; ++_i) \
;         __builtin_amdgcn_global_load_lds((const unsigned*)((const char*)(gbase) + (voff)[_i]), (PG8_LAS unsigned*)(lds + (bufoff) + ldsw + _i * 8192), 16, 0, 0); } while (0)
; #define PG8_LDA(dst, b, h) do { _Pragma("unroll") for (int m = 0; m < 4; ++m) _Pragma("unroll") for (int k = 0; k < 2; ++k) dst[m][k] = *(const PG8_LAS bf16x8*)(lds + PG8_SA(b, h) + aoff + m * 2048 + k * 1024); } while (0)
; #define PG8_MMA(ai, bj, At, Bt) do { __builtin_amdgcn_s_setprio(1); _Pragma("unroll") for (int m = 0; m < 4; ++m) _Pragma("unroll") for (int n = 0; n < 2; ++n) _Pragma("unroll") for (int k = 0; k < 2; ++k) \
;         acc[ai][bj][m][n] = __builtin_amdgcn_mfma_f32_16x16x32_bf16(Bt[n][k], At[m][k], acc[ai][bj][m][n], 0, 0, 0); __builtin_amdgcn_s_setprio(0); } while (0)
; #define PG8_WAIT_V(n) asm volatile("s_waitcnt vmcnt(" #n ")" ::: "memory")
; #define PG8_WAIT_L(n) asm volatile("s_waitcnt lgkmcnt(" #n ")" ::: "memory")
; #define PG8_BAR __builtin_amdgcn_s_barrier()
; #define PG8_SCHED __builtin_amdgcn_sched_barrier(0)
; template <class Epi, class Sched, bool ALIGN_EPI = false, bool SP2 = false>
; __device__ __forceinline__ void gemm_phase(PG8_LAS unsigned char* lds, const Gemm g, const Sched& S, const Epi& E) {
;     ...
;         for (int t = 0; t < nt; t += 2) {
;     ...
;             PG8_LDA(At, 1, 1); PG8_STAGE(PG8_SB(1, 0), b3, voffB); PG8_STAGE(PG8_SB(1, 1), b3 + hstep, voffB); PG8_STAGE(PG8_SA(1, 0), a3, voffA);
;             PG8_WAIT_V(8); PG8_WAIT_L(0); PG8_BAR; PG8_MMA(1, 0, At, B0); PG8_MMA(1, 1, At, B1); PG8_BAR; PG8_SCHED;
	s_add_i32 s28, s33, s36
	s_add_i32 m0, s28, 0xffffff80
	ds_read_b128 v[180:183], v185 offset:49152
	ds_read_b128 v[188:191], v185 offset:50176
	ds_read_b128 v[192:195], v185 offset:51200
	ds_read_b128 v[196:199], v185 offset:52224
	ds_read_b128 v[200:203], v185 offset:53248
	ds_read_b128 v[204:207], v185 offset:54272
	ds_read_b128 v[208:211], v185 offset:55296
	ds_read_b128 v[212:215], v185 offset:56320
	global_load_lds_dwordx4 v[216:217], off offset:128
	s_add_i32 m0, s28, 0x1f80
	s_add_u32 s24, s24, 0x100080
	s_addc_u32 s25, s25, 0
	s_add_i32 s28, s42, s36
	global_load_lds_dwordx4 v[218:219], off offset:128
	s_mov_b32 m0, s28
	s_nop 0
	global_load_lds_dwordx4 v156, s[24:25]
	s_add_i32 m0, s28, 0x2000
	s_nop 0
	global_load_lds_dwordx4 v160, s[24:25]
	s_add_i32 m0, s44, 0xffffff80
	s_nop 0
	global_load_lds_dwordx4 v[220:221], off offset:128
	s_add_i32 m0, s45, 0xffffff80
	s_nop 0
	global_load_lds_dwordx4 v[222:223], off offset:128
	s_waitcnt vmcnt(8)
	s_waitcnt lgkmcnt(0)
	s_barrier
	s_waitcnt lgkmcnt(0)
	v_mfma_f32_16x16x32_bf16 v[58:61], v[130:133], v[180:183], v[58:61]
	v_mfma_f32_16x16x32_bf16 v[54:57], v[138:141], v[180:183], v[54:57]
	v_mfma_f32_16x16x32_bf16 v[42:45], v[130:133], v[192:195], v[42:45]
	v_mfma_f32_16x16x32_bf16 v[34:37], v[138:141], v[192:195], v[34:37]
	v_mfma_f32_16x16x32_bf16 v[26:29], v[130:133], v[200:203], v[26:29]
	v_mfma_f32_16x16x32_bf16 v[18:21], v[138:141], v[200:203], v[18:21]
	v_mfma_f32_16x16x32_bf16 v[6:9], v[130:133], v[208:211], v[6:9]
	v_mfma_f32_16x16x32_bf16 v[2:5], v[138:141], v[208:211], v[2:5]
	v_mfma_f32_16x16x32_bf16 v[58:61], v[134:137], v[188:191], v[58:61]
	v_mfma_f32_16x16x32_bf16 v[54:57], v[142:145], v[188:191], v[54:57]
	v_mfma_f32_16x16x32_bf16 v[42:45], v[134:137], v[196:199], v[42:45]
	v_mfma_f32_16x16x32_bf16 v[34:37], v[142:145], v[196:199], v[34:37]
	v_mfma_f32_16x16x32_bf16 v[26:29], v[134:137], v[204:207], v[26:29]
	v_mfma_f32_16x16x32_bf16 v[18:21], v[142:145], v[204:207], v[18:21]
	v_mfma_f32_16x16x32_bf16 v[6:9], v[134:137], v[212:215], v[6:9]
	v_mfma_f32_16x16x32_bf16 v[2:5], v[142:145], v[212:215], v[2:5]
	v_mfma_f32_16x16x32_bf16 v[62:65], v[146:149], v[180:183], v[62:65]
	v_mfma_f32_16x16x32_bf16 v[50:53], v[172:175], v[180:183], v[50:53]
	v_mfma_f32_16x16x32_bf16 v[46:49], v[146:149], v[192:195], v[46:49]
	v_mfma_f32_16x16x32_bf16 v[38:41], v[172:175], v[192:195], v[38:41]
	v_mfma_f32_16x16x32_bf16 v[30:33], v[146:149], v[200:203], v[30:33]
	v_mfma_f32_16x16x32_bf16 v[22:25], v[172:175], v[200:203], v[22:25]
	v_mfma_f32_16x16x32_bf16 v[10:13], v[146:149], v[208:211], v[10:13]
	v_mfma_f32_16x16x32_bf16 v[14:17], v[172:175], v[208:211], v[14:17]
	v_mfma_f32_16x16x32_bf16 v[62:65], v[150:153], v[188:191], v[62:65]
	v_mfma_f32_16x16x32_bf16 v[50:53], v[176:179], v[188:191], v[50:53]
	v_mfma_f32_16x16x32_bf16 v[46:49], v[150:153], v[196:199], v[46:49]
	v_mfma_f32_16x16x32_bf16 v[38:41], v[176:179], v[196:199], v[38:41]
	v_mfma_f32_16x16x32_bf16 v[30:33], v[150:153], v[204:207], v[30:33]
	v_mfma_f32_16x16x32_bf16 v[22:25], v[176:179], v[204:207], v[22:25]
	v_mfma_f32_16x16x32_bf16 v[10:13], v[150:153], v[212:215], v[10:13]
	v_mfma_f32_16x16x32_bf16 v[14:17], v[176:179], v[212:215], v[14:17]
	s_barrier
	s_add_i32 s62, s62, 2
	s_add_u32 s26, s26, 0x100
	s_addc_u32 s27, s27, 0
	s_add_u32 s52, s52, 0x100
	s_addc_u32 s53, s53, 0
	s_cmp_gt_u32 s62, 61
	s_cbranch_scc0 .LBB0_1595


; #define PG8_BAR __builtin_amdgcn_s_barrier()
; template <class Epi, class Sched, bool ALIGN_EPI = false, bool SP2 = false>
; __device__ __forceinline__ void gemm_phase(PG8_LAS unsigned char* lds, const Gemm g, const Sched& S, const Epi& E) {
;     ...
;         if constexpr (ALIGN_EPI) { if (wr == 0) PG8_BAR; }
	s_and_b64 vcc, exec, s[10:11]
	s_cbranch_vccz .LBB0_1598
	s_barrier

; #define PG8_STAGE(bufoff, gbase, voff) do { _Pragma("unroll") for (int _i = 0; _i < 2; ++_i) \
;         __builtin_amdgcn_global_load_lds((const unsigned*)((const char*)(gbase) + (voff)[_i]), (PG8_LAS unsigned*)(lds + (bufoff) + ldsw + _i * 8192), 16, 0, 0); } while (0)
; #define PG8_LDA(dst, b, h) do { _Pragma("unroll") for (int m = 0; m < 4; ++m) _Pragma("unroll") for (int k = 0; k < 2; ++k) dst[m][k] = *(const PG8_LAS bf16x8*)(lds + PG8_SA(b, h) + aoff + m * 2048 + k * 1024); } while (0)
; #define PG8_LDB(dst, b, h) do { _Pragma("unroll") for (int n = 0; n < 2; ++n) _Pragma("unroll") for (int k = 0; k < 2; ++k) dst[n][k] = *(const PG8_LAS bf16x8*)(lds + PG8_SB(b, h) + boff + n * 2048 + k * 1024); } while (0)
; #define PG8_MMA(ai, bj, At, Bt) do { __builtin_amdgcn_s_setprio(1); _Pragma("unroll") for (int m = 0; m < 4; ++m) _Pragma("unroll") for (int n = 0; n < 2; ++n) _Pragma("unroll") for (int k = 0; k < 2; ++k) \
;         acc[ai][bj][m][n] = __builtin_amdgcn_mfma_f32_16x16x32_bf16(Bt[n][k], At[m][k], acc[ai][bj][m][n], 0, 0, 0); __builtin_amdgcn_s_setprio(0); } while (0)
; #define PG8_WAIT_V(n) asm volatile("s_waitcnt vmcnt(" #n ")" ::: "memory")
; template <class Epi, class Sched, bool ALIGN_EPI = false, bool SP2 = false>
; __device__ __forceinline__ void gemm_phase(PG8_LAS unsigned char* lds, const Gemm g, const Sched& S, const Epi& E) {
;     ...
;         const char* nA = has_next ? (const char*)g.A + (size_t)nxt.pm * tstep : cA; const char* nB = has_next ? (const char*)g.Bt + (size_t)nxt.pn * tstep : cB;
;         for (int t = 0; t < nt; t += 2) {
;             const bool last = (t == nt - 2);
;             const char* a1 = cA + (size_t)(t + 1) * kstep;
;             const char* a2 = last ? nA : cA + (size_t)(t + 2) * kstep; const char* b2 = last ? nB : cB + (size_t)(t + 2) * kstep;
;             const char* a3 = a2 + kstep; const char* b3 = b2 + kstep;
;             if (last && has_next) S.a_ready(nxt);
;             if constexpr (SP2) {
;             PG8_LDB(B0, 0, 0); PG8_LDB(B1, 0, 1); PG8_SCHED; PG8_LDA(At, 0, 0); PG8_STAGE(PG8_SA(1, 1), a1 + hstep, voffA);
;             PG8_WAIT_V(8); PG8_WAIT_L(0); PG8_BAR; PG8_MMA(0, 0, At, B0); PG8_MMA(0, 1, At, B1); PG8_BAR; PG8_SCHED;
;             PG8_LDA(At, 0, 1); PG8_STAGE(PG8_SB(0, 0), b2, voffB); PG8_STAGE(PG8_SB(0, 1), b2 + hstep, voffB); PG8_STAGE(PG8_SA(0, 0), a2, voffA);
.LBB0_1680:
	s_ashr_i32 s15, s14, 31
	s_lshl_b64 s[16:17], s[14:15], 21
	s_add_u32 s16, s96, s16
	s_addc_u32 s17, s97, s17
	s_and_b64 s[18:19], s[0:1], exec
	s_cselect_b32 s15, s17, s25
	s_cselect_b32 s48, s16, s24
	s_ashr_i32 s13, s12, 31
	s_lshl_b64 s[18:19], s[12:13], 21
	s_add_u32 s18, s11, s18
	s_addc_u32 s19, s28, s19
	s_and_b64 s[26:27], s[0:1], exec
	s_cselect_b32 s13, s19, s23
	s_cselect_b32 s49, s18, s22
	s_add_u32 s24, s24, 0x100080
	s_addc_u32 s25, s25, 0
	s_add_u32 s50, s22, 0x100
	s_addc_u32 s51, s23, 0
	s_mov_b32 s52, -2
	v_add_u32_e32 v241, 0x10000, v151
.LBB0_1681:
	ds_read_b128 v[160:163], v241 offset:0
	ds_read_b128 v[166:169], v241 offset:1024
	ds_read_b128 v[170:173], v241 offset:2048
	ds_read_b128 v[174:177], v241 offset:3072
	ds_read_b128 v[178:181], v241 offset:16384
	ds_read_b128 v[182:185], v241 offset:17408
	ds_read_b128 v[186:189], v241 offset:18432
	ds_read_b128 v[190:193], v241 offset:19456
	s_add_u32 s22, s24, 0xfff00080
	s_addc_u32 s23, s25, -1
	s_cmp_eq_u32 s52, 60
	s_cselect_b32 s27, s15, s23
	s_cselect_b32 s26, s48, s22
	s_cselect_b32 s23, s13, s51
	s_cselect_b32 s22, s49, s50
	s_add_i32 m0, s21, 0xc000
	ds_read_b128 v[194:197], v155
	ds_read_b128 v[198:201], v155 offset:1024
	ds_read_b128 v[202:205], v155 offset:2048
	ds_read_b128 v[206:209], v155 offset:3072
	ds_read_b128 v[210:213], v155 offset:4096
	ds_read_b128 v[214:217], v155 offset:5120
	ds_read_b128 v[218:221], v155 offset:6144
	ds_read_b128 v[222:225], v155 offset:7168
	global_load_lds_dwordx4 v138, s[24:25]
	s_add_i32 m0, s21, 0xe000
	s_nop 0
	global_load_lds_dwordx4 v140, s[24:25]
	s_waitcnt vmcnt(8)
	s_waitcnt lgkmcnt(0)
	s_barrier
	s_waitcnt lgkmcnt(0)
	v_mfma_f32_16x16x32_bf16 v[122:125], v[160:163], v[194:197], v[122:125]
	v_mfma_f32_16x16x32_bf16 v[114:117], v[170:173], v[194:197], v[114:117]
	v_mfma_f32_16x16x32_bf16 v[106:109], v[160:163], v[202:205], v[106:109]
	v_mfma_f32_16x16x32_bf16 v[98:101], v[170:173], v[202:205], v[98:101]
	v_mfma_f32_16x16x32_bf16 v[90:93], v[160:163], v[210:213], v[90:93]
	v_mfma_f32_16x16x32_bf16 v[82:85], v[170:173], v[210:213], v[82:85]
	v_mfma_f32_16x16x32_bf16 v[74:77], v[160:163], v[218:221], v[74:77]
	v_mfma_f32_16x16x32_bf16 v[62:65], v[170:173], v[218:221], v[62:65]
	v_mfma_f32_16x16x32_bf16 v[122:125], v[166:169], v[198:201], v[122:125]
	v_mfma_f32_16x16x32_bf16 v[114:117], v[174:177], v[198:201], v[114:117]
	v_mfma_f32_16x16x32_bf16 v[106:109], v[166:169], v[206:209], v[106:109]
	v_mfma_f32_16x16x32_bf16 v[98:101], v[174:177], v[206:209], v[98:101]
	v_mfma_f32_16x16x32_bf16 v[90:93], v[166:169], v[214:217], v[90:93]
	v_mfma_f32_16x16x32_bf16 v[82:85], v[174:177], v[214:217], v[82:85]
	v_mfma_f32_16x16x32_bf16 v[74:77], v[166:169], v[222:225], v[74:77]
	v_mfma_f32_16x16x32_bf16 v[62:65], v[174:177], v[222:225], v[62:65]
	v_mfma_f32_16x16x32_bf16 v[126:129], v[178:181], v[194:197], v[126:129]
	v_mfma_f32_16x16x32_bf16 v[118:121], v[186:189], v[194:197], v[118:121]
	v_mfma_f32_16x16x32_bf16 v[110:113], v[178:181], v[202:205], v[110:113]
	v_mfma_f32_16x16x32_bf16 v[102:105], v[186:189], v[202:205], v[102:105]
	v_mfma_f32_16x16x32_bf16 v[94:97], v[178:181], v[210:213], v[94:97]
	v_mfma_f32_16x16x32_bf16 v[86:89], v[186:189], v[210:213], v[86:89]
	v_mfma_f32_16x16x32_bf16 v[78:81], v[178:181], v[218:221], v[78:81]
	v_mfma_f32_16x16x32_bf16 v[70:73], v[186:189], v[218:221], v[70:73]
	v_mfma_f32_16x16x32_bf16 v[126:129], v[182:185], v[198:201], v[126:129]
	v_mfma_f32_16x16x32_bf16 v[118:121], v[190:193], v[198:201], v[118:121]
	v_mfma_f32_16x16x32_bf16 v[110:113], v[182:185], v[206:209], v[110:113]
	v_mfma_f32_16x16x32_bf16 v[102:105], v[190:193], v[206:209], v[102:105]
	v_mfma_f32_16x16x32_bf16 v[94:97], v[182:185], v[214:217], v[94:97]
	v_mfma_f32_16x16x32_bf16 v[86:89], v[190:193], v[214:217], v[86:89]
	v_mfma_f32_16x16x32_bf16 v[78:81], v[182:185], v[222:225], v[78:81]
	v_mfma_f32_16x16x32_bf16 v[70:73], v[190:193], v[222:225], v[70:73]
	s_barrier
	s_add_i32 s33, s44, s29
	v_lshl_add_u64 v[148:149], s[22:23], 0, v[132:133]
	s_mov_b32 m0, s33
	ds_read_b128 v[194:197], v155 offset:16384
	ds_read_b128 v[198:201], v155 offset:17408
	ds_read_b128 v[202:205], v155 offset:18432
	ds_read_b128 v[206:209], v155 offset:19456
	ds_read_b128 v[210:213], v155 offset:20480
	ds_read_b128 v[214:217], v155 offset:21504
	ds_read_b128 v[218:221], v155 offset:22528
	ds_read_b128 v[222:225], v155 offset:23552
	global_load_lds_dwordx4 v[148:149], off
	s_add_i32 m0, s33, 0x2000
	s_add_u32 s62, s22, 0x100000
	v_lshl_add_u64 v[156:157], s[22:23], 0, v[136:137]
	s_addc_u32 s63, s23, 0
	s_add_i32 s33, s45, s29
	global_load_lds_dwordx4 v[156:157], off
	s_mov_b32 m0, s33
	v_lshl_add_u64 v[228:229], s[26:27], 0, v[134:135]
	global_load_lds_dwordx4 v132, s[62:63]
	s_add_i32 m0, s33, 0x2000
	s_nop 0
	global_load_lds_dwordx4 v136, s[62:63]
	v_lshl_add_u64 v[226:227], s[26:27], 0, v[130:131]
	s_mov_b32 m0, s21
	s_nop 0
	global_load_lds_dwordx4 v[226:227], off
	s_mov_b32 m0, s34
	s_nop 0
	global_load_lds_dwordx4 v[228:229], off
	s_waitcnt vmcnt(8)
	s_waitcnt lgkmcnt(0)
	s_barrier
; #define PG8_STAGE(bufoff, gbase, voff) do { _Pragma("unroll") for (int _i = 0; _i < 2; ++_i) \
;         __builtin_amdgcn_global_load_lds((const unsigned*)((const char*)(gbase) + (voff)[_i]), (PG8_LAS unsigned*)(lds + (bufoff) + ldsw + _i * 8192), 16, 0, 0); } while (0)
; #define PG8_LDA(dst, b, h) do { _Pragma("unroll") for (int m = 0; m < 4; ++m) _Pragma("unroll") for (int k = 0; k < 2; ++k) dst[m][k] = *(const PG8_LAS bf16x8*)(lds + PG8_SA(b, h) + aoff + m * 2048 + k * 1024); } while (0)
; #define PG8_LDB(dst, b, h) do { _Pragma("unroll") for (int n = 0; n < 2; ++n) _Pragma("unroll") for (int k = 0; k < 2; ++k) dst[n][k] = *(const PG8_LAS bf16x8*)(lds + PG8_SB(b, h) + boff + n * 2048 + k * 1024); } while (0)
; #define PG8_MMA(ai, bj, At, Bt) do { __builtin_amdgcn_s_setprio(1); _Pragma("unroll") for (int m = 0; m < 4; ++m) _Pragma("unroll") for (int n = 0; n < 2; ++n) _Pragma("unroll") for (int k = 0; k < 2; ++k) \
;         acc[ai][bj][m][n] = __builtin_amdgcn_mfma_f32_16x16x32_bf16(Bt[n][k], At[m][k], acc[ai][bj][m][n], 0, 0, 0); __builtin_amdgcn_s_setprio(0); } while (0)
; #define PG8_WAIT_V(n) asm volatile("s_waitcnt vmcnt(" #n ")" ::: "memory")
; #define PG8_WAIT_L(n) asm volatile("s_waitcnt lgkmcnt(" #n ")" ::: "memory")
; #define PG8_BAR __builtin_amdgcn_s_barrier()
; #define PG8_SCHED __builtin_amdgcn_sched_barrier(0)
; template <class Epi, class Sched, bool ALIGN_EPI = false, bool SP2 = false>
; __device__ __forceinline__ void gemm_phase(PG8_LAS unsigned char* lds, const Gemm g, const Sched& S, const Epi& E) {
;     ...
;             PG8_WAIT_V(8); PG8_WAIT_L(0); PG8_BAR; PG8_MMA(1, 0, At, B0); PG8_MMA(1, 1, At, B1); PG8_BAR; PG8_SCHED;
;             PG8_LDB(B0, 1, 0); PG8_LDB(B1, 1, 1); PG8_SCHED; PG8_LDA(At, 1, 0); PG8_STAGE(PG8_SA(0, 1), a2 + hstep, voffA);
;             PG8_WAIT_V(8); PG8_WAIT_L(0); PG8_BAR; PG8_MMA(0, 0, At, B0); PG8_MMA(0, 1, At, B1); PG8_BAR; PG8_SCHED;
	s_waitcnt lgkmcnt(0)
	v_mfma_f32_16x16x32_bf16 v[58:61], v[160:163], v[194:197], v[58:61]
	v_mfma_f32_16x16x32_bf16 v[50:53], v[170:173], v[194:197], v[50:53]
	v_mfma_f32_16x16x32_bf16 v[42:45], v[160:163], v[202:205], v[42:45]
	v_mfma_f32_16x16x32_bf16 v[34:37], v[170:173], v[202:205], v[34:37]
	v_mfma_f32_16x16x32_bf16 v[26:29], v[160:163], v[210:213], v[26:29]
	v_mfma_f32_16x16x32_bf16 v[18:21], v[170:173], v[210:213], v[18:21]
	v_mfma_f32_16x16x32_bf16 v[10:13], v[160:163], v[218:221], v[10:13]
	v_mfma_f32_16x16x32_bf16 v[2:5], v[170:173], v[218:221], v[2:5]
	v_mfma_f32_16x16x32_bf16 v[58:61], v[166:169], v[198:201], v[58:61]
	v_mfma_f32_16x16x32_bf16 v[50:53], v[174:177], v[198:201], v[50:53]
	v_mfma_f32_16x16x32_bf16 v[42:45], v[166:169], v[206:209], v[42:45]
	v_mfma_f32_16x16x32_bf16 v[34:37], v[174:177], v[206:209], v[34:37]
	v_mfma_f32_16x16x32_bf16 v[26:29], v[166:169], v[214:217], v[26:29]
	v_mfma_f32_16x16x32_bf16 v[18:21], v[174:177], v[214:217], v[18:21]
	v_mfma_f32_16x16x32_bf16 v[10:13], v[166:169], v[222:225], v[10:13]
	v_mfma_f32_16x16x32_bf16 v[2:5], v[174:177], v[222:225], v[2:5]
	v_mfma_f32_16x16x32_bf16 v[66:69], v[178:181], v[194:197], v[66:69]
	v_mfma_f32_16x16x32_bf16 v[54:57], v[186:189], v[194:197], v[54:57]
	v_mfma_f32_16x16x32_bf16 v[46:49], v[178:181], v[202:205], v[46:49]
	v_mfma_f32_16x16x32_bf16 v[38:41], v[186:189], v[202:205], v[38:41]
	v_mfma_f32_16x16x32_bf16 v[30:33], v[178:181], v[210:213], v[30:33]
	v_mfma_f32_16x16x32_bf16 v[22:25], v[186:189], v[210:213], v[22:25]
	v_mfma_f32_16x16x32_bf16 v[14:17], v[178:181], v[218:221], v[14:17]
	v_mfma_f32_16x16x32_bf16 v[6:9], v[186:189], v[218:221], v[6:9]
	v_mfma_f32_16x16x32_bf16 v[66:69], v[182:185], v[198:201], v[66:69]
	v_mfma_f32_16x16x32_bf16 v[54:57], v[190:193], v[198:201], v[54:57]
	v_mfma_f32_16x16x32_bf16 v[46:49], v[182:185], v[206:209], v[46:49]
	v_mfma_f32_16x16x32_bf16 v[38:41], v[190:193], v[206:209], v[38:41]
	v_mfma_f32_16x16x32_bf16 v[30:33], v[182:185], v[214:217], v[30:33]
	v_mfma_f32_16x16x32_bf16 v[22:25], v[190:193], v[214:217], v[22:25]
	v_mfma_f32_16x16x32_bf16 v[14:17], v[182:185], v[222:225], v[14:17]
	v_mfma_f32_16x16x32_bf16 v[6:9], v[190:193], v[222:225], v[6:9]
	s_barrier
	s_add_i32 s33, 0, 0x18000
	s_add_i32 s42, 0, 0x1c000
	ds_read_b128 v[160:163], v241 offset:32768
	ds_read_b128 v[166:169], v241 offset:33792
	ds_read_b128 v[170:173], v241 offset:34816
	ds_read_b128 v[174:177], v241 offset:35840
	ds_read_b128 v[178:181], v241 offset:49152
	ds_read_b128 v[182:185], v241 offset:50176
	ds_read_b128 v[186:189], v241 offset:51200
	ds_read_b128 v[190:193], v241 offset:52224
	s_add_u32 s26, s26, 0x100000
	s_addc_u32 s27, s27, 0
	s_mov_b32 m0, s35
	ds_read_b128 v[194:197], v155 offset:32768
	ds_read_b128 v[198:201], v155 offset:33792
	ds_read_b128 v[202:205], v155 offset:34816
	ds_read_b128 v[206:209], v155 offset:35840
	ds_read_b128 v[210:213], v155 offset:36864
	ds_read_b128 v[214:217], v155 offset:37888
	ds_read_b128 v[218:221], v155 offset:38912
	ds_read_b128 v[222:225], v155 offset:39936
	global_load_lds_dwordx4 v130, s[26:27]
	s_mov_b32 m0, s36
	s_nop 0
	global_load_lds_dwordx4 v134, s[26:27]
	s_waitcnt vmcnt(8)
	s_waitcnt lgkmcnt(0)
	s_barrier
	s_waitcnt lgkmcnt(0)
	v_mfma_f32_16x16x32_bf16 v[122:125], v[160:163], v[194:197], v[122:125]
	v_mfma_f32_16x16x32_bf16 v[114:117], v[170:173], v[194:197], v[114:117]
	v_mfma_f32_16x16x32_bf16 v[106:109], v[160:163], v[202:205], v[106:109]
	v_mfma_f32_16x16x32_bf16 v[98:101], v[170:173], v[202:205], v[98:101]
	v_mfma_f32_16x16x32_bf16 v[90:93], v[160:163], v[210:213], v[90:93]
	v_mfma_f32_16x16x32_bf16 v[82:85], v[170:173], v[210:213], v[82:85]
	v_mfma_f32_16x16x32_bf16 v[74:77], v[160:163], v[218:221], v[74:77]
	v_mfma_f32_16x16x32_bf16 v[62:65], v[170:173], v[218:221], v[62:65]
	v_mfma_f32_16x16x32_bf16 v[122:125], v[166:169], v[198:201], v[122:125]
	v_mfma_f32_16x16x32_bf16 v[114:117], v[174:177], v[198:201], v[114:117]
	v_mfma_f32_16x16x32_bf16 v[106:109], v[166:169], v[206:209], v[106:109]
	v_mfma_f32_16x16x32_bf16 v[98:101], v[174:177], v[206:209], v[98:101]
	v_mfma_f32_16x16x32_bf16 v[90:93], v[166:169], v[214:217], v[90:93]
	v_mfma_f32_16x16x32_bf16 v[82:85], v[174:177], v[214:217], v[82:85]
	v_mfma_f32_16x16x32_bf16 v[74:77], v[166:169], v[222:225], v[74:77]
	v_mfma_f32_16x16x32_bf16 v[62:65], v[174:177], v[222:225], v[62:65]
	v_mfma_f32_16x16x32_bf16 v[126:129], v[178:181], v[194:197], v[126:129]
	v_mfma_f32_16x16x32_bf16 v[118:121], v[186:189], v[194:197], v[118:121]
	v_mfma_f32_16x16x32_bf16 v[110:113], v[178:181], v[202:205], v[110:113]
	v_mfma_f32_16x16x32_bf16 v[102:105], v[186:189], v[202:205], v[102:105]
	v_mfma_f32_16x16x32_bf16 v[94:97], v[178:181], v[210:213], v[94:97]
	v_mfma_f32_16x16x32_bf16 v[86:89], v[186:189], v[210:213], v[86:89]
	v_mfma_f32_16x16x32_bf16 v[78:81], v[178:181], v[218:221], v[78:81]
	v_mfma_f32_16x16x32_bf16 v[70:73], v[186:189], v[218:221], v[70:73]
	v_mfma_f32_16x16x32_bf16 v[126:129], v[182:185], v[198:201], v[126:129]
	v_mfma_f32_16x16x32_bf16 v[118:121], v[190:193], v[198:201], v[118:121]
	v_mfma_f32_16x16x32_bf16 v[110:113], v[182:185], v[206:209], v[110:113]
	v_mfma_f32_16x16x32_bf16 v[102:105], v[190:193], v[206:209], v[102:105]
	v_mfma_f32_16x16x32_bf16 v[94:97], v[182:185], v[214:217], v[94:97]
	v_mfma_f32_16x16x32_bf16 v[86:89], v[190:193], v[214:217], v[86:89]
	v_mfma_f32_16x16x32_bf16 v[78:81], v[182:185], v[222:225], v[78:81]
	v_mfma_f32_16x16x32_bf16 v[70:73], v[190:193], v[222:225], v[70:73]
	s_barrier
; #define PG8_STAGE(bufoff, gbase, voff) do { _Pragma("unroll") for (int _i = 0; _i < 2; ++_i) \
;         __builtin_amdgcn_global_load_lds((const unsigned*)((const char*)(gbase) + (voff)[_i]), (PG8_LAS unsigned*)(lds + (bufoff) + ldsw + _i * 8192), 16, 0, 0); } while (0)
; #define PG8_LDA(dst, b, h) do { _Pragma("unroll") for (int m = 0; m < 4; ++m) _Pragma("unroll") for (int k = 0; k < 2; ++k) dst[m][k] = *(const PG8_LAS bf16x8*)(lds + PG8_SA(b, h) + aoff + m * 2048 + k * 1024); } while (0)
; #define PG8_MMA(ai, bj, At, Bt) do { __builtin_amdgcn_s_setprio(1); _Pragma("unroll") for (int m = 0; m < 4; ++m) _Pragma("unroll") for (int n = 0; n < 2; ++n) _Pragma("unroll") for (int k = 0; k < 2; ++k) \
;         acc[ai][bj][m][n] = __builtin_amdgcn_mfma_f32_16x16x32_bf16(Bt[n][k], At[m][k], acc[ai][bj][m][n], 0, 0, 0); __builtin_amdgcn_s_setprio(0); } while (0)
; #define PG8_WAIT_V(n) asm volatile("s_waitcnt vmcnt(" #n ")" ::: "memory")
; #define PG8_WAIT_L(n) asm volatile("s_waitcnt lgkmcnt(" #n ")" ::: "memory")
; #define PG8_BAR __builtin_amdgcn_s_barrier()
; #define PG8_SCHED __builtin_amdgcn_sched_barrier(0)
; template <class Epi, class Sched, bool ALIGN_EPI = false, bool SP2 = false>
; __device__ __forceinline__ void gemm_phase(PG8_LAS unsigned char* lds, const Gemm g, const Sched& S, const Epi& E) {
;     ...
;         for (int t = 0; t < nt; t += 2) {
;     ...
;             PG8_LDA(At, 1, 1); PG8_STAGE(PG8_SB(1, 0), b3, voffB); PG8_STAGE(PG8_SB(1, 1), b3 + hstep, voffB); PG8_STAGE(PG8_SA(1, 0), a3, voffA);
;             PG8_WAIT_V(8); PG8_WAIT_L(0); PG8_BAR; PG8_MMA(1, 0, At, B0); PG8_MMA(1, 1, At, B1); PG8_BAR; PG8_SCHED;
	s_add_i32 s26, s33, s29
	s_add_i32 m0, s26, 0xffffff80
	ds_read_b128 v[194:197], v155 offset:49152
	ds_read_b128 v[198:201], v155 offset:50176
	ds_read_b128 v[202:205], v155 offset:51200
	ds_read_b128 v[206:209], v155 offset:52224
	ds_read_b128 v[210:213], v155 offset:53248
	ds_read_b128 v[214:217], v155 offset:54272
	ds_read_b128 v[218:221], v155 offset:55296
	ds_read_b128 v[222:225], v155 offset:56320
	global_load_lds_dwordx4 v[148:149], off offset:128
	s_add_i32 m0, s26, 0x1f80
	s_add_u32 s22, s22, 0x100080
	s_addc_u32 s23, s23, 0
	s_add_i32 s26, s42, s29
	global_load_lds_dwordx4 v[156:157], off offset:128
	s_mov_b32 m0, s26
	s_nop 0
	global_load_lds_dwordx4 v132, s[22:23]
	s_add_i32 m0, s26, 0x2000
	s_nop 0
	global_load_lds_dwordx4 v136, s[22:23]
	s_add_i32 m0, s41, 0xffffff80
	s_nop 0
	global_load_lds_dwordx4 v[226:227], off offset:128
	s_add_i32 m0, s43, 0xffffff80
	s_nop 0
	global_load_lds_dwordx4 v[228:229], off offset:128
	s_waitcnt vmcnt(8)
	s_waitcnt lgkmcnt(0)
	s_barrier
	s_waitcnt lgkmcnt(0)
	v_mfma_f32_16x16x32_bf16 v[58:61], v[160:163], v[194:197], v[58:61]
	v_mfma_f32_16x16x32_bf16 v[50:53], v[170:173], v[194:197], v[50:53]
	v_mfma_f32_16x16x32_bf16 v[42:45], v[160:163], v[202:205], v[42:45]
	v_mfma_f32_16x16x32_bf16 v[34:37], v[170:173], v[202:205], v[34:37]
	v_mfma_f32_16x16x32_bf16 v[26:29], v[160:163], v[210:213], v[26:29]
	v_mfma_f32_16x16x32_bf16 v[18:21], v[170:173], v[210:213], v[18:21]
	v_mfma_f32_16x16x32_bf16 v[10:13], v[160:163], v[218:221], v[10:13]
	v_mfma_f32_16x16x32_bf16 v[2:5], v[170:173], v[218:221], v[2:5]
	v_mfma_f32_16x16x32_bf16 v[58:61], v[166:169], v[198:201], v[58:61]
	v_mfma_f32_16x16x32_bf16 v[50:53], v[174:177], v[198:201], v[50:53]
	v_mfma_f32_16x16x32_bf16 v[42:45], v[166:169], v[206:209], v[42:45]
	v_mfma_f32_16x16x32_bf16 v[34:37], v[174:177], v[206:209], v[34:37]
	v_mfma_f32_16x16x32_bf16 v[26:29], v[166:169], v[214:217], v[26:29]
	v_mfma_f32_16x16x32_bf16 v[18:21], v[174:177], v[214:217], v[18:21]
	v_mfma_f32_16x16x32_bf16 v[10:13], v[166:169], v[222:225], v[10:13]
	v_mfma_f32_16x16x32_bf16 v[2:5], v[174:177], v[222:225], v[2:5]
	v_mfma_f32_16x16x32_bf16 v[66:69], v[178:181], v[194:197], v[66:69]
	v_mfma_f32_16x16x32_bf16 v[54:57], v[186:189], v[194:197], v[54:57]
	v_mfma_f32_16x16x32_bf16 v[46:49], v[178:181], v[202:205], v[46:49]
	v_mfma_f32_16x16x32_bf16 v[38:41], v[186:189], v[202:205], v[38:41]
	v_mfma_f32_16x16x32_bf16 v[30:33], v[178:181], v[210:213], v[30:33]
	v_mfma_f32_16x16x32_bf16 v[22:25], v[186:189], v[210:213], v[22:25]
	v_mfma_f32_16x16x32_bf16 v[14:17], v[178:181], v[218:221], v[14:17]
	v_mfma_f32_16x16x32_bf16 v[6:9], v[186:189], v[218:221], v[6:9]
	v_mfma_f32_16x16x32_bf16 v[66:69], v[182:185], v[198:201], v[66:69]
	v_mfma_f32_16x16x32_bf16 v[54:57], v[190:193], v[198:201], v[54:57]
	v_mfma_f32_16x16x32_bf16 v[46:49], v[182:185], v[206:209], v[46:49]
	v_mfma_f32_16x16x32_bf16 v[38:41], v[190:193], v[206:209], v[38:41]
	v_mfma_f32_16x16x32_bf16 v[30:33], v[182:185], v[214:217], v[30:33]
	v_mfma_f32_16x16x32_bf16 v[22:25], v[190:193], v[214:217], v[22:25]
	v_mfma_f32_16x16x32_bf16 v[14:17], v[182:185], v[222:225], v[14:17]
	v_mfma_f32_16x16x32_bf16 v[6:9], v[190:193], v[222:225], v[6:9]
	s_barrier
	s_add_i32 s52, s52, 2
	s_add_u32 s24, s24, 0x100
	s_addc_u32 s25, s25, 0
	s_add_u32 s50, s50, 0x100
	s_addc_u32 s51, s51, 0
	s_cmp_gt_u32 s52, 61
	s_cbranch_scc0 .LBB0_1681


; #define PG8_BAR __builtin_amdgcn_s_barrier()
; template <class Epi, class Sched, bool ALIGN_EPI = false, bool SP2 = false>
; __device__ __forceinline__ void gemm_phase(PG8_LAS unsigned char* lds, const Gemm g, const Sched& S, const Epi& E) {
;     ...
;         if constexpr (ALIGN_EPI) { if (wr == 0) PG8_BAR; }
	s_and_b64 vcc, exec, s[8:9]
	s_cbranch_vccz .LBB0_1684
	s_barrier

; #define PG8_STAGE(bufoff, gbase, voff) do { _Pragma("unroll") for (int _i = 0; _i < 2; ++_i) \
;         __builtin_amdgcn_global_load_lds((const unsigned*)((const char*)(gbase) + (voff)[_i]), (PG8_LAS unsigned*)(lds + (bufoff) + ldsw + _i * 8192), 16, 0, 0); } while (0)
; #define PG8_LDA(dst, b, h) do { _Pragma("unroll") for (int m = 0; m < 4; ++m) _Pragma("unroll") for (int k = 0; k < 2; ++k) dst[m][k] = *(const PG8_LAS bf16x8*)(lds + PG8_SA(b, h) + aoff + m * 2048 + k * 1024); } while (0)
; #define PG8_LDB(dst, b, h) do { _Pragma("unroll") for (int n = 0; n < 2; ++n) _Pragma("unroll") for (int k = 0; k < 2; ++k) dst[n][k] = *(const PG8_LAS bf16x8*)(lds + PG8_SB(b, h) + boff + n * 2048 + k * 1024); } while (0)
; #define PG8_MMA(ai, bj, At, Bt) do { __builtin_amdgcn_s_setprio(1); _Pragma("unroll") for (int m = 0; m < 4; ++m) _Pragma("unroll") for (int n = 0; n < 2; ++n) _Pragma("unroll") for (int k = 0; k < 2; ++k) \
;         acc[ai][bj][m][n] = __builtin_amdgcn_mfma_f32_16x16x32_bf16(Bt[n][k], At[m][k], acc[ai][bj][m][n], 0, 0, 0); __builtin_amdgcn_s_setprio(0); } while (0)
; #define PG8_WAIT_V(n) asm volatile("s_waitcnt vmcnt(" #n ")" ::: "memory")
; template <class Epi, class Sched, bool ALIGN_EPI = false, bool SP2 = false>
; __device__ __forceinline__ void gemm_phase(PG8_LAS unsigned char* lds, const Gemm g, const Sched& S, const Epi& E) {
;     ...
;         const char* nA = has_next ? (const char*)g.A + (size_t)nxt.pm * tstep : cA; const char* nB = has_next ? (const char*)g.Bt + (size_t)nxt.pn * tstep : cB;
;         for (int t = 0; t < nt; t += 2) {
;             const bool last = (t == nt - 2);
;             const char* a1 = cA + (size_t)(t + 1) * kstep;
;             const char* a2 = last ? nA : cA + (size_t)(t + 2) * kstep; const char* b2 = last ? nB : cB + (size_t)(t + 2) * kstep;
;             const char* a3 = a2 + kstep; const char* b3 = b2 + kstep;
;             if (last && has_next) S.a_ready(nxt);
;             if constexpr (SP2) {
;             PG8_LDB(B0, 0, 0); PG8_LDB(B1, 0, 1); PG8_SCHED; PG8_LDA(At, 0, 0); PG8_STAGE(PG8_SA(1, 1), a1 + hstep, voffA);
;             PG8_WAIT_V(8); PG8_WAIT_L(0); PG8_BAR; PG8_MMA(0, 0, At, B0); PG8_MMA(0, 1, At, B1); PG8_BAR; PG8_SCHED;
;             PG8_LDA(At, 0, 1); PG8_STAGE(PG8_SB(0, 0), b2, voffB); PG8_STAGE(PG8_SB(0, 1), b2 + hstep, voffB); PG8_STAGE(PG8_SA(0, 0), a2, voffA);
.LBB0_1800:
	s_add_u32 s18, s18, 0x2b0080
	s_addc_u32 s19, s19, 0
	s_add_u32 s46, s16, 0x100
	s_addc_u32 s47, s17, 0
	s_mov_b32 s48, -2
	v_add_u32_e32 v241, 0x10000, v182
.LBB0_1801:
	ds_read_b128 v[130:133], v241 offset:0
	ds_read_b128 v[134:137], v241 offset:1024
	ds_read_b128 v[138:141], v241 offset:2048
	ds_read_b128 v[142:145], v241 offset:3072
	ds_read_b128 v[146:149], v241 offset:16384
	ds_read_b128 v[150:153], v241 offset:17408
	ds_read_b128 v[170:173], v241 offset:18432
	ds_read_b128 v[174:177], v241 offset:19456
	s_add_u32 s16, s18, 0xffd50080
	s_addc_u32 s17, s19, -1
	s_cmpk_eq_i32 s48, 0xa8
	s_cselect_b32 s21, s5, s17
	s_cselect_b32 s20, s4, s16
	s_cselect_b32 s17, s15, s47
	s_cselect_b32 s16, s14, s46
	s_add_i32 m0, s25, 0xc000
	ds_read_b128 v[178:181], v184
	ds_read_b128 v[186:189], v184 offset:1024
	ds_read_b128 v[190:193], v184 offset:2048
	ds_read_b128 v[194:197], v184 offset:3072
	ds_read_b128 v[198:201], v184 offset:4096
	ds_read_b128 v[202:205], v184 offset:5120
	ds_read_b128 v[206:209], v184 offset:6144
	ds_read_b128 v[210:213], v184 offset:7168
	global_load_lds_dwordx4 v0, s[18:19]
	s_add_i32 m0, s25, 0xe000
	s_nop 0
	global_load_lds_dwordx4 v162, s[18:19]
	s_waitcnt vmcnt(8)
	s_waitcnt lgkmcnt(0)
	s_barrier
	s_waitcnt lgkmcnt(0)
	v_mfma_f32_16x16x32_bf16 v[114:117], v[130:133], v[178:181], v[114:117]
	v_mfma_f32_16x16x32_bf16 v[118:121], v[138:141], v[178:181], v[118:121]
	v_mfma_f32_16x16x32_bf16 v[106:109], v[130:133], v[190:193], v[106:109]
	v_mfma_f32_16x16x32_bf16 v[98:101], v[138:141], v[190:193], v[98:101]
	v_mfma_f32_16x16x32_bf16 v[90:93], v[130:133], v[198:201], v[90:93]
	v_mfma_f32_16x16x32_bf16 v[82:85], v[138:141], v[198:201], v[82:85]
	v_mfma_f32_16x16x32_bf16 v[74:77], v[130:133], v[206:209], v[74:77]
	v_mfma_f32_16x16x32_bf16 v[66:69], v[138:141], v[206:209], v[66:69]
	v_mfma_f32_16x16x32_bf16 v[114:117], v[134:137], v[186:189], v[114:117]
	v_mfma_f32_16x16x32_bf16 v[118:121], v[142:145], v[186:189], v[118:121]
	v_mfma_f32_16x16x32_bf16 v[106:109], v[134:137], v[194:197], v[106:109]
	v_mfma_f32_16x16x32_bf16 v[98:101], v[142:145], v[194:197], v[98:101]
	v_mfma_f32_16x16x32_bf16 v[90:93], v[134:137], v[202:205], v[90:93]
	v_mfma_f32_16x16x32_bf16 v[82:85], v[142:145], v[202:205], v[82:85]
	v_mfma_f32_16x16x32_bf16 v[74:77], v[134:137], v[210:213], v[74:77]
	v_mfma_f32_16x16x32_bf16 v[66:69], v[142:145], v[210:213], v[66:69]
	v_mfma_f32_16x16x32_bf16 v[122:125], v[146:149], v[178:181], v[122:125]
	v_mfma_f32_16x16x32_bf16 v[126:129], v[170:173], v[178:181], v[126:129]
	v_mfma_f32_16x16x32_bf16 v[110:113], v[146:149], v[190:193], v[110:113]
	v_mfma_f32_16x16x32_bf16 v[102:105], v[170:173], v[190:193], v[102:105]
	v_mfma_f32_16x16x32_bf16 v[94:97], v[146:149], v[198:201], v[94:97]
	v_mfma_f32_16x16x32_bf16 v[86:89], v[170:173], v[198:201], v[86:89]
	v_mfma_f32_16x16x32_bf16 v[78:81], v[146:149], v[206:209], v[78:81]
	v_mfma_f32_16x16x32_bf16 v[70:73], v[170:173], v[206:209], v[70:73]
	v_mfma_f32_16x16x32_bf16 v[122:125], v[150:153], v[186:189], v[122:125]
	v_mfma_f32_16x16x32_bf16 v[126:129], v[174:177], v[186:189], v[126:129]
	v_mfma_f32_16x16x32_bf16 v[110:113], v[150:153], v[194:197], v[110:113]
	v_mfma_f32_16x16x32_bf16 v[102:105], v[174:177], v[194:197], v[102:105]
	v_mfma_f32_16x16x32_bf16 v[94:97], v[150:153], v[202:205], v[94:97]
	v_mfma_f32_16x16x32_bf16 v[86:89], v[174:177], v[202:205], v[86:89]
	v_mfma_f32_16x16x32_bf16 v[78:81], v[150:153], v[210:213], v[78:81]
	v_mfma_f32_16x16x32_bf16 v[70:73], v[174:177], v[210:213], v[70:73]
	s_barrier
	s_add_i32 s33, s36, s24
	v_lshl_add_u64 v[214:215], s[16:17], 0, v[156:157]
	s_mov_b32 m0, s33
	ds_read_b128 v[178:181], v184 offset:16384
	ds_read_b128 v[186:189], v184 offset:17408
	ds_read_b128 v[190:193], v184 offset:18432
	ds_read_b128 v[194:197], v184 offset:19456
	ds_read_b128 v[198:201], v184 offset:20480
	ds_read_b128 v[202:205], v184 offset:21504
	ds_read_b128 v[206:209], v184 offset:22528
	ds_read_b128 v[210:213], v184 offset:23552
	global_load_lds_dwordx4 v[214:215], off
	s_add_i32 m0, s33, 0x2000
	s_add_u32 s50, s16, 0x2b0000
	v_lshl_add_u64 v[216:217], s[16:17], 0, v[160:161]
	s_addc_u32 s51, s17, 0
	s_add_i32 s33, s37, s24
	global_load_lds_dwordx4 v[216:217], off
	s_mov_b32 m0, s33
	v_lshl_add_u64 v[220:221], s[20:21], 0, v[158:159]
	global_load_lds_dwordx4 v156, s[50:51]
	s_add_i32 m0, s33, 0x2000
	s_nop 0
	global_load_lds_dwordx4 v160, s[50:51]
	v_lshl_add_u64 v[218:219], s[20:21], 0, v[154:155]
	s_mov_b32 m0, s25
	s_nop 0
	global_load_lds_dwordx4 v[218:219], off
	s_mov_b32 m0, s26
	s_nop 0
	global_load_lds_dwordx4 v[220:221], off
	s_waitcnt vmcnt(8)
	s_waitcnt lgkmcnt(0)
	s_barrier
; #define PG8_STAGE(bufoff, gbase, voff) do { _Pragma("unroll") for (int _i = 0; _i < 2; ++_i) \
;         __builtin_amdgcn_global_load_lds((const unsigned*)((const char*)(gbase) + (voff)[_i]), (PG8_LAS unsigned*)(lds + (bufoff) + ldsw + _i * 8192), 16, 0, 0); } while (0)
; #define PG8_LDA(dst, b, h) do { _Pragma("unroll") for (int m = 0; m < 4; ++m) _Pragma("unroll") for (int k = 0; k < 2; ++k) dst[m][k] = *(const PG8_LAS bf16x8*)(lds + PG8_SA(b, h) + aoff + m * 2048 + k * 1024); } while (0)
; #define PG8_LDB(dst, b, h) do { _Pragma("unroll") for (int n = 0; n < 2; ++n) _Pragma("unroll") for (int k = 0; k < 2; ++k) dst[n][k] = *(const PG8_LAS bf16x8*)(lds + PG8_SB(b, h) + boff + n * 2048 + k * 1024); } while (0)
; #define PG8_MMA(ai, bj, At, Bt) do { __builtin_amdgcn_s_setprio(1); _Pragma("unroll") for (int m = 0; m < 4; ++m) _Pragma("unroll") for (int n = 0; n < 2; ++n) _Pragma("unroll") for (int k = 0; k < 2; ++k) \
;         acc[ai][bj][m][n] = __builtin_amdgcn_mfma_f32_16x16x32_bf16(Bt[n][k], At[m][k], acc[ai][bj][m][n], 0, 0, 0); __builtin_amdgcn_s_setprio(0); } while (0)
; #define PG8_WAIT_V(n) asm volatile("s_waitcnt vmcnt(" #n ")" ::: "memory")
; #define PG8_WAIT_L(n) asm volatile("s_waitcnt lgkmcnt(" #n ")" ::: "memory")
; #define PG8_BAR __builtin_amdgcn_s_barrier()
; #define PG8_SCHED __builtin_amdgcn_sched_barrier(0)
; template <class Epi, class Sched, bool ALIGN_EPI = false, bool SP2 = false>
; __device__ __forceinline__ void gemm_phase(PG8_LAS unsigned char* lds, const Gemm g, const Sched& S, const Epi& E) {
;     ...
;             PG8_WAIT_V(8); PG8_WAIT_L(0); PG8_BAR; PG8_MMA(1, 0, At, B0); PG8_MMA(1, 1, At, B1); PG8_BAR; PG8_SCHED;
;             PG8_LDB(B0, 1, 0); PG8_LDB(B1, 1, 1); PG8_SCHED; PG8_LDA(At, 1, 0); PG8_STAGE(PG8_SA(0, 1), a2 + hstep, voffA);
;             PG8_WAIT_V(8); PG8_WAIT_L(0); PG8_BAR; PG8_MMA(0, 0, At, B0); PG8_MMA(0, 1, At, B1); PG8_BAR; PG8_SCHED;
	s_waitcnt lgkmcnt(0)
	v_mfma_f32_16x16x32_bf16 v[58:61], v[130:133], v[178:181], v[58:61]
	v_mfma_f32_16x16x32_bf16 v[54:57], v[138:141], v[178:181], v[54:57]
	v_mfma_f32_16x16x32_bf16 v[42:45], v[130:133], v[190:193], v[42:45]
	v_mfma_f32_16x16x32_bf16 v[34:37], v[138:141], v[190:193], v[34:37]
	v_mfma_f32_16x16x32_bf16 v[26:29], v[130:133], v[198:201], v[26:29]
	v_mfma_f32_16x16x32_bf16 v[18:21], v[138:141], v[198:201], v[18:21]
	v_mfma_f32_16x16x32_bf16 v[6:9], v[130:133], v[206:209], v[6:9]
	v_mfma_f32_16x16x32_bf16 v[2:5], v[138:141], v[206:209], v[2:5]
	v_mfma_f32_16x16x32_bf16 v[58:61], v[134:137], v[186:189], v[58:61]
	v_mfma_f32_16x16x32_bf16 v[54:57], v[142:145], v[186:189], v[54:57]
	v_mfma_f32_16x16x32_bf16 v[42:45], v[134:137], v[194:197], v[42:45]
	v_mfma_f32_16x16x32_bf16 v[34:37], v[142:145], v[194:197], v[34:37]
	v_mfma_f32_16x16x32_bf16 v[26:29], v[134:137], v[202:205], v[26:29]
	v_mfma_f32_16x16x32_bf16 v[18:21], v[142:145], v[202:205], v[18:21]
	v_mfma_f32_16x16x32_bf16 v[6:9], v[134:137], v[210:213], v[6:9]
	v_mfma_f32_16x16x32_bf16 v[2:5], v[142:145], v[210:213], v[2:5]
	v_mfma_f32_16x16x32_bf16 v[62:65], v[146:149], v[178:181], v[62:65]
	v_mfma_f32_16x16x32_bf16 v[50:53], v[170:173], v[178:181], v[50:53]
	v_mfma_f32_16x16x32_bf16 v[46:49], v[146:149], v[190:193], v[46:49]
	v_mfma_f32_16x16x32_bf16 v[38:41], v[170:173], v[190:193], v[38:41]
	v_mfma_f32_16x16x32_bf16 v[30:33], v[146:149], v[198:201], v[30:33]
	v_mfma_f32_16x16x32_bf16 v[22:25], v[170:173], v[198:201], v[22:25]
	v_mfma_f32_16x16x32_bf16 v[10:13], v[146:149], v[206:209], v[10:13]
	v_mfma_f32_16x16x32_bf16 v[14:17], v[170:173], v[206:209], v[14:17]
	v_mfma_f32_16x16x32_bf16 v[62:65], v[150:153], v[186:189], v[62:65]
	v_mfma_f32_16x16x32_bf16 v[50:53], v[174:177], v[186:189], v[50:53]
	v_mfma_f32_16x16x32_bf16 v[46:49], v[150:153], v[194:197], v[46:49]
	v_mfma_f32_16x16x32_bf16 v[38:41], v[174:177], v[194:197], v[38:41]
	v_mfma_f32_16x16x32_bf16 v[30:33], v[150:153], v[202:205], v[30:33]
	v_mfma_f32_16x16x32_bf16 v[22:25], v[174:177], v[202:205], v[22:25]
	v_mfma_f32_16x16x32_bf16 v[10:13], v[150:153], v[210:213], v[10:13]
	v_mfma_f32_16x16x32_bf16 v[14:17], v[174:177], v[210:213], v[14:17]
	s_barrier
	s_add_i32 s33, 0, 0x18000
	s_add_i32 s42, 0, 0x1c000
	ds_read_b128 v[130:133], v241 offset:32768
	ds_read_b128 v[134:137], v241 offset:33792
	ds_read_b128 v[138:141], v241 offset:34816
	ds_read_b128 v[142:145], v241 offset:35840
	ds_read_b128 v[146:149], v241 offset:49152
	ds_read_b128 v[150:153], v241 offset:50176
	ds_read_b128 v[170:173], v241 offset:51200
	ds_read_b128 v[174:177], v241 offset:52224
	s_add_u32 s20, s20, 0x2b0000
	s_addc_u32 s21, s21, 0
	s_mov_b32 m0, s27
	ds_read_b128 v[178:181], v184 offset:32768
	ds_read_b128 v[186:189], v184 offset:33792
	ds_read_b128 v[190:193], v184 offset:34816
	ds_read_b128 v[194:197], v184 offset:35840
	ds_read_b128 v[198:201], v184 offset:36864
	ds_read_b128 v[202:205], v184 offset:37888
	ds_read_b128 v[206:209], v184 offset:38912
	ds_read_b128 v[210:213], v184 offset:39936
	global_load_lds_dwordx4 v154, s[20:21]
	s_mov_b32 m0, s28
	s_nop 0
	global_load_lds_dwordx4 v158, s[20:21]
	s_waitcnt vmcnt(8)
	s_waitcnt lgkmcnt(0)
	s_barrier
	s_waitcnt lgkmcnt(0)
	v_mfma_f32_16x16x32_bf16 v[114:117], v[130:133], v[178:181], v[114:117]
	v_mfma_f32_16x16x32_bf16 v[118:121], v[138:141], v[178:181], v[118:121]
	v_mfma_f32_16x16x32_bf16 v[106:109], v[130:133], v[190:193], v[106:109]
	v_mfma_f32_16x16x32_bf16 v[98:101], v[138:141], v[190:193], v[98:101]
	v_mfma_f32_16x16x32_bf16 v[90:93], v[130:133], v[198:201], v[90:93]
	v_mfma_f32_16x16x32_bf16 v[82:85], v[138:141], v[198:201], v[82:85]
	v_mfma_f32_16x16x32_bf16 v[74:77], v[130:133], v[206:209], v[74:77]
	v_mfma_f32_16x16x32_bf16 v[66:69], v[138:141], v[206:209], v[66:69]
	v_mfma_f32_16x16x32_bf16 v[114:117], v[134:137], v[186:189], v[114:117]
	v_mfma_f32_16x16x32_bf16 v[118:121], v[142:145], v[186:189], v[118:121]
	v_mfma_f32_16x16x32_bf16 v[106:109], v[134:137], v[194:197], v[106:109]
	v_mfma_f32_16x16x32_bf16 v[98:101], v[142:145], v[194:197], v[98:101]
	v_mfma_f32_16x16x32_bf16 v[90:93], v[134:137], v[202:205], v[90:93]
	v_mfma_f32_16x16x32_bf16 v[82:85], v[142:145], v[202:205], v[82:85]
	v_mfma_f32_16x16x32_bf16 v[74:77], v[134:137], v[210:213], v[74:77]
	v_mfma_f32_16x16x32_bf16 v[66:69], v[142:145], v[210:213], v[66:69]
	v_mfma_f32_16x16x32_bf16 v[122:125], v[146:149], v[178:181], v[122:125]
	v_mfma_f32_16x16x32_bf16 v[126:129], v[170:173], v[178:181], v[126:129]
	v_mfma_f32_16x16x32_bf16 v[110:113], v[146:149], v[190:193], v[110:113]
	v_mfma_f32_16x16x32_bf16 v[102:105], v[170:173], v[190:193], v[102:105]
	v_mfma_f32_16x16x32_bf16 v[94:97], v[146:149], v[198:201], v[94:97]
	v_mfma_f32_16x16x32_bf16 v[86:89], v[170:173], v[198:201], v[86:89]
	v_mfma_f32_16x16x32_bf16 v[78:81], v[146:149], v[206:209], v[78:81]
	v_mfma_f32_16x16x32_bf16 v[70:73], v[170:173], v[206:209], v[70:73]
	v_mfma_f32_16x16x32_bf16 v[122:125], v[150:153], v[186:189], v[122:125]
	v_mfma_f32_16x16x32_bf16 v[126:129], v[174:177], v[186:189], v[126:129]
	v_mfma_f32_16x16x32_bf16 v[110:113], v[150:153], v[194:197], v[110:113]
	v_mfma_f32_16x16x32_bf16 v[102:105], v[174:177], v[194:197], v[102:105]
	v_mfma_f32_16x16x32_bf16 v[94:97], v[150:153], v[202:205], v[94:97]
	v_mfma_f32_16x16x32_bf16 v[86:89], v[174:177], v[202:205], v[86:89]
	v_mfma_f32_16x16x32_bf16 v[78:81], v[150:153], v[210:213], v[78:81]
	v_mfma_f32_16x16x32_bf16 v[70:73], v[174:177], v[210:213], v[70:73]
	s_barrier
; #define PG8_STAGE(bufoff, gbase, voff) do { _Pragma("unroll") for (int _i = 0; _i < 2; ++_i) \
;         __builtin_amdgcn_global_load_lds((const unsigned*)((const char*)(gbase) + (voff)[_i]), (PG8_LAS unsigned*)(lds + (bufoff) + ldsw + _i * 8192), 16, 0, 0); } while (0)
; #define PG8_LDA(dst, b, h) do { _Pragma("unroll") for (int m = 0; m < 4; ++m) _Pragma("unroll") for (int k = 0; k < 2; ++k) dst[m][k] = *(const PG8_LAS bf16x8*)(lds + PG8_SA(b, h) + aoff + m * 2048 + k * 1024); } while (0)
; #define PG8_MMA(ai, bj, At, Bt) do { __builtin_amdgcn_s_setprio(1); _Pragma("unroll") for (int m = 0; m < 4; ++m) _Pragma("unroll") for (int n = 0; n < 2; ++n) _Pragma("unroll") for (int k = 0; k < 2; ++k) \
;         acc[ai][bj][m][n] = __builtin_amdgcn_mfma_f32_16x16x32_bf16(Bt[n][k], At[m][k], acc[ai][bj][m][n], 0, 0, 0); __builtin_amdgcn_s_setprio(0); } while (0)
; #define PG8_WAIT_V(n) asm volatile("s_waitcnt vmcnt(" #n ")" ::: "memory")
; #define PG8_WAIT_L(n) asm volatile("s_waitcnt lgkmcnt(" #n ")" ::: "memory")
; #define PG8_BAR __builtin_amdgcn_s_barrier()
; #define PG8_SCHED __builtin_amdgcn_sched_barrier(0)
; template <class Epi, class Sched, bool ALIGN_EPI = false, bool SP2 = false>
; __device__ __forceinline__ void gemm_phase(PG8_LAS unsigned char* lds, const Gemm g, const Sched& S, const Epi& E) {
;     ...
;         for (int t = 0; t < nt; t += 2) {
;             const bool last = (t == nt - 2);
;     ...
;             PG8_LDA(At, 1, 1); PG8_STAGE(PG8_SB(1, 0), b3, voffB); PG8_STAGE(PG8_SB(1, 1), b3 + hstep, voffB); PG8_STAGE(PG8_SA(1, 0), a3, voffA);
;             PG8_WAIT_V(8); PG8_WAIT_L(0); PG8_BAR; PG8_MMA(1, 0, At, B0); PG8_MMA(1, 1, At, B1); PG8_BAR; PG8_SCHED;
	s_add_i32 s20, s33, s24
	s_add_i32 m0, s20, 0xffffff80
	ds_read_b128 v[178:181], v184 offset:49152
	ds_read_b128 v[186:189], v184 offset:50176
	ds_read_b128 v[190:193], v184 offset:51200
	ds_read_b128 v[194:197], v184 offset:52224
	ds_read_b128 v[198:201], v184 offset:53248
	ds_read_b128 v[202:205], v184 offset:54272
	ds_read_b128 v[206:209], v184 offset:55296
	ds_read_b128 v[210:213], v184 offset:56320
	global_load_lds_dwordx4 v[214:215], off offset:128
	s_add_i32 m0, s20, 0x1f80
	s_add_u32 s16, s16, 0x2b0080
	s_addc_u32 s17, s17, 0
	s_add_i32 s20, s42, s24
	global_load_lds_dwordx4 v[216:217], off offset:128
	s_mov_b32 m0, s20
	s_nop 0
	global_load_lds_dwordx4 v156, s[16:17]
	s_add_i32 m0, s20, 0x2000
	s_nop 0
	global_load_lds_dwordx4 v160, s[16:17]
	s_add_i32 m0, s30, 0xffffff80
	s_nop 0
	global_load_lds_dwordx4 v[218:219], off offset:128
	s_add_i32 m0, s31, 0xffffff80
	s_nop 0
	global_load_lds_dwordx4 v[220:221], off offset:128
	s_waitcnt vmcnt(8)
	s_waitcnt lgkmcnt(0)
	s_barrier
	s_waitcnt lgkmcnt(0)
	v_mfma_f32_16x16x32_bf16 v[58:61], v[130:133], v[178:181], v[58:61]
	v_mfma_f32_16x16x32_bf16 v[54:57], v[138:141], v[178:181], v[54:57]
	v_mfma_f32_16x16x32_bf16 v[42:45], v[130:133], v[190:193], v[42:45]
	v_mfma_f32_16x16x32_bf16 v[34:37], v[138:141], v[190:193], v[34:37]
	v_mfma_f32_16x16x32_bf16 v[26:29], v[130:133], v[198:201], v[26:29]
	v_mfma_f32_16x16x32_bf16 v[18:21], v[138:141], v[198:201], v[18:21]
	v_mfma_f32_16x16x32_bf16 v[6:9], v[130:133], v[206:209], v[6:9]
	v_mfma_f32_16x16x32_bf16 v[2:5], v[138:141], v[206:209], v[2:5]
	v_mfma_f32_16x16x32_bf16 v[58:61], v[134:137], v[186:189], v[58:61]
	v_mfma_f32_16x16x32_bf16 v[54:57], v[142:145], v[186:189], v[54:57]
	v_mfma_f32_16x16x32_bf16 v[42:45], v[134:137], v[194:197], v[42:45]
	v_mfma_f32_16x16x32_bf16 v[34:37], v[142:145], v[194:197], v[34:37]
	v_mfma_f32_16x16x32_bf16 v[26:29], v[134:137], v[202:205], v[26:29]
	v_mfma_f32_16x16x32_bf16 v[18:21], v[142:145], v[202:205], v[18:21]
	v_mfma_f32_16x16x32_bf16 v[6:9], v[134:137], v[210:213], v[6:9]
	v_mfma_f32_16x16x32_bf16 v[2:5], v[142:145], v[210:213], v[2:5]
	v_mfma_f32_16x16x32_bf16 v[62:65], v[146:149], v[178:181], v[62:65]
	v_mfma_f32_16x16x32_bf16 v[50:53], v[170:173], v[178:181], v[50:53]
	v_mfma_f32_16x16x32_bf16 v[46:49], v[146:149], v[190:193], v[46:49]
	v_mfma_f32_16x16x32_bf16 v[38:41], v[170:173], v[190:193], v[38:41]
	v_mfma_f32_16x16x32_bf16 v[30:33], v[146:149], v[198:201], v[30:33]
	v_mfma_f32_16x16x32_bf16 v[22:25], v[170:173], v[198:201], v[22:25]
	v_mfma_f32_16x16x32_bf16 v[10:13], v[146:149], v[206:209], v[10:13]
	v_mfma_f32_16x16x32_bf16 v[14:17], v[170:173], v[206:209], v[14:17]
	v_mfma_f32_16x16x32_bf16 v[62:65], v[150:153], v[186:189], v[62:65]
	v_mfma_f32_16x16x32_bf16 v[50:53], v[174:177], v[186:189], v[50:53]
	v_mfma_f32_16x16x32_bf16 v[46:49], v[150:153], v[194:197], v[46:49]
	v_mfma_f32_16x16x32_bf16 v[38:41], v[174:177], v[194:197], v[38:41]
	v_mfma_f32_16x16x32_bf16 v[30:33], v[150:153], v[202:205], v[30:33]
	v_mfma_f32_16x16x32_bf16 v[22:25], v[174:177], v[202:205], v[22:25]
	v_mfma_f32_16x16x32_bf16 v[10:13], v[150:153], v[210:213], v[10:13]
	v_mfma_f32_16x16x32_bf16 v[14:17], v[174:177], v[210:213], v[14:17]
	s_barrier
	s_add_i32 s48, s48, 2
	s_add_u32 s18, s18, 0x100
	s_addc_u32 s19, s19, 0
	s_add_u32 s46, s46, 0x100
	s_addc_u32 s47, s47, 0
	s_cmpk_gt_u32 s48, 0xa9
	s_cbranch_scc0 .LBB0_1801


; #define PG8_BAR __builtin_amdgcn_s_barrier()
; template <class Epi, class Sched, bool ALIGN_EPI = false, bool SP2 = false>
; __device__ __forceinline__ void gemm_phase(PG8_LAS unsigned char* lds, const Gemm g, const Sched& S, const Epi& E) {
;     ...
;         if constexpr (ALIGN_EPI) { if (wr == 0) PG8_BAR; }
;         if constexpr (!Epi::AFTER_DRAIN) { E(acc, cur, wr, wc, fr, fq); S.done(cur); }
;         if (!has_next) break;
	s_and_b64 vcc, exec, s[12:13]
	s_cbranch_vccz .LBB0_1804
	s_barrier

; #define LAS __attribute__((address_space(3)))
; __global__ void __launch_bounds__(NTHR, 2) hybrid_fwd(Args args) {
;     extern __shared__ __attribute__((aligned(16))) unsigned char lds_raw[];
;     LAS unsigned char* lds = (LAS unsigned char*)lds_raw;
;     const Params& p = args.p;
;     const int tid = threadIdx.x, lane = tid & 63, wave = __builtin_amdgcn_readfirstlane(tid >> 6);
	.amdhsa_kernel _Z10hybrid_fwd4Args
		.amdhsa_group_segment_fixed_size 0
		.amdhsa_private_segment_fixed_size 0
		.amdhsa_kernarg_size 464
		.amdhsa_user_sgpr_count 2
		.amdhsa_user_sgpr_dispatch_ptr 0
		.amdhsa_user_sgpr_queue_ptr 0
		.amdhsa_user_sgpr_kernarg_segment_ptr 1
		.amdhsa_user_sgpr_dispatch_id 0
		.amdhsa_user_sgpr_kernarg_preload_length 0
		.amdhsa_user_sgpr_kernarg_preload_offset 0
		.amdhsa_user_sgpr_private_segment_size 0
		.amdhsa_uses_dynamic_stack 0
		.amdhsa_enable_private_segment 0
		.amdhsa_system_sgpr_workgroup_id_x 1
		.amdhsa_system_sgpr_workgroup_id_y 0
		.amdhsa_system_sgpr_workgroup_id_z 0
		.amdhsa_system_sgpr_workgroup_info 0
		.amdhsa_system_vgpr_workitem_id 0
		.amdhsa_next_free_vgpr 242
		.amdhsa_next_free_sgpr 102
		.amdhsa_accum_offset 244
		.amdhsa_reserve_vcc 1
		.amdhsa_float_round_mode_32 0
		.amdhsa_float_round_mode_16_64 0
		.amdhsa_float_denorm_mode_32 3
		.amdhsa_float_denorm_mode_16_64 3
		.amdhsa_dx10_clamp 1
		.amdhsa_ieee_mode 1
		.amdhsa_fp16_overflow 0
		.amdhsa_tg_split 0
		.amdhsa_exception_fp_ieee_invalid_op 0
		.amdhsa_exception_fp_denorm_src 0
		.amdhsa_exception_fp_ieee_div_zero 0
		.amdhsa_exception_fp_ieee_overflow 0
		.amdhsa_exception_fp_ieee_underflow 0
		.amdhsa_exception_fp_ieee_inexact 0
		.amdhsa_exception_int_div_zero 0
	.end_amdhsa_kernel

; #define LAS __attribute__((address_space(3)))
; __global__ void __launch_bounds__(NTHR, 2) hybrid_fwd(Args args) {
;     extern __shared__ __attribute__((aligned(16))) unsigned char lds_raw[];
;     LAS unsigned char* lds = (LAS unsigned char*)lds_raw;
;     const Params& p = args.p;
;     const int tid = threadIdx.x, lane = tid & 63, wave = __builtin_amdgcn_readfirstlane(tid >> 6);
amdhsa.kernels:
  - .agpr_count:     0
    .args:
      - .offset:         0
        .size:           208
        .value_kind:     by_value
      - .offset:         208
        .size:           4
        .value_kind:     hidden_block_count_x
      - .offset:         212
        .size:           4
        .value_kind:     hidden_block_count_y
      - .offset:         216
        .size:           4
        .value_kind:     hidden_block_count_z
      - .offset:         220
        .size:           2
        .value_kind:     hidden_group_size_x
      - .offset:         222
        .size:           2
        .value_kind:     hidden_group_size_y
      - .offset:         224
        .size:           2
        .value_kind:     hidden_group_size_z
      - .offset:         226
        .size:           2
        .value_kind:     hidden_remainder_x
      - .offset:         228
        .size:           2
        .value_kind:     hidden_remainder_y
      - .offset:         230
        .size:           2
        .value_kind:     hidden_remainder_z
      - .offset:         248
        .size:           8
        .value_kind:     hidden_global_offset_x
      - .offset:         256
        .size:           8
        .value_kind:     hidden_global_offset_y
      - .offset:         264
        .size:           8
        .value_kind:     hidden_global_offset_z
      - .offset:         272
        .size:           2
        .value_kind:     hidden_grid_dims
      - .offset:         328
        .size:           4
        .value_kind:     hidden_dynamic_lds_size
    .group_segment_fixed_size: 0
    .kernarg_segment_align: 8
    .kernarg_segment_size: 464
    .language:       OpenCL C
    .language_version:
      - 2
      - 0
    .max_flat_workgroup_size: 512
    .name:           _Z10hybrid_fwd4Args
    .private_segment_fixed_size: 0
    .sgpr_count:     108
    .sgpr_spill_count: 83
    .symbol:         _Z10hybrid_fwd4Args.kd
    .uniform_work_group_size: 1
    .uses_dynamic_stack: false
    .vgpr_count:     242
    .vgpr_spill_count: 0
    .wavefront_size: 64
